# LN: gamma/beta preloaded (all three LN instances), q=1..3 pieces prefetched with q=0; r2 chunk units share an XCD; attention loop rescheduled
# speedup vs baseline: 1.0029x; 1.0029x over previous
.LBB0_51:
	global_load_dwordx4 v[154:157], v[74:75], off
	global_load_dwordx4 v[158:161], v[76:77], off
	global_load_dwordx4 v[162:165], v[74:75], off offset:1024
	global_load_dwordx4 v[166:169], v[76:77], off offset:1024
	global_load_dwordx4 v[170:173], v[74:75], off offset:2048
	global_load_dwordx4 v[174:177], v[76:77], off offset:2048
	global_load_dwordx4 v[178:181], v[74:75], off offset:3072
	global_load_dwordx4 v[182:185], v[76:77], off offset:3072
	v_add_u32_e32 v0, 0xfffff000, v64
	v_ashrrev_i32_e32 v0, 10, v0
	v_add_u32_e32 v0, 1, v0
	v_cmp_lt_i32_e32 vcc, s33, v64
	s_mov_b32 s2, 0x1000000
	global_load_dwordx4 v[186:189], v[86:87], off offset:1024
	global_load_dwordx4 v[186:189], v[86:87], off offset:2048
	global_load_dwordx4 v[186:189], v[86:87], off offset:3072
	flat_load_dwordx4 v[8:11], v[86:87]
	v_cndmask_b32_e32 v4, 0, v0, vcc
	v_add_u32_e32 v0, s38, v64
	v_cmp_lt_i32_e32 vcc, s6, v0
	v_ashrrev_i32_e32 v5, 31, v4
	v_lshl_add_u64 v[88:89], v[4:5], 0, s[28:29]
	v_cndmask_b32_e32 v0, v0, v64, vcc
	v_add_u32_e32 v1, 0xfffff000, v0
	v_ashrrev_i32_e32 v1, 10, v1
	v_add_u32_e32 v1, 1, v1
	v_cmp_lt_i32_e32 vcc, s33, v0
	v_mad_u64_u32 v[4:5], s[4:5], v88, s7, v[78:79]
	s_nop 0
	v_cndmask_b32_e32 v2, 0, v1, vcc
	v_add_u32_e32 v1, s35, v64
	v_cmp_lt_i32_e32 vcc, s6, v1
	v_mad_i32_i24 v5, v89, s7, v5
	global_load_dwordx4 v[186:189], v[4:5], off offset:1024
	global_load_dwordx4 v[186:189], v[4:5], off offset:2048
	global_load_dwordx4 v[186:189], v[4:5], off offset:3072
	flat_load_dwordx4 v[12:15], v[4:5]
	v_cndmask_b32_e32 v40, v1, v64, vcc
	v_add_u32_e32 v1, 0xfffff000, v40
	v_ashrrev_i32_e32 v1, 10, v1
	v_add_u32_e32 v1, 1, v1
	v_cmp_lt_i32_e32 vcc, s33, v40
	v_ashrrev_i32_e32 v3, 31, v2
	v_lshl_add_u64 v[92:93], v[2:3], 0, s[28:29]
	v_cndmask_b32_e32 v42, 0, v1, vcc
	v_add_u32_e32 v1, s26, v64
	v_cmp_lt_i32_e32 vcc, s6, v1
	s_mov_b64 s[8:9], 0x1000000
	v_mad_u64_u32 v[48:49], s[4:5], v92, s7, v[78:79]
	v_cndmask_b32_e32 v20, v1, v64, vcc
	v_add_u32_e32 v1, 0xfffff000, v20
	v_ashrrev_i32_e32 v1, 10, v1
	v_add_u32_e32 v1, 1, v1
	v_cmp_lt_i32_e32 vcc, s33, v20
	v_lshlrev_b32_e32 v152, 1, v66
	v_mad_i32_i24 v49, v93, s7, v49
	v_cndmask_b32_e32 v22, 0, v1, vcc
	v_add_co_u32_e32 v6, vcc, s2, v84
	s_brev_b32 s2, 64
	s_nop 0
	v_addc_co_u32_e32 v7, vcc, 0, v85, vcc
	v_add_co_u32_e32 v24, vcc, s2, v84
	global_load_dwordx2 v[186:187], v[6:7], off offset:512
	global_load_dwordx2 v[186:187], v[6:7], off offset:1024
	global_load_dwordx2 v[186:187], v[6:7], off offset:1536
	flat_load_dwordx2 v[16:17], v[6:7]
	s_nop 0
	v_addc_co_u32_e32 v25, vcc, 0, v85, vcc
	global_load_dwordx2 v[186:187], v[24:25], off offset:512
	global_load_dwordx2 v[186:187], v[24:25], off offset:1024
	global_load_dwordx2 v[186:187], v[24:25], off offset:1536
	flat_load_dwordx2 v[26:27], v[24:25]
	v_lshlrev_b32_e32 v104, 1, v68
	v_mov_b32_e32 v105, v153
	v_lshlrev_b32_e32 v106, 1, v70
	v_mov_b32_e32 v107, v153
	v_lshlrev_b32_e32 v120, 1, v72
	v_mov_b32_e32 v121, v153
	v_ashrrev_i32_e32 v41, 31, v40
	v_ashrrev_i32_e32 v43, 31, v42
	v_lshlrev_b64 v[96:97], 11, v[40:41]
	v_lshl_add_u64 v[98:99], v[42:43], 0, s[28:29]
	v_lshl_add_u64 v[42:43], s[56:57], 0, v[96:97]
	v_ashrrev_i32_e32 v21, 31, v20
	v_ashrrev_i32_e32 v23, 31, v22
	s_mov_b32 s2, 0x3727c5ac
	s_waitcnt vmcnt(0) lgkmcnt(0)
	v_lshlrev_b32_e32 v18, 16, v16
	v_and_b32_e32 v19, 0xffff0000, v16
	v_lshlrev_b32_e32 v16, 16, v17
	v_and_b32_e32 v17, 0xffff0000, v17
	v_lshlrev_b32_e32 v28, 16, v26
	v_and_b32_e32 v29, 0xffff0000, v26
	v_lshlrev_b32_e32 v26, 16, v27
	v_and_b32_e32 v27, 0xffff0000, v27
	v_pk_add_f32 v[18:19], v[18:19], v[28:29]
	v_pk_add_f32 v[16:17], v[16:17], v[26:27]
	v_pk_mul_f32 v[12:13], v[12:13], v[18:19]
	v_pk_mul_f32 v[14:15], v[14:15], v[16:17]
	v_pk_fma_f32 v[8:9], v[8:9], s[42:43], v[12:13] op_sel_hi:[1,0,1]
	v_pk_fma_f32 v[10:11], v[10:11], s[42:43], v[14:15] op_sel_hi:[1,0,1]
	v_mov_b32_e32 v14, v8
	v_pk_mov_b32 v[12:13], v[8:9], v[10:11] op_sel:[1,0]
	v_mov_b32_e32 v15, v11
	v_pk_add_f32 v[12:13], v[12:13], v[14:15]
	s_nop 0
	v_add_f32_e32 v1, v12, v13
	flat_load_dwordx4 v[12:15], v[86:87] offset:1024
	flat_load_dwordx4 v[16:19], v[4:5] offset:1024
	flat_load_dwordx2 v[26:27], v[6:7] offset:512
	flat_load_dwordx2 v[32:33], v[24:25] offset:512
	v_add_f32_e32 v28, 0, v1
	v_ashrrev_i32_e32 v1, 31, v0
	v_lshlrev_b64 v[90:91], 11, v[0:1]
	v_lshlrev_b64 v[2:3], 12, v[0:1]
	s_waitcnt vmcnt(0) lgkmcnt(0)
	v_lshlrev_b32_e32 v30, 16, v26
	v_and_b32_e32 v31, 0xffff0000, v26
	v_lshlrev_b32_e32 v26, 16, v27
	v_and_b32_e32 v27, 0xffff0000, v27
	v_lshlrev_b32_e32 v34, 16, v32
	v_and_b32_e32 v35, 0xffff0000, v32
	v_lshlrev_b32_e32 v32, 16, v33
	v_and_b32_e32 v33, 0xffff0000, v33
	v_pk_add_f32 v[30:31], v[30:31], v[34:35]
	v_pk_add_f32 v[26:27], v[26:27], v[32:33]
	v_pk_mul_f32 v[16:17], v[16:17], v[30:31]
	v_pk_mul_f32 v[18:19], v[18:19], v[26:27]
	v_pk_fma_f32 v[12:13], v[12:13], s[42:43], v[16:17] op_sel_hi:[1,0,1]
	v_pk_fma_f32 v[14:15], v[14:15], s[42:43], v[18:19] op_sel_hi:[1,0,1]
	v_mov_b32_e32 v18, v12
	v_pk_mov_b32 v[16:17], v[12:13], v[14:15] op_sel:[1,0]
	v_mov_b32_e32 v19, v15
	v_pk_add_f32 v[16:17], v[16:17], v[18:19]
	s_nop 0
	v_pk_add_f32 v[30:31], v[16:17], v[16:17] op_sel:[0,1] op_sel_hi:[1,0]
	flat_load_dwordx4 v[16:19], v[86:87] offset:2048
	flat_load_dwordx4 v[32:35], v[4:5] offset:2048
	flat_load_dwordx2 v[26:27], v[6:7] offset:1024
	flat_load_dwordx2 v[38:39], v[24:25] offset:1024
	s_waitcnt vmcnt(0) lgkmcnt(0)
	v_lshlrev_b32_e32 v36, 16, v26
	v_and_b32_e32 v37, 0xffff0000, v26
	v_lshlrev_b32_e32 v44, 16, v38
	v_and_b32_e32 v45, 0xffff0000, v38
	v_lshlrev_b32_e32 v26, 16, v27
	v_and_b32_e32 v27, 0xffff0000, v27
	v_lshlrev_b32_e32 v38, 16, v39
	v_and_b32_e32 v39, 0xffff0000, v39
	v_pk_add_f32 v[36:37], v[36:37], v[44:45]
	v_pk_add_f32 v[26:27], v[26:27], v[38:39]
	v_pk_mul_f32 v[32:33], v[32:33], v[36:37]
	v_pk_mul_f32 v[26:27], v[34:35], v[26:27]
	v_pk_fma_f32 v[16:17], v[16:17], s[42:43], v[32:33] op_sel_hi:[1,0,1]
	flat_load_dwordx4 v[32:35], v[86:87] offset:3072
	flat_load_dwordx4 v[36:39], v[4:5] offset:3072
	s_nop 0
	flat_load_dwordx2 v[4:5], v[6:7] offset:1536
	v_pk_fma_f32 v[18:19], v[18:19], s[42:43], v[26:27] op_sel_hi:[1,0,1]
	flat_load_dwordx2 v[24:25], v[24:25] offset:1536
	v_add_f32_e32 v44, v16, v17
	v_add_f32_e32 v46, v18, v19
	s_waitcnt vmcnt(0) lgkmcnt(0)
	v_lshlrev_b32_e32 v6, 16, v4
	v_and_b32_e32 v7, 0xffff0000, v4
	v_lshlrev_b32_e32 v26, 16, v24
	v_and_b32_e32 v27, 0xffff0000, v24
	v_lshlrev_b32_e32 v4, 16, v5
	v_and_b32_e32 v5, 0xffff0000, v5
	v_lshlrev_b32_e32 v24, 16, v25
	v_and_b32_e32 v25, 0xffff0000, v25
	v_pk_add_f32 v[6:7], v[6:7], v[26:27]
	v_pk_add_f32 v[4:5], v[4:5], v[24:25]
	v_pk_mul_f32 v[6:7], v[36:37], v[6:7]
	v_pk_mul_f32 v[4:5], v[38:39], v[4:5]
	v_pk_fma_f32 v[24:25], v[32:33], s[42:43], v[6:7] op_sel_hi:[1,0,1]
	v_pk_fma_f32 v[26:27], v[34:35], s[42:43], v[4:5] op_sel_hi:[1,0,1]
	v_mov_b32_e32 v29, v24
	v_mov_b32_e32 v31, v25
	v_pk_add_f32 v[4:5], v[28:29], v[30:31]
	v_mov_b32_e32 v45, v26
	v_mov_b32_e32 v47, v27
	v_lshl_add_u64 v[28:29], s[56:57], 0, v[90:91]
	v_pk_add_f32 v[6:7], v[44:45], v[46:47]
	v_lshl_add_u64 v[44:45], v[28:29], 0, s[8:9]
	v_pk_add_f32 v[4:5], v[4:5], v[6:7]
	v_lshl_add_u64 v[52:53], v[28:29], 0, v[152:153]
	v_lshl_add_u64 v[34:35], v[44:45], 0, v[152:153]
	v_add_f32_e32 v122, v4, v5
	global_load_dwordx4 v[186:189], v[48:49], off offset:1024
	global_load_dwordx4 v[186:189], v[48:49], off offset:2048
	global_load_dwordx4 v[186:189], v[48:49], off offset:3072
	flat_load_dwordx4 v[4:7], v[48:49]
	global_load_dwordx2 v[186:187], v[52:53], off offset:512
	global_load_dwordx2 v[186:187], v[52:53], off offset:1024
	global_load_dwordx2 v[186:187], v[52:53], off offset:1536
	flat_load_dwordx2 v[28:29], v[52:53]
	v_lshl_add_u64 v[32:33], v[80:81], 0, v[2:3]
	global_load_dwordx2 v[186:187], v[34:35], off offset:512
	global_load_dwordx2 v[186:187], v[34:35], off offset:1024
	global_load_dwordx2 v[186:187], v[34:35], off offset:1536
	flat_load_dwordx2 v[34:35], v[34:35]
	v_lshl_add_u64 v[38:39], v[44:45], 0, v[104:105]
	global_load_dwordx4 v[186:189], v[32:33], off offset:1024
	global_load_dwordx4 v[186:189], v[32:33], off offset:2048
	global_load_dwordx4 v[186:189], v[32:33], off offset:3072
	flat_load_dwordx4 v[0:3], v[32:33]
	v_lshl_add_u64 v[54:55], v[44:45], 0, v[106:107]
	v_lshl_add_u64 v[44:45], v[44:45], 0, v[120:121]
	s_waitcnt vmcnt(0) lgkmcnt(0)
	v_lshlrev_b32_e32 v30, 16, v28
	v_and_b32_e32 v31, 0xffff0000, v28
	v_lshlrev_b32_e32 v28, 16, v29
	v_and_b32_e32 v29, 0xffff0000, v29
	v_lshlrev_b32_e32 v36, 16, v34
	v_and_b32_e32 v37, 0xffff0000, v34
	v_lshlrev_b32_e32 v34, 16, v35
	v_and_b32_e32 v35, 0xffff0000, v35
	v_pk_add_f32 v[30:31], v[30:31], v[36:37]
	v_pk_add_f32 v[28:29], v[28:29], v[34:35]
	v_pk_mul_f32 v[4:5], v[4:5], v[30:31]
	v_pk_mul_f32 v[6:7], v[6:7], v[28:29]
	v_pk_fma_f32 v[28:29], v[0:1], s[42:43], v[4:5] op_sel_hi:[1,0,1]
	v_pk_fma_f32 v[30:31], v[2:3], s[42:43], v[6:7] op_sel_hi:[1,0,1]
	v_mov_b32_e32 v2, v28
	v_pk_mov_b32 v[0:1], v[28:29], v[30:31] op_sel:[1,0]
	v_mov_b32_e32 v3, v31
	v_pk_add_f32 v[0:1], v[0:1], v[2:3]
	s_nop 0
	v_add_f32_e32 v0, v0, v1
	v_add_f32_e32 v46, 0, v0
	flat_load_dwordx4 v[0:3], v[32:33] offset:1024
	flat_load_dwordx4 v[4:7], v[48:49] offset:1024
	flat_load_dwordx2 v[34:35], v[52:53] offset:512
	s_waitcnt vmcnt(0) lgkmcnt(0)
	v_lshlrev_b32_e32 v36, 16, v34
	flat_load_dwordx2 v[38:39], v[38:39]
	v_and_b32_e32 v37, 0xffff0000, v34
	v_lshlrev_b32_e32 v34, 16, v35
	v_and_b32_e32 v35, 0xffff0000, v35
	s_waitcnt vmcnt(0) lgkmcnt(0)
	v_lshlrev_b32_e32 v50, 16, v38
	v_and_b32_e32 v51, 0xffff0000, v38
	v_lshlrev_b32_e32 v38, 16, v39
	v_and_b32_e32 v39, 0xffff0000, v39
	v_pk_add_f32 v[36:37], v[36:37], v[50:51]
	v_pk_add_f32 v[34:35], v[34:35], v[38:39]
	v_pk_mul_f32 v[4:5], v[4:5], v[36:37]
	v_pk_mul_f32 v[6:7], v[6:7], v[34:35]
	v_pk_fma_f32 v[38:39], v[0:1], s[42:43], v[4:5] op_sel_hi:[1,0,1]
	v_pk_fma_f32 v[60:61], v[2:3], s[42:43], v[6:7] op_sel_hi:[1,0,1]
	v_mov_b32_e32 v2, v38
	v_pk_mov_b32 v[0:1], v[38:39], v[60:61] op_sel:[1,0]
	v_mov_b32_e32 v3, v61
	v_pk_add_f32 v[0:1], v[0:1], v[2:3]
	s_nop 0
	v_pk_add_f32 v[50:51], v[0:1], v[0:1] op_sel:[0,1] op_sel_hi:[1,0]
	flat_load_dwordx4 v[0:3], v[32:33] offset:2048
	flat_load_dwordx4 v[4:7], v[48:49] offset:2048
	flat_load_dwordx2 v[34:35], v[52:53] offset:1024
	s_waitcnt vmcnt(0) lgkmcnt(0)
	v_lshlrev_b32_e32 v36, 16, v34
	flat_load_dwordx2 v[54:55], v[54:55]
	v_and_b32_e32 v37, 0xffff0000, v34
	v_lshlrev_b32_e32 v34, 16, v35
	v_and_b32_e32 v35, 0xffff0000, v35
	s_waitcnt vmcnt(0) lgkmcnt(0)
	v_lshlrev_b32_e32 v56, 16, v54
	v_and_b32_e32 v57, 0xffff0000, v54
	v_lshlrev_b32_e32 v54, 16, v55
	v_and_b32_e32 v55, 0xffff0000, v55
	v_pk_add_f32 v[34:35], v[34:35], v[54:55]
	v_pk_add_f32 v[36:37], v[36:37], v[56:57]
	v_pk_mul_f32 v[6:7], v[6:7], v[34:35]
	v_pk_mul_f32 v[4:5], v[4:5], v[36:37]
	v_pk_fma_f32 v[36:37], v[2:3], s[42:43], v[6:7] op_sel_hi:[1,0,1]
	v_pk_fma_f32 v[34:35], v[0:1], s[42:43], v[4:5] op_sel_hi:[1,0,1]
	flat_load_dwordx4 v[0:3], v[32:33] offset:3072
	flat_load_dwordx4 v[4:7], v[48:49] offset:3072
	s_nop 0
	flat_load_dwordx2 v[52:53], v[52:53] offset:1536
	v_add_f32_e32 v54, v34, v35
	flat_load_dwordx2 v[44:45], v[44:45]
	v_add_f32_e32 v56, v36, v37
	s_waitcnt vmcnt(0) lgkmcnt(0)
	v_lshlrev_b32_e32 v48, 16, v52
	v_and_b32_e32 v49, 0xffff0000, v52
	v_lshlrev_b32_e32 v58, 16, v44
	v_and_b32_e32 v59, 0xffff0000, v44
	v_lshlrev_b32_e32 v52, 16, v53
	v_and_b32_e32 v53, 0xffff0000, v53
	v_lshlrev_b32_e32 v44, 16, v45
	v_and_b32_e32 v45, 0xffff0000, v45
	v_pk_add_f32 v[48:49], v[48:49], v[58:59]
	v_pk_add_f32 v[44:45], v[52:53], v[44:45]
	v_pk_mul_f32 v[4:5], v[4:5], v[48:49]
	v_pk_mul_f32 v[6:7], v[6:7], v[44:45]
	v_pk_fma_f32 v[62:63], v[0:1], s[42:43], v[4:5] op_sel_hi:[1,0,1]
	v_pk_fma_f32 v[118:119], v[2:3], s[42:43], v[6:7] op_sel_hi:[1,0,1]
	v_mov_b32_e32 v47, v62
	v_mov_b32_e32 v51, v63
	v_pk_add_f32 v[0:1], v[46:47], v[50:51]
	v_mov_b32_e32 v55, v118
	v_mov_b32_e32 v57, v119
	v_lshl_add_u64 v[44:45], v[42:43], 0, s[8:9]
	v_mad_u64_u32 v[46:47], s[4:5], v98, s7, v[78:79]
	v_pk_add_f32 v[2:3], v[54:55], v[56:57]
	v_mad_i32_i24 v47, v99, s7, v47
	v_lshl_add_u64 v[42:43], v[42:43], 0, v[152:153]
	v_lshl_add_u64 v[52:53], v[44:45], 0, v[152:153]
	v_pk_add_f32 v[0:1], v[0:1], v[2:3]
	global_load_dwordx4 v[186:189], v[46:47], off offset:1024
	global_load_dwordx4 v[186:189], v[46:47], off offset:2048
	global_load_dwordx4 v[186:189], v[46:47], off offset:3072
	flat_load_dwordx4 v[4:7], v[46:47]
	global_load_dwordx2 v[186:187], v[42:43], off offset:512
	global_load_dwordx2 v[186:187], v[42:43], off offset:1024
	global_load_dwordx2 v[186:187], v[42:43], off offset:1536
	flat_load_dwordx2 v[48:49], v[42:43]
	v_add_f32_e32 v126, v0, v1
	global_load_dwordx2 v[186:187], v[52:53], off offset:512
	global_load_dwordx2 v[186:187], v[52:53], off offset:1024
	global_load_dwordx2 v[186:187], v[52:53], off offset:1536
	flat_load_dwordx2 v[52:53], v[52:53]
	v_lshlrev_b64 v[0:1], 12, v[40:41]
	v_lshl_add_u64 v[40:41], v[80:81], 0, v[0:1]
	global_load_dwordx4 v[186:189], v[40:41], off offset:1024
	global_load_dwordx4 v[186:189], v[40:41], off offset:2048
	global_load_dwordx4 v[186:189], v[40:41], off offset:3072
	flat_load_dwordx4 v[0:3], v[40:41]
	v_lshl_add_u64 v[56:57], v[44:45], 0, v[104:105]
	v_lshl_add_u64 v[102:103], v[44:45], 0, v[106:107]
	v_lshl_add_u64 v[44:45], v[44:45], 0, v[120:121]
	s_waitcnt vmcnt(0) lgkmcnt(0)
	v_lshlrev_b32_e32 v50, 16, v48
	v_and_b32_e32 v51, 0xffff0000, v48
	v_lshlrev_b32_e32 v48, 16, v49
	v_and_b32_e32 v49, 0xffff0000, v49
	v_lshlrev_b32_e32 v54, 16, v52
	v_and_b32_e32 v55, 0xffff0000, v52
	v_lshlrev_b32_e32 v52, 16, v53
	v_and_b32_e32 v53, 0xffff0000, v53
	v_pk_add_f32 v[50:51], v[50:51], v[54:55]
	v_pk_add_f32 v[48:49], v[48:49], v[52:53]
	v_pk_mul_f32 v[4:5], v[4:5], v[50:51]
	v_pk_mul_f32 v[6:7], v[6:7], v[48:49]
	v_pk_fma_f32 v[50:51], v[0:1], s[42:43], v[4:5] op_sel_hi:[1,0,1]
	v_pk_fma_f32 v[52:53], v[2:3], s[42:43], v[6:7] op_sel_hi:[1,0,1]
	v_mov_b32_e32 v2, v50
	v_pk_mov_b32 v[0:1], v[50:51], v[52:53] op_sel:[1,0]
	v_mov_b32_e32 v3, v53
	v_pk_add_f32 v[0:1], v[0:1], v[2:3]
	s_nop 0
	v_add_f32_e32 v0, v0, v1
	v_add_f32_e32 v94, 0, v0
	flat_load_dwordx4 v[0:3], v[40:41] offset:1024
	flat_load_dwordx4 v[4:7], v[46:47] offset:1024
	flat_load_dwordx2 v[48:49], v[42:43] offset:512
	s_waitcnt vmcnt(0) lgkmcnt(0)
	v_lshlrev_b32_e32 v54, 16, v48
	flat_load_dwordx2 v[56:57], v[56:57]
	v_and_b32_e32 v55, 0xffff0000, v48
	v_lshlrev_b32_e32 v48, 16, v49
	v_and_b32_e32 v49, 0xffff0000, v49
	s_waitcnt vmcnt(0) lgkmcnt(0)
	v_lshlrev_b32_e32 v58, 16, v56
	v_and_b32_e32 v59, 0xffff0000, v56
	v_lshlrev_b32_e32 v56, 16, v57
	v_and_b32_e32 v57, 0xffff0000, v57
	v_pk_add_f32 v[54:55], v[54:55], v[58:59]
	v_pk_add_f32 v[48:49], v[48:49], v[56:57]
	v_pk_mul_f32 v[4:5], v[4:5], v[54:55]
	v_pk_mul_f32 v[6:7], v[6:7], v[48:49]
	v_pk_fma_f32 v[56:57], v[0:1], s[42:43], v[4:5] op_sel_hi:[1,0,1]
	v_pk_fma_f32 v[58:59], v[2:3], s[42:43], v[6:7] op_sel_hi:[1,0,1]
	v_mov_b32_e32 v2, v56
	v_pk_mov_b32 v[0:1], v[56:57], v[58:59] op_sel:[1,0]
	v_mov_b32_e32 v3, v59
	v_pk_add_f32 v[0:1], v[0:1], v[2:3]
	s_nop 0
	v_pk_add_f32 v[100:101], v[0:1], v[0:1] op_sel:[0,1] op_sel_hi:[1,0]
	flat_load_dwordx4 v[0:3], v[40:41] offset:2048
	flat_load_dwordx4 v[4:7], v[46:47] offset:2048
	flat_load_dwordx2 v[48:49], v[42:43] offset:1024
	s_waitcnt vmcnt(0) lgkmcnt(0)
	v_lshlrev_b32_e32 v54, 16, v48
	flat_load_dwordx2 v[102:103], v[102:103]
	v_and_b32_e32 v55, 0xffff0000, v48
	v_lshlrev_b32_e32 v48, 16, v49
	v_and_b32_e32 v49, 0xffff0000, v49
	s_waitcnt vmcnt(0) lgkmcnt(0)
	v_lshlrev_b32_e32 v108, 16, v102
	v_and_b32_e32 v109, 0xffff0000, v102
	v_lshlrev_b32_e32 v102, 16, v103
	v_and_b32_e32 v103, 0xffff0000, v103
	v_pk_add_f32 v[48:49], v[48:49], v[102:103]
	v_pk_add_f32 v[54:55], v[54:55], v[108:109]
	v_pk_mul_f32 v[6:7], v[6:7], v[48:49]
	v_pk_mul_f32 v[4:5], v[4:5], v[54:55]
	v_pk_fma_f32 v[116:117], v[2:3], s[42:43], v[6:7] op_sel_hi:[1,0,1]
	v_pk_fma_f32 v[54:55], v[0:1], s[42:43], v[4:5] op_sel_hi:[1,0,1]
	flat_load_dwordx4 v[0:3], v[40:41] offset:3072
	flat_load_dwordx4 v[4:7], v[46:47] offset:3072
	s_nop 0
	flat_load_dwordx2 v[42:43], v[42:43] offset:1536
	v_add_f32_e32 v102, v54, v55
	flat_load_dwordx2 v[44:45], v[44:45]
	v_add_f32_e32 v108, v116, v117
	s_waitcnt vmcnt(0) lgkmcnt(0)
	v_lshlrev_b32_e32 v46, 16, v42
	v_and_b32_e32 v47, 0xffff0000, v42
	v_lshlrev_b32_e32 v42, 16, v43
	v_and_b32_e32 v43, 0xffff0000, v43
	v_lshlrev_b32_e32 v48, 16, v44
	v_and_b32_e32 v49, 0xffff0000, v44
	v_lshlrev_b32_e32 v44, 16, v45
	v_and_b32_e32 v45, 0xffff0000, v45
	v_pk_add_f32 v[42:43], v[42:43], v[44:45]
	v_pk_add_f32 v[44:45], v[46:47], v[48:49]
	v_pk_mul_f32 v[6:7], v[6:7], v[42:43]
	v_pk_mul_f32 v[4:5], v[4:5], v[44:45]
	v_pk_fma_f32 v[48:49], v[2:3], s[42:43], v[6:7] op_sel_hi:[1,0,1]
	v_pk_fma_f32 v[46:47], v[0:1], s[42:43], v[4:5] op_sel_hi:[1,0,1]
	v_mov_b32_e32 v103, v48
	v_mov_b32_e32 v95, v46
	v_mov_b32_e32 v101, v47
	v_mov_b32_e32 v109, v49
	v_pk_add_f32 v[0:1], v[94:95], v[100:101]
	v_pk_add_f32 v[2:3], v[102:103], v[108:109]
	v_lshlrev_b64 v[94:95], 11, v[20:21]
	v_pk_add_f32 v[0:1], v[0:1], v[2:3]
	v_lshl_add_u64 v[100:101], v[22:23], 0, s[28:29]
	v_add_f32_e32 v125, v0, v1
	v_lshlrev_b64 v[0:1], 12, v[20:21]
	v_lshl_add_u64 v[20:21], s[56:57], 0, v[94:95]
	v_lshl_add_u64 v[22:23], v[20:21], 0, s[8:9]
	v_mad_u64_u32 v[128:129], s[4:5], v100, s7, v[78:79]
	v_mad_i32_i24 v129, v101, s7, v129
	v_lshl_add_u64 v[20:21], v[20:21], 0, v[152:153]
	v_lshl_add_u64 v[108:109], v[22:23], 0, v[152:153]
	global_load_dwordx4 v[186:189], v[128:129], off offset:1024
	global_load_dwordx4 v[186:189], v[128:129], off offset:2048
	global_load_dwordx4 v[186:189], v[128:129], off offset:3072
	flat_load_dwordx4 v[4:7], v[128:129]
	global_load_dwordx2 v[186:187], v[20:21], off offset:512
	global_load_dwordx2 v[186:187], v[20:21], off offset:1024
	global_load_dwordx2 v[186:187], v[20:21], off offset:1536
	flat_load_dwordx2 v[42:43], v[20:21]
	v_lshl_add_u64 v[102:103], v[80:81], 0, v[0:1]
	global_load_dwordx2 v[186:187], v[108:109], off offset:512
	global_load_dwordx2 v[186:187], v[108:109], off offset:1024
	global_load_dwordx2 v[186:187], v[108:109], off offset:1536
	flat_load_dwordx2 v[108:109], v[108:109]
	v_lshl_add_u64 v[104:105], v[22:23], 0, v[104:105]
	global_load_dwordx4 v[186:189], v[102:103], off offset:1024
	global_load_dwordx4 v[186:189], v[102:103], off offset:2048
	global_load_dwordx4 v[186:189], v[102:103], off offset:3072
	flat_load_dwordx4 v[0:3], v[102:103]
	v_lshl_add_u64 v[106:107], v[22:23], 0, v[106:107]
	v_lshl_add_u64 v[22:23], v[22:23], 0, v[120:121]
	v_readlane_b32 s4, v254, 33
	v_readlane_b32 s5, v254, 34
	s_waitcnt vmcnt(0) lgkmcnt(0)
	v_lshlrev_b32_e32 v44, 16, v42
	v_and_b32_e32 v45, 0xffff0000, v42
	v_lshlrev_b32_e32 v42, 16, v43
	v_and_b32_e32 v43, 0xffff0000, v43
	v_lshlrev_b32_e32 v110, 16, v108
	v_and_b32_e32 v111, 0xffff0000, v108
	v_lshlrev_b32_e32 v108, 16, v109
	v_and_b32_e32 v109, 0xffff0000, v109
	v_pk_add_f32 v[44:45], v[44:45], v[110:111]
	v_pk_add_f32 v[42:43], v[42:43], v[108:109]
	v_pk_mul_f32 v[4:5], v[4:5], v[44:45]
	v_pk_mul_f32 v[6:7], v[6:7], v[42:43]
	v_pk_fma_f32 v[44:45], v[0:1], s[42:43], v[4:5] op_sel_hi:[1,0,1]
	v_pk_fma_f32 v[114:115], v[2:3], s[42:43], v[6:7] op_sel_hi:[1,0,1]
	v_mov_b32_e32 v2, v44
	v_pk_mov_b32 v[0:1], v[44:45], v[114:115] op_sel:[1,0]
	v_mov_b32_e32 v3, v115
	v_pk_add_f32 v[0:1], v[0:1], v[2:3]
	s_nop 0
	v_add_f32_e32 v0, v0, v1
	v_add_f32_e32 v130, 0, v0
	flat_load_dwordx4 v[0:3], v[102:103] offset:1024
	flat_load_dwordx4 v[4:7], v[128:129] offset:1024
	flat_load_dwordx2 v[42:43], v[20:21] offset:512
	s_waitcnt vmcnt(0) lgkmcnt(0)
	v_lshlrev_b32_e32 v108, 16, v42
	flat_load_dwordx2 v[104:105], v[104:105]
	v_and_b32_e32 v109, 0xffff0000, v42
	v_lshlrev_b32_e32 v42, 16, v43
	v_and_b32_e32 v43, 0xffff0000, v43
	s_waitcnt vmcnt(0) lgkmcnt(0)
	v_lshlrev_b32_e32 v110, 16, v104
	v_and_b32_e32 v111, 0xffff0000, v104
	v_lshlrev_b32_e32 v104, 16, v105
	v_and_b32_e32 v105, 0xffff0000, v105
	v_pk_add_f32 v[108:109], v[108:109], v[110:111]
	v_pk_add_f32 v[42:43], v[42:43], v[104:105]
	v_pk_mul_f32 v[4:5], v[4:5], v[108:109]
	v_pk_mul_f32 v[6:7], v[6:7], v[42:43]
	v_pk_fma_f32 v[42:43], v[0:1], s[42:43], v[4:5] op_sel_hi:[1,0,1]
	v_pk_fma_f32 v[112:113], v[2:3], s[42:43], v[6:7] op_sel_hi:[1,0,1]
	v_mov_b32_e32 v2, v42
	v_pk_mov_b32 v[0:1], v[42:43], v[112:113] op_sel:[1,0]
	v_mov_b32_e32 v3, v113
	v_pk_add_f32 v[0:1], v[0:1], v[2:3]
	s_nop 0
	v_pk_add_f32 v[132:133], v[0:1], v[0:1] op_sel:[0,1] op_sel_hi:[1,0]
	flat_load_dwordx4 v[0:3], v[102:103] offset:2048
	flat_load_dwordx4 v[4:7], v[128:129] offset:2048
	flat_load_dwordx2 v[104:105], v[20:21] offset:1024
	s_waitcnt vmcnt(0) lgkmcnt(0)
	v_lshlrev_b32_e32 v108, 16, v104
	flat_load_dwordx2 v[106:107], v[106:107]
	v_and_b32_e32 v109, 0xffff0000, v104
	v_lshlrev_b32_e32 v104, 16, v105
	v_and_b32_e32 v105, 0xffff0000, v105
	s_waitcnt vmcnt(0) lgkmcnt(0)
	v_lshlrev_b32_e32 v110, 16, v106
	v_and_b32_e32 v111, 0xffff0000, v106
	v_lshlrev_b32_e32 v106, 16, v107
	v_and_b32_e32 v107, 0xffff0000, v107
	v_pk_add_f32 v[104:105], v[104:105], v[106:107]
	v_pk_add_f32 v[106:107], v[108:109], v[110:111]
	v_pk_mul_f32 v[6:7], v[6:7], v[104:105]
	v_pk_mul_f32 v[4:5], v[4:5], v[106:107]
	v_pk_fma_f32 v[110:111], v[2:3], s[42:43], v[6:7] op_sel_hi:[1,0,1]
	v_pk_fma_f32 v[108:109], v[0:1], s[42:43], v[4:5] op_sel_hi:[1,0,1]
	flat_load_dwordx4 v[0:3], v[102:103] offset:3072
	flat_load_dwordx4 v[4:7], v[128:129] offset:3072
	s_nop 0
	flat_load_dwordx2 v[20:21], v[20:21] offset:1536
	v_add_f32_e32 v134, v108, v109
	flat_load_dwordx2 v[22:23], v[22:23]
	v_add_f32_e32 v136, v110, v111
	s_waitcnt vmcnt(0) lgkmcnt(0)
	v_lshlrev_b32_e32 v104, 16, v20
	v_and_b32_e32 v105, 0xffff0000, v20
	v_lshlrev_b32_e32 v20, 16, v21
	v_and_b32_e32 v21, 0xffff0000, v21
	v_lshlrev_b32_e32 v106, 16, v22
	v_and_b32_e32 v107, 0xffff0000, v22
	v_lshlrev_b32_e32 v22, 16, v23
	v_and_b32_e32 v23, 0xffff0000, v23
	v_pk_add_f32 v[20:21], v[20:21], v[22:23]
	v_pk_add_f32 v[22:23], v[104:105], v[106:107]
	v_pk_mul_f32 v[6:7], v[6:7], v[20:21]
	v_pk_mul_f32 v[4:5], v[4:5], v[22:23]
	v_pk_fma_f32 v[106:107], v[2:3], s[42:43], v[6:7] op_sel_hi:[1,0,1]
	v_pk_fma_f32 v[104:105], v[0:1], s[42:43], v[4:5] op_sel_hi:[1,0,1]
	v_mov_b32_e32 v135, v106
	v_mov_b32_e32 v131, v104
	v_mov_b32_e32 v133, v105
	v_mov_b32_e32 v137, v107
	v_pk_add_f32 v[0:1], v[130:131], v[132:133]
	v_pk_add_f32 v[2:3], v[134:135], v[136:137]
	ds_bpermute_b32 v22, v67, v126
	v_pk_add_f32 v[0:1], v[0:1], v[2:3]
	s_waitcnt lgkmcnt(0)
	v_add_f32_e32 v22, v126, v22
	v_add_f32_e32 v65, v0, v1
	ds_bpermute_b32 v0, v67, v122
	ds_bpermute_b32 v23, v69, v22
	s_waitcnt lgkmcnt(1)
	v_add_f32_e32 v0, v122, v0
	ds_bpermute_b32 v1, v69, v0
	s_waitcnt lgkmcnt(1)
	v_add_f32_e32 v22, v22, v23
	ds_bpermute_b32 v23, v71, v22
	s_waitcnt lgkmcnt(1)
	v_add_f32_e32 v0, v0, v1
	ds_bpermute_b32 v1, v71, v0
	s_waitcnt lgkmcnt(1)
	v_add_f32_e32 v22, v22, v23
	ds_bpermute_b32 v23, v73, v22
	s_waitcnt lgkmcnt(1)
	v_add_f32_e32 v0, v0, v1
	ds_bpermute_b32 v1, v73, v0
	s_waitcnt lgkmcnt(1)
	v_add_f32_e32 v22, v22, v23
	ds_bpermute_b32 v23, v123, v22
	s_waitcnt lgkmcnt(1)
	v_add_f32_e32 v0, v0, v1
	ds_bpermute_b32 v1, v123, v0
	s_waitcnt lgkmcnt(1)
	v_add_f32_e32 v22, v22, v23
	ds_bpermute_b32 v23, v124, v22
	s_waitcnt lgkmcnt(1)
	v_add_f32_e32 v0, v0, v1
	ds_bpermute_b32 v1, v124, v0
	s_waitcnt lgkmcnt(1)
	v_add_f32_e32 v122, v22, v23
	v_fmamk_f32 v29, v122, 0xba800000, v29
	v_fmac_f32_e32 v28, 0xba800000, v122
	v_fmamk_f32 v31, v122, 0xba800000, v31
	s_waitcnt lgkmcnt(0)
	v_add_f32_e32 v20, v0, v1
	v_fmamk_f32 v9, v20, 0xba800000, v9
	v_fmac_f32_e32 v8, 0xba800000, v20
	v_fmamk_f32 v11, v20, 0xba800000, v11
	v_fmac_f32_e32 v10, 0xba800000, v20
	v_pk_mul_f32 v[0:1], v[10:11], v[10:11]
	v_pk_mul_f32 v[2:3], v[8:9], v[8:9]
	v_fmamk_f32 v13, v20, 0xba800000, v13
	v_pk_mov_b32 v[4:5], v[2:3], v[0:1] op_sel:[1,0]
	v_mov_b32_e32 v3, v1
	v_pk_add_f32 v[0:1], v[4:5], v[2:3]
	v_fmac_f32_e32 v12, 0xba800000, v20
	v_fmamk_f32 v15, v20, 0xba800000, v15
	v_fmac_f32_e32 v14, 0xba800000, v20
	v_pk_add_f32 v[0:1], v[0:1], v[0:1] op_sel_hi:[0,1]
	v_pk_mul_f32 v[2:3], v[14:15], v[14:15]
	v_pk_mul_f32 v[4:5], v[12:13], v[12:13]
	v_fmac_f32_e32 v16, 0xba800000, v20
	v_pk_mov_b32 v[6:7], v[4:5], v[2:3] op_sel:[1,0]
	v_mov_b32_e32 v5, v3
	v_fmamk_f32 v17, v20, 0xba800000, v17
	v_fmac_f32_e32 v18, 0xba800000, v20
	v_mul_f32_e32 v0, v16, v16
	v_pk_add_f32 v[2:3], v[6:7], v[4:5]
	v_fmamk_f32 v19, v20, 0xba800000, v19
	v_pk_fma_f32 v[4:5], v[16:17], v[16:17], v[0:1] op_sel_hi:[1,1,0]
	v_mul_f32_e32 v0, v18, v18
	v_pk_add_f32 v[2:3], v[2:3], v[2:3] op_sel_hi:[0,1]
	v_pk_fma_f32 v[6:7], v[18:19], v[18:19], v[0:1] op_sel_hi:[1,1,0]
	v_fmamk_f32 v27, v20, 0xba800000, v27
	v_fmac_f32_e32 v26, 0xba800000, v20
	v_fmamk_f32 v25, v20, 0xba800000, v25
	v_fmac_f32_e32 v24, 0xba800000, v20
	v_mul_f32_e32 v4, v24, v24
	v_mul_f32_e32 v6, v25, v25
	v_mul_f32_e32 v0, v26, v26
	v_mul_f32_e32 v2, v27, v27
	v_pk_add_f32 v[4:5], v[4:5], v[6:7]
	v_pk_add_f32 v[0:1], v[0:1], v[2:3]
	v_fmac_f32_e32 v30, 0xba800000, v122
	v_pk_add_f32 v[20:21], v[4:5], v[0:1]
	v_mov_b64_e32 v[0:1], v[154:155]
	v_mov_b64_e32 v[2:3], v[156:157]
	v_mov_b64_e32 v[4:5], v[158:159]
	v_mov_b64_e32 v[6:7], v[160:161]
	v_pk_mul_f32 v[22:23], v[30:31], v[30:31]
	v_pk_mul_f32 v[120:121], v[28:29], v[28:29]
	v_fmamk_f32 v39, v122, 0xba800000, v39
	v_pk_mov_b32 v[126:127], v[120:121], v[22:23] op_sel:[1,0]
	v_mov_b32_e32 v121, v23
	v_pk_add_f32 v[22:23], v[126:127], v[120:121]
	v_fmac_f32_e32 v38, 0xba800000, v122
	v_fmamk_f32 v61, v122, 0xba800000, v61
	v_fmac_f32_e32 v60, 0xba800000, v122
	v_pk_add_f32 v[22:23], v[22:23], v[22:23] op_sel_hi:[0,1]
	v_pk_mul_f32 v[120:121], v[60:61], v[60:61]
	v_pk_mul_f32 v[126:127], v[38:39], v[38:39]
	v_fmac_f32_e32 v34, 0xba800000, v122
	v_pk_mov_b32 v[128:129], v[126:127], v[120:121] op_sel:[1,0]
	v_mov_b32_e32 v127, v121
	v_fmamk_f32 v35, v122, 0xba800000, v35
	v_fmac_f32_e32 v36, 0xba800000, v122
	v_mul_f32_e32 v22, v34, v34
	v_pk_add_f32 v[120:121], v[128:129], v[126:127]
	v_fmamk_f32 v37, v122, 0xba800000, v37
	v_pk_fma_f32 v[126:127], v[34:35], v[34:35], v[22:23] op_sel_hi:[1,1,0]
	v_mul_f32_e32 v22, v36, v36
	v_pk_add_f32 v[120:121], v[120:121], v[120:121] op_sel_hi:[0,1]
	v_pk_fma_f32 v[128:129], v[36:37], v[36:37], v[22:23] op_sel_hi:[1,1,0]
	v_fmamk_f32 v119, v122, 0xba800000, v119
	v_fmac_f32_e32 v118, 0xba800000, v122
	v_fmamk_f32 v63, v122, 0xba800000, v63
	v_fmac_f32_e32 v62, 0xba800000, v122
	v_mul_f32_e32 v126, v62, v62
	v_mul_f32_e32 v128, v63, v63
	v_mul_f32_e32 v22, v118, v118
	v_mul_f32_e32 v120, v119, v119
	v_pk_add_f32 v[126:127], v[126:127], v[128:129]
	v_pk_add_f32 v[22:23], v[22:23], v[120:121]
	v_mov_b32_e32 v121, v20
	v_pk_add_f32 v[22:23], v[126:127], v[22:23]
	s_nop 0
	v_mov_b32_e32 v120, v22
	v_mov_b32_e32 v20, v23
	v_pk_add_f32 v[20:21], v[120:121], v[20:21]
	ds_bpermute_b32 v23, v67, v21
	ds_bpermute_b32 v22, v67, v20
	v_mov_b64_e32 v[120:121], s[2:3]
	s_mov_b32 s2, 0x3a800000
	s_waitcnt lgkmcnt(0)
	v_pk_add_f32 v[20:21], v[20:21], v[22:23]
	ds_bpermute_b32 v23, v69, v21
	ds_bpermute_b32 v22, v69, v20
	s_waitcnt lgkmcnt(0)
	v_pk_add_f32 v[20:21], v[20:21], v[22:23]
	ds_bpermute_b32 v23, v71, v21
	ds_bpermute_b32 v22, v71, v20
	s_waitcnt lgkmcnt(0)
	v_pk_add_f32 v[20:21], v[20:21], v[22:23]
	ds_bpermute_b32 v23, v73, v21
	ds_bpermute_b32 v22, v73, v20
	s_waitcnt lgkmcnt(0)
	v_pk_add_f32 v[20:21], v[20:21], v[22:23]
	ds_bpermute_b32 v23, v123, v21
	ds_bpermute_b32 v22, v123, v20
	s_waitcnt lgkmcnt(0)
	v_pk_add_f32 v[20:21], v[20:21], v[22:23]
	ds_bpermute_b32 v23, v124, v21
	ds_bpermute_b32 v22, v124, v20
	s_waitcnt lgkmcnt(0)
	v_pk_add_f32 v[20:21], v[20:21], v[22:23]
	s_nop 0
	v_pk_fma_f32 v[126:127], v[20:21], s[2:3], v[120:121] op_sel_hi:[1,0,0]
	s_nop 0
	v_mul_f32_e32 v20, 0x4b800000, v127
	v_cmp_gt_f32_e64 s[8:9], s68, v127
	v_cmp_gt_f32_e32 vcc, s68, v126
	s_nop 0
	v_cndmask_b32_e64 v20, v127, v20, s[8:9]
	v_rsq_f32_e32 v20, v20
	s_nop 0
	v_mul_f32_e32 v21, 0x45800000, v20
	v_cndmask_b32_e64 v122, v20, v21, s[8:9]
	v_pk_mul_f32 v[8:9], v[8:9], v[122:123] op_sel_hi:[1,0]
	v_pk_mul_f32 v[10:11], v[10:11], v[122:123] op_sel_hi:[1,0]
	v_pk_fma_f32 v[20:21], v[0:1], v[8:9], v[4:5]
	v_pk_fma_f32 v[22:23], v[2:3], v[10:11], v[6:7]
	flat_store_dwordx4 v[86:87], v[20:23]
	v_mov_b64_e32 v[0:1], v[162:163]
	v_mov_b64_e32 v[2:3], v[164:165]
	v_mov_b64_e32 v[4:5], v[166:167]
	v_mov_b64_e32 v[6:7], v[168:169]
	v_pk_mul_f32 v[8:9], v[14:15], v[122:123] op_sel_hi:[1,0]
	v_pk_mul_f32 v[10:11], v[12:13], v[122:123] op_sel_hi:[1,0]
	v_pk_fma_f32 v[14:15], v[2:3], v[8:9], v[6:7]
	v_pk_fma_f32 v[12:13], v[0:1], v[10:11], v[4:5]
	flat_store_dwordx4 v[86:87], v[12:15] offset:1024
	v_mov_b64_e32 v[0:1], v[170:171]
	v_mov_b64_e32 v[2:3], v[172:173]
	v_mov_b64_e32 v[4:5], v[174:175]
	v_mov_b64_e32 v[6:7], v[176:177]
	v_pk_mul_f32 v[8:9], v[18:19], v[122:123] op_sel_hi:[1,0]
	v_pk_mul_f32 v[10:11], v[16:17], v[122:123] op_sel_hi:[1,0]
	v_pk_mul_f32 v[18:19], v[24:25], v[122:123] op_sel_hi:[1,0]
	v_pk_mul_f32 v[16:17], v[26:27], v[122:123] op_sel_hi:[1,0]
	v_pk_fma_f32 v[4:5], v[0:1], v[10:11], v[4:5]
	v_pk_fma_f32 v[6:7], v[2:3], v[8:9], v[6:7]
	flat_store_dwordx4 v[86:87], v[4:7] offset:2048
	v_mov_b64_e32 v[0:1], v[178:179]
	v_mov_b64_e32 v[2:3], v[180:181]
	v_mov_b64_e32 v[8:9], v[182:183]
	v_mov_b64_e32 v[10:11], v[184:185]
	v_pk_fma_f32 v[0:1], v[0:1], v[18:19], v[8:9]
	v_mul_f32_e32 v8, 0x4b800000, v126
	v_cndmask_b32_e32 v8, v126, v8, vcc
	v_rsq_f32_e32 v8, v8
	v_pk_fma_f32 v[2:3], v[2:3], v[16:17], v[10:11]
	flat_store_dwordx4 v[86:87], v[0:3] offset:3072
	v_mul_f32_e32 v9, 0x45800000, v8
	v_cndmask_b32_e32 v122, v8, v9, vcc
	v_mov_b64_e32 v[8:9], v[154:155]
	v_mov_b64_e32 v[10:11], v[156:157]
	v_mov_b64_e32 v[16:17], v[158:159]
	v_mov_b64_e32 v[18:19], v[160:161]
	v_pk_mul_f32 v[24:25], v[30:31], v[122:123] op_sel_hi:[1,0]
	v_pk_mul_f32 v[26:27], v[28:29], v[122:123] op_sel_hi:[1,0]
	v_pk_mul_f32 v[30:31], v[60:61], v[122:123] op_sel_hi:[1,0]
	v_pk_mul_f32 v[28:29], v[38:39], v[122:123] op_sel_hi:[1,0]
	v_pk_mul_f32 v[36:37], v[36:37], v[122:123] op_sel_hi:[1,0]
	v_pk_mul_f32 v[34:35], v[34:35], v[122:123] op_sel_hi:[1,0]
	v_pk_mul_f32 v[38:39], v[118:119], v[122:123] op_sel_hi:[1,0]
	v_pk_mul_f32 v[60:61], v[62:63], v[122:123] op_sel_hi:[1,0]
	ds_bpermute_b32 v62, v67, v65
	s_waitcnt lgkmcnt(0)
	v_add_f32_e32 v62, v65, v62
	ds_bpermute_b32 v63, v69, v62
	s_waitcnt lgkmcnt(0)
	v_add_f32_e32 v62, v62, v63
	ds_bpermute_b32 v63, v71, v62
	s_waitcnt lgkmcnt(0)
	v_add_f32_e32 v62, v62, v63
	ds_bpermute_b32 v63, v73, v62
	s_waitcnt lgkmcnt(0)
	v_add_f32_e32 v62, v62, v63
	ds_bpermute_b32 v63, v123, v62
	s_waitcnt lgkmcnt(0)
	v_add_f32_e32 v62, v62, v63
	ds_bpermute_b32 v63, v124, v62
	s_waitcnt lgkmcnt(0)
	v_add_f32_e32 v65, v62, v63
	v_fmamk_f32 v45, v65, 0xba800000, v45
	v_fmac_f32_e32 v44, 0xba800000, v65
	v_fmamk_f32 v115, v65, 0xba800000, v115
	v_fmac_f32_e32 v114, 0xba800000, v65
	v_pk_mul_f32 v[62:63], v[114:115], v[114:115]
	v_pk_mul_f32 v[118:119], v[44:45], v[44:45]
	v_fmamk_f32 v43, v65, 0xba800000, v43
	v_pk_mov_b32 v[126:127], v[118:119], v[62:63] op_sel:[1,0]
	v_mov_b32_e32 v119, v63
	v_pk_add_f32 v[62:63], v[126:127], v[118:119]
	v_fmac_f32_e32 v42, 0xba800000, v65
	v_fmamk_f32 v113, v65, 0xba800000, v113
	v_fmac_f32_e32 v112, 0xba800000, v65
	v_pk_add_f32 v[62:63], v[62:63], v[62:63] op_sel_hi:[0,1]
	v_pk_mul_f32 v[118:119], v[112:113], v[112:113]
	v_pk_mul_f32 v[126:127], v[42:43], v[42:43]
	v_fmac_f32_e32 v108, 0xba800000, v65
	v_pk_mov_b32 v[128:129], v[126:127], v[118:119] op_sel:[1,0]
	v_mov_b32_e32 v127, v119
	v_fmamk_f32 v109, v65, 0xba800000, v109
	v_fmac_f32_e32 v110, 0xba800000, v65
	v_mul_f32_e32 v62, v108, v108
	v_pk_add_f32 v[118:119], v[128:129], v[126:127]
	v_fmamk_f32 v111, v65, 0xba800000, v111
	v_pk_fma_f32 v[126:127], v[108:109], v[108:109], v[62:63] op_sel_hi:[1,1,0]
	v_mul_f32_e32 v62, v110, v110
	v_pk_add_f32 v[118:119], v[118:119], v[118:119] op_sel_hi:[0,1]
	v_pk_fma_f32 v[128:129], v[110:111], v[110:111], v[62:63] op_sel_hi:[1,1,0]
	v_fmamk_f32 v107, v65, 0xba800000, v107
	v_fmac_f32_e32 v106, 0xba800000, v65
	v_fmamk_f32 v105, v65, 0xba800000, v105
	v_fmac_f32_e32 v104, 0xba800000, v65
	v_mul_f32_e32 v126, v104, v104
	v_mul_f32_e32 v128, v105, v105
	v_mul_f32_e32 v62, v106, v106
	v_pk_fma_f32 v[8:9], v[8:9], v[26:27], v[16:17]
	v_pk_fma_f32 v[10:11], v[10:11], v[24:25], v[18:19]
	flat_store_dwordx4 v[32:33], v[8:11]
	v_mov_b64_e32 v[16:17], v[162:163]
	v_mov_b64_e32 v[18:19], v[164:165]
	v_mov_b64_e32 v[24:25], v[166:167]
	v_mov_b64_e32 v[26:27], v[168:169]
	v_mul_f32_e32 v118, v107, v107
	v_pk_add_f32 v[126:127], v[126:127], v[128:129]
	v_pk_add_f32 v[62:63], v[62:63], v[118:119]
	v_pk_fma_f32 v[28:29], v[16:17], v[28:29], v[24:25]
	v_pk_fma_f32 v[30:31], v[18:19], v[30:31], v[26:27]
	flat_store_dwordx4 v[32:33], v[28:31] offset:1024
	v_mov_b64_e32 v[16:17], v[170:171]
	v_mov_b64_e32 v[18:19], v[172:173]
	v_mov_b64_e32 v[24:25], v[174:175]
	v_mov_b64_e32 v[26:27], v[176:177]
	v_pk_add_f32 v[62:63], v[126:127], v[62:63]
	v_pk_fma_f32 v[24:25], v[16:17], v[34:35], v[24:25]
	v_pk_fma_f32 v[26:27], v[18:19], v[36:37], v[26:27]
	flat_store_dwordx4 v[32:33], v[24:27] offset:2048
	v_mov_b64_e32 v[16:17], v[178:179]
	v_mov_b64_e32 v[18:19], v[180:181]
	v_mov_b64_e32 v[34:35], v[182:183]
	v_mov_b64_e32 v[36:37], v[184:185]
	v_mov_b32_e32 v118, v62
	v_pk_fma_f32 v[16:17], v[16:17], v[60:61], v[34:35]
	v_pk_fma_f32 v[18:19], v[18:19], v[38:39], v[36:37]
	flat_store_dwordx4 v[32:33], v[16:19] offset:3072
	ds_bpermute_b32 v32, v67, v125
	s_waitcnt lgkmcnt(0)
	v_add_f32_e32 v32, v125, v32
	ds_bpermute_b32 v33, v69, v32
	s_waitcnt lgkmcnt(0)
	v_add_f32_e32 v32, v32, v33
	ds_bpermute_b32 v33, v71, v32
	s_waitcnt lgkmcnt(0)
	v_add_f32_e32 v32, v32, v33
	ds_bpermute_b32 v33, v73, v32
	s_waitcnt lgkmcnt(0)
	v_add_f32_e32 v32, v32, v33
	ds_bpermute_b32 v33, v123, v32
	s_waitcnt lgkmcnt(0)
	v_add_f32_e32 v32, v32, v33
	ds_bpermute_b32 v33, v124, v32
	s_waitcnt lgkmcnt(0)
	v_add_f32_e32 v60, v32, v33
	v_fmamk_f32 v51, v60, 0xba800000, v51
	v_fmac_f32_e32 v50, 0xba800000, v60
	v_fmamk_f32 v53, v60, 0xba800000, v53
	v_fmac_f32_e32 v52, 0xba800000, v60
	v_pk_mul_f32 v[32:33], v[52:53], v[52:53]
	v_pk_mul_f32 v[34:35], v[50:51], v[50:51]
	v_fmamk_f32 v57, v60, 0xba800000, v57
	v_pk_mov_b32 v[36:37], v[34:35], v[32:33] op_sel:[1,0]
	v_mov_b32_e32 v35, v33
	v_pk_add_f32 v[32:33], v[36:37], v[34:35]
	v_fmac_f32_e32 v56, 0xba800000, v60
	v_fmamk_f32 v59, v60, 0xba800000, v59
	v_fmac_f32_e32 v58, 0xba800000, v60
	v_pk_add_f32 v[32:33], v[32:33], v[32:33] op_sel_hi:[0,1]
	v_pk_mul_f32 v[34:35], v[58:59], v[58:59]
	v_pk_mul_f32 v[36:37], v[56:57], v[56:57]
	v_fmac_f32_e32 v54, 0xba800000, v60
	v_pk_mov_b32 v[38:39], v[36:37], v[34:35] op_sel:[1,0]
	v_mov_b32_e32 v37, v35
	v_fmamk_f32 v55, v60, 0xba800000, v55
	v_fmac_f32_e32 v116, 0xba800000, v60
	v_mul_f32_e32 v32, v54, v54
	v_pk_add_f32 v[34:35], v[38:39], v[36:37]
	v_fmamk_f32 v117, v60, 0xba800000, v117
	v_pk_fma_f32 v[36:37], v[54:55], v[54:55], v[32:33] op_sel_hi:[1,1,0]
	v_mul_f32_e32 v32, v116, v116
	v_pk_add_f32 v[34:35], v[34:35], v[34:35] op_sel_hi:[0,1]
	v_pk_fma_f32 v[38:39], v[116:117], v[116:117], v[32:33] op_sel_hi:[1,1,0]
	v_fmamk_f32 v49, v60, 0xba800000, v49
	v_fmac_f32_e32 v48, 0xba800000, v60
	v_fmamk_f32 v47, v60, 0xba800000, v47
	v_fmac_f32_e32 v46, 0xba800000, v60
	v_mul_f32_e32 v36, v46, v46
	v_mul_f32_e32 v38, v47, v47
	v_mul_f32_e32 v32, v48, v48
	v_mul_f32_e32 v34, v49, v49
	v_pk_add_f32 v[36:37], v[36:37], v[38:39]
	v_pk_add_f32 v[32:33], v[32:33], v[34:35]
	s_nop 0
	v_pk_add_f32 v[60:61], v[36:37], v[32:33]
	v_mov_b64_e32 v[32:33], v[154:155]
	v_mov_b64_e32 v[34:35], v[156:157]
	v_mov_b64_e32 v[36:37], v[158:159]
	v_mov_b64_e32 v[38:39], v[160:161]
	v_mov_b32_e32 v119, v60
	v_mov_b32_e32 v60, v63
	v_pk_add_f32 v[60:61], v[118:119], v[60:61]
	ds_bpermute_b32 v63, v67, v61
	ds_bpermute_b32 v62, v67, v60
	s_waitcnt lgkmcnt(0)
	v_pk_add_f32 v[60:61], v[60:61], v[62:63]
	ds_bpermute_b32 v63, v69, v61
	ds_bpermute_b32 v62, v69, v60
	s_waitcnt lgkmcnt(0)
	v_pk_add_f32 v[60:61], v[60:61], v[62:63]
	ds_bpermute_b32 v63, v71, v61
	ds_bpermute_b32 v62, v71, v60
	s_waitcnt lgkmcnt(0)
	v_pk_add_f32 v[60:61], v[60:61], v[62:63]
	ds_bpermute_b32 v63, v73, v61
	ds_bpermute_b32 v62, v73, v60
	s_waitcnt lgkmcnt(0)
	v_pk_add_f32 v[60:61], v[60:61], v[62:63]
	ds_bpermute_b32 v63, v123, v61
	ds_bpermute_b32 v62, v123, v60
	s_waitcnt lgkmcnt(0)
	v_pk_add_f32 v[60:61], v[60:61], v[62:63]
	ds_bpermute_b32 v63, v124, v61
	ds_bpermute_b32 v62, v124, v60
	s_waitcnt lgkmcnt(0)
	v_pk_add_f32 v[60:61], v[60:61], v[62:63]
	s_nop 0
	v_pk_fma_f32 v[118:119], v[60:61], s[2:3], v[120:121] op_sel_hi:[1,0,0]
	s_nop 0
	v_mul_f32_e32 v60, 0x4b800000, v119
	v_cmp_gt_f32_e64 s[8:9], s68, v119
	v_cmp_gt_f32_e32 vcc, s68, v118
	s_nop 0
	v_cndmask_b32_e64 v60, v119, v60, s[8:9]
	v_rsq_f32_e32 v60, v60
	s_nop 0
	v_mul_f32_e32 v61, 0x45800000, v60
	v_cndmask_b32_e64 v120, v60, v61, s[8:9]
	v_pk_mul_f32 v[52:53], v[52:53], v[120:121] op_sel_hi:[1,0]
	v_pk_mul_f32 v[50:51], v[50:51], v[120:121] op_sel_hi:[1,0]
	v_pk_mul_f32 v[46:47], v[46:47], v[120:121] op_sel_hi:[1,0]
	v_pk_fma_f32 v[60:61], v[32:33], v[50:51], v[36:37]
	v_pk_fma_f32 v[62:63], v[34:35], v[52:53], v[38:39]
	flat_store_dwordx4 v[40:41], v[60:63]
	v_mov_b64_e32 v[32:33], v[162:163]
	v_mov_b64_e32 v[34:35], v[164:165]
	v_mov_b64_e32 v[36:37], v[166:167]
	v_mov_b64_e32 v[38:39], v[168:169]
	v_pk_mul_f32 v[50:51], v[58:59], v[120:121] op_sel_hi:[1,0]
	v_pk_mul_f32 v[52:53], v[56:57], v[120:121] op_sel_hi:[1,0]
	v_pk_fma_f32 v[58:59], v[34:35], v[50:51], v[38:39]
	v_pk_fma_f32 v[56:57], v[32:33], v[52:53], v[36:37]
	flat_store_dwordx4 v[40:41], v[56:59] offset:1024
	v_mov_b64_e32 v[32:33], v[170:171]
	v_mov_b64_e32 v[34:35], v[172:173]
	v_mov_b64_e32 v[36:37], v[174:175]
	v_mov_b64_e32 v[38:39], v[176:177]
	v_pk_mul_f32 v[50:51], v[116:117], v[120:121] op_sel_hi:[1,0]
	v_pk_mul_f32 v[52:53], v[54:55], v[120:121] op_sel_hi:[1,0]
	v_pk_fma_f32 v[54:55], v[34:35], v[50:51], v[38:39]
	v_pk_fma_f32 v[52:53], v[32:33], v[52:53], v[36:37]
	flat_store_dwordx4 v[40:41], v[52:55] offset:2048
	v_mov_b64_e32 v[32:33], v[178:179]
	v_mov_b64_e32 v[34:35], v[180:181]
	v_mov_b64_e32 v[36:37], v[182:183]
	v_mov_b64_e32 v[38:39], v[184:185]
	v_pk_mul_f32 v[50:51], v[48:49], v[120:121] op_sel_hi:[1,0]
	v_pk_fma_f32 v[48:49], v[32:33], v[46:47], v[36:37]
	v_mul_f32_e32 v32, 0x4b800000, v118
	v_cndmask_b32_e32 v32, v118, v32, vcc
	v_rsq_f32_e32 v32, v32
	v_pk_fma_f32 v[50:51], v[34:35], v[50:51], v[38:39]
	flat_store_dwordx4 v[40:41], v[48:51] offset:3072
	v_mul_f32_e32 v33, 0x45800000, v32
	v_cndmask_b32_e32 v116, v32, v33, vcc
	v_mov_b64_e32 v[32:33], v[154:155]
	v_mov_b64_e32 v[34:35], v[156:157]
	v_mov_b64_e32 v[36:37], v[158:159]
	v_mov_b64_e32 v[38:39], v[160:161]
	v_pk_mul_f32 v[40:41], v[114:115], v[116:117] op_sel_hi:[1,0]
	v_pk_mul_f32 v[44:45], v[44:45], v[116:117] op_sel_hi:[1,0]
	v_pk_mul_f32 v[112:113], v[112:113], v[116:117] op_sel_hi:[1,0]
	v_pk_mul_f32 v[110:111], v[110:111], v[116:117] op_sel_hi:[1,0]
	v_pk_mul_f32 v[108:109], v[108:109], v[116:117] op_sel_hi:[1,0]
	s_andn2_b64 vcc, exec, s[4:5]
	v_pk_fma_f32 v[44:45], v[32:33], v[44:45], v[36:37]
	v_pk_fma_f32 v[46:47], v[34:35], v[40:41], v[38:39]
	flat_store_dwordx4 v[102:103], v[44:47]
	v_mov_b64_e32 v[32:33], v[162:163]
	v_mov_b64_e32 v[34:35], v[164:165]
	v_mov_b64_e32 v[36:37], v[166:167]
	v_mov_b64_e32 v[38:39], v[168:169]
	v_pk_mul_f32 v[40:41], v[42:43], v[116:117] op_sel_hi:[1,0]
	v_pk_fma_f32 v[42:43], v[34:35], v[112:113], v[38:39]
	v_pk_fma_f32 v[40:41], v[32:33], v[40:41], v[36:37]
	flat_store_dwordx4 v[102:103], v[40:43] offset:1024
	v_mov_b64_e32 v[32:33], v[170:171]
	v_mov_b64_e32 v[34:35], v[172:173]
	v_mov_b64_e32 v[36:37], v[174:175]
	v_mov_b64_e32 v[38:39], v[176:177]
	v_pk_fma_f32 v[36:37], v[32:33], v[108:109], v[36:37]
	v_pk_fma_f32 v[38:39], v[34:35], v[110:111], v[38:39]
	flat_store_dwordx4 v[102:103], v[36:39] offset:2048
	v_pk_mul_f32 v[108:109], v[106:107], v[116:117] op_sel_hi:[1,0]
	v_pk_mul_f32 v[110:111], v[104:105], v[116:117] op_sel_hi:[1,0]
	v_mov_b64_e32 v[32:33], v[178:179]
	v_mov_b64_e32 v[34:35], v[180:181]
	v_mov_b64_e32 v[104:105], v[182:183]
	v_mov_b64_e32 v[106:107], v[184:185]
	v_pk_fma_f32 v[32:33], v[32:33], v[110:111], v[104:105]
	v_pk_fma_f32 v[34:35], v[34:35], v[108:109], v[106:107]
	flat_store_dwordx4 v[102:103], v[32:35] offset:3072
	s_cbranch_vccnz .LBB0_50
	v_mad_u64_u32 v[104:105], s[4:5], v88, s7, 0
	v_mad_u64_u32 v[102:103], s[4:5], v92, s7, 0
	v_mad_i32_i24 v105, v89, s7, v105
	v_mad_i32_i24 v103, v93, s7, v103
	v_mad_u64_u32 v[92:93], s[4:5], v98, s7, 0
	v_mad_u64_u32 v[88:89], s[4:5], v100, s7, 0
	v_mad_i32_i24 v93, v99, s7, v93
	v_lshl_add_u64 v[98:99], s[60:61], 0, v[104:105]
	s_mov_b64 s[4:5], 0x6000
	s_mov_b64 s[8:9], 0x7000
	v_mad_i32_i24 v89, v101, s7, v89
	v_lshl_add_u64 v[100:101], v[98:99], 0, s[4:5]
	v_lshl_add_u64 v[98:99], v[98:99], 0, s[8:9]
	v_lshlrev_b32_e32 v152, 2, v66
	v_lshl_add_u64 v[104:105], v[100:101], 0, v[152:153]
	v_lshl_add_u64 v[108:109], v[98:99], 0, v[152:153]
	flat_load_dwordx4 v[104:107], v[104:105]
	s_nop 0
	flat_load_dwordx4 v[108:111], v[108:109]
	s_waitcnt vmcnt(0) lgkmcnt(0)
	v_pk_add_f32 v[110:111], v[110:111], 1.0 op_sel_hi:[1,0]
	v_pk_add_f32 v[108:109], v[108:109], 1.0 op_sel_hi:[1,0]
	v_pk_fma_f32 v[22:23], v[22:23], v[110:111], v[106:107]
	v_pk_fma_f32 v[20:21], v[20:21], v[108:109], v[104:105]
	s_nop 0
	v_cvt_pk_bf16_f32 v20, v20, v21
	v_cvt_pk_bf16_f32 v21, v22, v23
	flat_store_dwordx2 v[84:85], v[20:21]
	v_lshlrev_b32_e32 v20, 2, v68
	v_mov_b32_e32 v21, v153
	v_lshl_add_u64 v[22:23], v[100:101], 0, v[20:21]
	flat_load_dwordx4 v[104:107], v[22:23]
	v_lshl_add_u64 v[22:23], v[98:99], 0, v[20:21]
	flat_load_dwordx4 v[108:111], v[22:23]
	s_waitcnt vmcnt(0) lgkmcnt(0)
	v_pk_add_f32 v[22:23], v[110:111], 1.0 op_sel_hi:[1,0]
	v_pk_add_f32 v[108:109], v[108:109], 1.0 op_sel_hi:[1,0]
	v_pk_fma_f32 v[14:15], v[14:15], v[22:23], v[106:107]
	v_pk_fma_f32 v[12:13], v[12:13], v[108:109], v[104:105]
	s_nop 0
	v_cvt_pk_bf16_f32 v12, v12, v13
	v_cvt_pk_bf16_f32 v13, v14, v15
	flat_store_dwordx2 v[84:85], v[12:13] offset:512
	v_lshlrev_b32_e32 v12, 2, v70
	v_mov_b32_e32 v13, v153
	v_lshl_add_u64 v[14:15], v[100:101], 0, v[12:13]
	flat_load_dwordx4 v[104:107], v[14:15]
	v_lshl_add_u64 v[14:15], v[98:99], 0, v[12:13]
	flat_load_dwordx4 v[108:111], v[14:15]
	s_waitcnt vmcnt(0) lgkmcnt(0)
	v_pk_add_f32 v[14:15], v[110:111], 1.0 op_sel_hi:[1,0]
	v_pk_add_f32 v[22:23], v[108:109], 1.0 op_sel_hi:[1,0]
	v_pk_fma_f32 v[6:7], v[6:7], v[14:15], v[106:107]
	v_pk_fma_f32 v[4:5], v[4:5], v[22:23], v[104:105]
	s_nop 0
	v_cvt_pk_bf16_f32 v4, v4, v5
	v_cvt_pk_bf16_f32 v5, v6, v7
	flat_store_dwordx2 v[84:85], v[4:5] offset:1024
	v_lshlrev_b32_e32 v4, 2, v72
	v_mov_b32_e32 v5, v153
	v_lshl_add_u64 v[6:7], v[100:101], 0, v[4:5]
	flat_load_dwordx4 v[104:107], v[6:7]
	v_lshl_add_u64 v[6:7], v[98:99], 0, v[4:5]
	flat_load_dwordx4 v[98:101], v[6:7]
	s_waitcnt vmcnt(0) lgkmcnt(0)
	v_pk_add_f32 v[6:7], v[100:101], 1.0 op_sel_hi:[1,0]
	v_pk_add_f32 v[14:15], v[98:99], 1.0 op_sel_hi:[1,0]
	v_pk_fma_f32 v[2:3], v[2:3], v[6:7], v[106:107]
	v_pk_fma_f32 v[0:1], v[0:1], v[14:15], v[104:105]
	s_nop 0
	v_cvt_pk_bf16_f32 v0, v0, v1
	v_cvt_pk_bf16_f32 v1, v2, v3
	flat_store_dwordx2 v[84:85], v[0:1] offset:1536
	v_lshl_add_u64 v[0:1], s[60:61], 0, v[102:103]
	v_lshl_add_u64 v[2:3], v[0:1], 0, s[4:5]
	v_lshl_add_u64 v[0:1], v[0:1], 0, s[8:9]
	v_lshl_add_u64 v[6:7], v[2:3], 0, v[152:153]
	flat_load_dwordx4 v[98:101], v[6:7]
	v_lshl_add_u64 v[6:7], v[0:1], 0, v[152:153]
	flat_load_dwordx4 v[102:105], v[6:7]
	s_waitcnt vmcnt(0) lgkmcnt(0)
	v_pk_add_f32 v[6:7], v[104:105], 1.0 op_sel_hi:[1,0]
	v_pk_add_f32 v[14:15], v[102:103], 1.0 op_sel_hi:[1,0]
	v_pk_fma_f32 v[6:7], v[10:11], v[6:7], v[100:101]
	v_pk_fma_f32 v[8:9], v[8:9], v[14:15], v[98:99]
	v_lshl_add_u64 v[10:11], v[82:83], 0, v[90:91]
	v_cvt_pk_bf16_f32 v8, v8, v9
	v_cvt_pk_bf16_f32 v9, v6, v7
	flat_store_dwordx2 v[10:11], v[8:9]
	v_lshl_add_u64 v[6:7], v[2:3], 0, v[20:21]
	v_lshl_add_u64 v[14:15], v[0:1], 0, v[20:21]
	flat_load_dwordx4 v[6:9], v[6:7]
	s_nop 0
	flat_load_dwordx4 v[98:101], v[14:15]
	s_waitcnt vmcnt(0) lgkmcnt(0)
	v_pk_add_f32 v[14:15], v[100:101], 1.0 op_sel_hi:[1,0]
	v_pk_add_f32 v[22:23], v[98:99], 1.0 op_sel_hi:[1,0]
	v_pk_fma_f32 v[8:9], v[30:31], v[14:15], v[8:9]
	v_pk_fma_f32 v[6:7], v[28:29], v[22:23], v[6:7]
	v_lshl_add_u64 v[14:15], v[0:1], 0, v[12:13]
	v_cvt_pk_bf16_f32 v6, v6, v7
	v_cvt_pk_bf16_f32 v7, v8, v9
	flat_store_dwordx2 v[10:11], v[6:7] offset:512
	v_lshl_add_u64 v[6:7], v[2:3], 0, v[12:13]
	flat_load_dwordx4 v[6:9], v[6:7]
	v_lshl_add_u64 v[2:3], v[2:3], 0, v[4:5]
	flat_load_dwordx4 v[28:31], v[14:15]
	v_lshl_add_u64 v[0:1], v[0:1], 0, v[4:5]
	s_waitcnt vmcnt(0) lgkmcnt(0)
	v_pk_add_f32 v[14:15], v[30:31], 1.0 op_sel_hi:[1,0]
	v_pk_add_f32 v[22:23], v[28:29], 1.0 op_sel_hi:[1,0]
	v_pk_fma_f32 v[8:9], v[26:27], v[14:15], v[8:9]
	v_pk_fma_f32 v[6:7], v[24:25], v[22:23], v[6:7]
	s_nop 0
	v_cvt_pk_bf16_f32 v6, v6, v7
	v_cvt_pk_bf16_f32 v7, v8, v9
	flat_store_dwordx2 v[10:11], v[6:7] offset:1024
	flat_load_dwordx4 v[6:9], v[2:3]
	s_nop 0
	flat_load_dwordx4 v[0:3], v[0:1]
	s_waitcnt vmcnt(0) lgkmcnt(0)
	v_pk_add_f32 v[2:3], v[2:3], 1.0 op_sel_hi:[1,0]
	v_pk_add_f32 v[0:1], v[0:1], 1.0 op_sel_hi:[1,0]
	v_pk_fma_f32 v[2:3], v[18:19], v[2:3], v[8:9]
	v_pk_fma_f32 v[0:1], v[16:17], v[0:1], v[6:7]
	v_lshl_add_u64 v[18:19], v[82:83], 0, v[94:95]
	v_cvt_pk_bf16_f32 v0, v0, v1
	v_cvt_pk_bf16_f32 v1, v2, v3
	flat_store_dwordx2 v[10:11], v[0:1] offset:1536
	v_lshl_add_u64 v[0:1], s[60:61], 0, v[92:93]
	v_lshl_add_u64 v[2:3], v[0:1], 0, s[4:5]
	v_lshl_add_u64 v[0:1], v[0:1], 0, s[8:9]
	v_lshl_add_u64 v[6:7], v[2:3], 0, v[152:153]
	v_lshl_add_u64 v[10:11], v[0:1], 0, v[152:153]
	flat_load_dwordx4 v[6:9], v[6:7]
	s_nop 0
	flat_load_dwordx4 v[14:17], v[10:11]
	s_waitcnt vmcnt(0) lgkmcnt(0)
	v_pk_add_f32 v[10:11], v[16:17], 1.0 op_sel_hi:[1,0]
	v_pk_add_f32 v[14:15], v[14:15], 1.0 op_sel_hi:[1,0]
	v_pk_fma_f32 v[8:9], v[62:63], v[10:11], v[8:9]
	v_pk_fma_f32 v[6:7], v[60:61], v[14:15], v[6:7]
	v_lshl_add_u64 v[10:11], v[82:83], 0, v[96:97]
	v_cvt_pk_bf16_f32 v6, v6, v7
	v_cvt_pk_bf16_f32 v7, v8, v9
	flat_store_dwordx2 v[10:11], v[6:7]
	v_lshl_add_u64 v[6:7], v[2:3], 0, v[20:21]
	v_lshl_add_u64 v[14:15], v[0:1], 0, v[20:21]
	flat_load_dwordx4 v[6:9], v[6:7]
	s_nop 0
	flat_load_dwordx4 v[14:17], v[14:15]
	s_waitcnt vmcnt(0) lgkmcnt(0)
	v_pk_add_f32 v[16:17], v[16:17], 1.0 op_sel_hi:[1,0]
	v_pk_add_f32 v[14:15], v[14:15], 1.0 op_sel_hi:[1,0]
	v_pk_fma_f32 v[8:9], v[58:59], v[16:17], v[8:9]
	v_pk_fma_f32 v[6:7], v[56:57], v[14:15], v[6:7]
	v_lshl_add_u64 v[14:15], v[0:1], 0, v[12:13]
	v_cvt_pk_bf16_f32 v6, v6, v7
	v_cvt_pk_bf16_f32 v7, v8, v9
	flat_store_dwordx2 v[10:11], v[6:7] offset:512
	v_lshl_add_u64 v[6:7], v[2:3], 0, v[12:13]
	flat_load_dwordx4 v[6:9], v[6:7]
	v_lshl_add_u64 v[2:3], v[2:3], 0, v[4:5]
	flat_load_dwordx4 v[14:17], v[14:15]
	v_lshl_add_u64 v[0:1], v[0:1], 0, v[4:5]
	s_waitcnt vmcnt(0) lgkmcnt(0)
	v_pk_add_f32 v[16:17], v[16:17], 1.0 op_sel_hi:[1,0]
	v_pk_add_f32 v[14:15], v[14:15], 1.0 op_sel_hi:[1,0]
	v_pk_fma_f32 v[8:9], v[54:55], v[16:17], v[8:9]
	v_pk_fma_f32 v[6:7], v[52:53], v[14:15], v[6:7]
	s_nop 0
	v_cvt_pk_bf16_f32 v6, v6, v7
	v_cvt_pk_bf16_f32 v7, v8, v9
	flat_store_dwordx2 v[10:11], v[6:7] offset:1024
	flat_load_dwordx4 v[6:9], v[2:3]
	s_nop 0
	flat_load_dwordx4 v[0:3], v[0:1]
	s_waitcnt vmcnt(0) lgkmcnt(0)
	v_pk_add_f32 v[2:3], v[2:3], 1.0 op_sel_hi:[1,0]
	v_pk_add_f32 v[0:1], v[0:1], 1.0 op_sel_hi:[1,0]
	v_pk_fma_f32 v[2:3], v[50:51], v[2:3], v[8:9]
	v_pk_fma_f32 v[0:1], v[48:49], v[0:1], v[6:7]
	s_nop 0
	v_cvt_pk_bf16_f32 v0, v0, v1
	v_cvt_pk_bf16_f32 v1, v2, v3
	flat_store_dwordx2 v[10:11], v[0:1] offset:1536
	v_lshl_add_u64 v[0:1], s[60:61], 0, v[88:89]
	v_lshl_add_u64 v[2:3], v[0:1], 0, s[4:5]
	v_lshl_add_u64 v[0:1], v[0:1], 0, s[8:9]
	v_lshl_add_u64 v[6:7], v[2:3], 0, v[152:153]
	v_lshl_add_u64 v[10:11], v[0:1], 0, v[152:153]
	flat_load_dwordx4 v[6:9], v[6:7]
	s_nop 0
	flat_load_dwordx4 v[14:17], v[10:11]
	s_waitcnt vmcnt(0) lgkmcnt(0)
	v_pk_add_f32 v[10:11], v[16:17], 1.0 op_sel_hi:[1,0]
	v_pk_add_f32 v[14:15], v[14:15], 1.0 op_sel_hi:[1,0]
	v_pk_fma_f32 v[8:9], v[46:47], v[10:11], v[8:9]
	v_pk_fma_f32 v[6:7], v[44:45], v[14:15], v[6:7]
	v_lshl_add_u64 v[10:11], v[0:1], 0, v[20:21]
	v_cvt_pk_bf16_f32 v6, v6, v7
	v_cvt_pk_bf16_f32 v7, v8, v9
	flat_store_dwordx2 v[18:19], v[6:7]
	v_lshl_add_u64 v[6:7], v[2:3], 0, v[20:21]
	flat_load_dwordx4 v[6:9], v[6:7]
	s_nop 0
	flat_load_dwordx4 v[14:17], v[10:11]
	s_waitcnt vmcnt(0) lgkmcnt(0)
	v_pk_add_f32 v[10:11], v[16:17], 1.0 op_sel_hi:[1,0]
	v_pk_add_f32 v[14:15], v[14:15], 1.0 op_sel_hi:[1,0]
	v_pk_fma_f32 v[8:9], v[42:43], v[10:11], v[8:9]
	v_pk_fma_f32 v[6:7], v[40:41], v[14:15], v[6:7]
	v_lshl_add_u64 v[10:11], v[0:1], 0, v[12:13]
	v_cvt_pk_bf16_f32 v6, v6, v7
	v_cvt_pk_bf16_f32 v7, v8, v9
	flat_store_dwordx2 v[18:19], v[6:7] offset:512
	v_lshl_add_u64 v[6:7], v[2:3], 0, v[12:13]
	flat_load_dwordx4 v[6:9], v[6:7]
	v_lshl_add_u64 v[2:3], v[2:3], 0, v[4:5]
	flat_load_dwordx4 v[10:13], v[10:11]
	v_lshl_add_u64 v[0:1], v[0:1], 0, v[4:5]
	s_waitcnt vmcnt(0) lgkmcnt(0)
	v_pk_add_f32 v[12:13], v[12:13], 1.0 op_sel_hi:[1,0]
	v_pk_add_f32 v[10:11], v[10:11], 1.0 op_sel_hi:[1,0]
	v_pk_fma_f32 v[8:9], v[38:39], v[12:13], v[8:9]
	v_pk_fma_f32 v[6:7], v[36:37], v[10:11], v[6:7]
	s_nop 0
	v_cvt_pk_bf16_f32 v6, v6, v7
	v_cvt_pk_bf16_f32 v7, v8, v9
	flat_store_dwordx2 v[18:19], v[6:7] offset:1024
	flat_load_dwordx4 v[6:9], v[2:3]
	s_nop 0
	flat_load_dwordx4 v[0:3], v[0:1]
	s_waitcnt vmcnt(0) lgkmcnt(0)
	v_pk_add_f32 v[2:3], v[2:3], 1.0 op_sel_hi:[1,0]
	v_pk_add_f32 v[0:1], v[0:1], 1.0 op_sel_hi:[1,0]
	v_pk_fma_f32 v[2:3], v[34:35], v[2:3], v[8:9]
	v_pk_fma_f32 v[0:1], v[32:33], v[0:1], v[6:7]
	s_nop 0
	v_cvt_pk_bf16_f32 v0, v0, v1
	v_cvt_pk_bf16_f32 v1, v2, v3
	flat_store_dwordx2 v[18:19], v[0:1] offset:1536
	s_branch .LBB0_50

.LBB0_180:
	v_and_b32_e32 v210, 63, v206
	v_lshlrev_b32_e32 v210, 4, v210
	v_and_b32_e32 v211, 0x1c0, v206
	v_lshl_add_u32 v210, v211, 7, v210
	global_load_dwordx4 v[214:217], v[106:107], off
	global_load_dwordx4 v[218:221], v[108:109], off
	global_load_dwordx4 v[236:239], v[106:107], off offset:1024
	global_load_dwordx4 v[240:243], v[108:109], off offset:1024
	s_waitcnt vmcnt(0)
	ds_write_b128 v210, v[214:217]
	ds_write_b128 v210, v[218:221] offset:4096
	ds_write_b128 v210, v[236:239] offset:1024
	ds_write_b128 v210, v[240:243] offset:5120
	s_waitcnt lgkmcnt(0)
	global_load_dwordx4 v[214:217], v[106:107], off offset:2048
	global_load_dwordx4 v[218:221], v[108:109], off offset:2048
	global_load_dwordx4 v[236:239], v[106:107], off offset:3072
	global_load_dwordx4 v[240:243], v[108:109], off offset:3072
	s_waitcnt vmcnt(0)
	ds_write_b128 v210, v[214:217] offset:2048
	ds_write_b128 v210, v[218:221] offset:6144
	ds_write_b128 v210, v[236:239] offset:3072
	ds_write_b128 v210, v[240:243] offset:7168
	s_waitcnt lgkmcnt(0)
	v_readlane_b32 s4, v254, 27
	v_readlane_b32 s5, v254, 28
	v_cmp_gt_i32_e64 s[8:9], s27, v96
	v_cmp_lt_i32_e64 s[10:11], s33, v96
	s_mov_b64 s[12:13], -1
	s_and_b64 vcc, exec, s[4:5]
	s_cbranch_vccz .LBB0_182
	v_readlane_b32 s4, v254, 18
	v_readlane_b32 s5, v254, 19
	v_ashrrev_i32_e32 v139, 31, v96
	v_mov_b32_e32 v138, v96
	v_lshl_add_u64 v[0:1], s[4:5], 0, v[116:117]
	s_mov_b64 s[12:13], 0

.LBB0_212:
	s_waitcnt vmcnt(0) lgkmcnt(0)
	v_lshlrev_b32_e32 v228, 16, v202
	v_and_b32_e32 v229, 0xffff0000, v202
	v_lshlrev_b32_e32 v202, 16, v203
	v_and_b32_e32 v203, 0xffff0000, v203
	v_lshlrev_b32_e32 v230, 16, v204
	v_and_b32_e32 v231, 0xffff0000, v204
	v_lshlrev_b32_e32 v204, 16, v205
	v_and_b32_e32 v205, 0xffff0000, v205
	v_pk_mul_f32 v[94:95], v[94:95], 0.5 op_sel_hi:[1,0]
	v_pk_mul_f32 v[92:93], v[92:93], 0.5 op_sel_hi:[1,0]
	v_pk_add_f32 v[202:203], v[202:203], v[204:205]
	v_pk_add_f32 v[204:205], v[228:229], v[230:231]
	v_pk_mul_f32 v[94:95], v[94:95], v[202:203]
	v_pk_mul_f32 v[92:93], v[92:93], v[204:205]
	v_pk_fma_f32 v[90:91], v[90:91], s[42:43], v[94:95] op_sel_hi:[1,0,1]
	v_pk_fma_f32 v[88:89], v[88:89], s[42:43], v[92:93] op_sel_hi:[1,0,1]
	v_add_f32_e32 v93, v90, v91
	v_add_f32_e32 v92, v88, v89
	v_add_f32_e32 v92, v92, v93
	v_add_f32_e32 v143, 0, v92
	v_lshlrev_b32_e32 v92, 16, v198
	v_and_b32_e32 v93, 0xffff0000, v198
	v_lshlrev_b32_e32 v94, 16, v199
	v_and_b32_e32 v95, 0xffff0000, v199
	v_lshlrev_b32_e32 v198, 16, v200
	v_and_b32_e32 v199, 0xffff0000, v200
	v_lshlrev_b32_e32 v200, 16, v201
	v_and_b32_e32 v201, 0xffff0000, v201
	v_pk_mul_f32 v[86:87], v[86:87], 0.5 op_sel_hi:[1,0]
	v_pk_mul_f32 v[84:85], v[84:85], 0.5 op_sel_hi:[1,0]
	v_pk_add_f32 v[94:95], v[94:95], v[200:201]
	v_pk_add_f32 v[92:93], v[92:93], v[198:199]
	v_pk_mul_f32 v[86:87], v[86:87], v[94:95]
	v_pk_mul_f32 v[84:85], v[84:85], v[92:93]
	v_pk_fma_f32 v[86:87], v[78:79], s[42:43], v[86:87] op_sel_hi:[1,0,1]
	v_pk_fma_f32 v[84:85], v[76:77], s[42:43], v[84:85] op_sel_hi:[1,0,1]
	v_add_f32_e32 v77, v86, v87
	v_add_f32_e32 v76, v84, v85
	v_add_f32_e32 v76, v76, v77
	v_add_f32_e32 v143, v143, v76
	v_lshlrev_b32_e32 v76, 16, v194
	v_and_b32_e32 v77, 0xffff0000, v194
	v_lshlrev_b32_e32 v78, 16, v195
	v_and_b32_e32 v79, 0xffff0000, v195
	v_lshlrev_b32_e32 v92, 16, v196
	v_and_b32_e32 v93, 0xffff0000, v196
	v_lshlrev_b32_e32 v94, 16, v197
	v_and_b32_e32 v95, 0xffff0000, v197
	v_pk_mul_f32 v[82:83], v[82:83], 0.5 op_sel_hi:[1,0]
	v_pk_mul_f32 v[80:81], v[80:81], 0.5 op_sel_hi:[1,0]
	v_pk_add_f32 v[78:79], v[78:79], v[94:95]
	v_pk_add_f32 v[76:77], v[76:77], v[92:93]
	v_pk_mul_f32 v[78:79], v[82:83], v[78:79]
	v_pk_mul_f32 v[76:77], v[80:81], v[76:77]
	v_pk_fma_f32 v[82:83], v[74:75], s[42:43], v[78:79] op_sel_hi:[1,0,1]
	v_pk_fma_f32 v[80:81], v[72:73], s[42:43], v[76:77] op_sel_hi:[1,0,1]
	v_lshlrev_b32_e32 v72, 16, v188
	v_and_b32_e32 v73, 0xffff0000, v188
	v_lshlrev_b32_e32 v74, 16, v189
	v_and_b32_e32 v75, 0xffff0000, v189
	v_lshlrev_b32_e32 v76, 16, v190
	v_and_b32_e32 v77, 0xffff0000, v190
	v_lshlrev_b32_e32 v78, 16, v191
	v_and_b32_e32 v79, 0xffff0000, v191
	v_pk_mul_f32 v[70:71], v[70:71], 0.5 op_sel_hi:[1,0]
	v_pk_mul_f32 v[68:69], v[68:69], 0.5 op_sel_hi:[1,0]
	v_pk_add_f32 v[74:75], v[74:75], v[78:79]
	v_pk_add_f32 v[72:73], v[72:73], v[76:77]
	v_pk_mul_f32 v[70:71], v[70:71], v[74:75]
	v_pk_mul_f32 v[68:69], v[68:69], v[72:73]
	v_pk_fma_f32 v[188:189], v[66:67], s[42:43], v[70:71] op_sel_hi:[1,0,1]
	v_pk_fma_f32 v[190:191], v[64:65], s[42:43], v[68:69] op_sel_hi:[1,0,1]
	v_add_f32_e32 v65, v188, v189
	v_add_f32_e32 v64, v190, v191
	v_add_f32_e32 v64, v64, v65
	v_add_f32_e32 v72, 0, v64
	v_lshlrev_b32_e32 v64, 16, v184
	v_and_b32_e32 v65, 0xffff0000, v184
	v_lshlrev_b32_e32 v66, 16, v185
	v_and_b32_e32 v67, 0xffff0000, v185
	v_lshlrev_b32_e32 v68, 16, v186
	v_and_b32_e32 v69, 0xffff0000, v186
	v_lshlrev_b32_e32 v70, 16, v187
	v_and_b32_e32 v71, 0xffff0000, v187
	v_pk_mul_f32 v[62:63], v[62:63], 0.5 op_sel_hi:[1,0]
	v_pk_mul_f32 v[60:61], v[60:61], 0.5 op_sel_hi:[1,0]
	v_pk_add_f32 v[66:67], v[66:67], v[70:71]
	v_pk_add_f32 v[64:65], v[64:65], v[68:69]
	v_pk_mul_f32 v[62:63], v[62:63], v[66:67]
	v_pk_mul_f32 v[60:61], v[60:61], v[64:65]
	v_pk_fma_f32 v[186:187], v[54:55], s[42:43], v[62:63] op_sel_hi:[1,0,1]
	v_pk_fma_f32 v[184:185], v[52:53], s[42:43], v[60:61] op_sel_hi:[1,0,1]
	v_add_f32_e32 v53, v186, v187
	v_add_f32_e32 v52, v184, v185
	v_add_f32_e32 v52, v52, v53
	v_add_f32_e32 v64, v72, v52
	v_lshlrev_b32_e32 v52, 16, v180
	v_and_b32_e32 v53, 0xffff0000, v180
	v_lshlrev_b32_e32 v54, 16, v181
	v_and_b32_e32 v55, 0xffff0000, v181
	v_lshlrev_b32_e32 v60, 16, v182
	v_and_b32_e32 v61, 0xffff0000, v182
	v_lshlrev_b32_e32 v62, 16, v183
	v_and_b32_e32 v63, 0xffff0000, v183
	v_pk_mul_f32 v[58:59], v[58:59], 0.5 op_sel_hi:[1,0]
	v_pk_mul_f32 v[56:57], v[56:57], 0.5 op_sel_hi:[1,0]
	v_pk_add_f32 v[54:55], v[54:55], v[62:63]
	v_pk_add_f32 v[52:53], v[52:53], v[60:61]
	v_pk_mul_f32 v[54:55], v[58:59], v[54:55]
	v_pk_mul_f32 v[52:53], v[56:57], v[52:53]
	v_pk_fma_f32 v[50:51], v[50:51], s[42:43], v[54:55] op_sel_hi:[1,0,1]
	v_pk_fma_f32 v[48:49], v[48:49], s[42:43], v[52:53] op_sel_hi:[1,0,1]
	v_add_f32_e32 v53, v50, v51
	v_add_f32_e32 v52, v48, v49
	v_add_f32_e32 v52, v52, v53
	v_add_f32_e32 v60, v64, v52
	v_lshlrev_b32_e32 v52, 16, v176
	v_and_b32_e32 v53, 0xffff0000, v176
	v_lshlrev_b32_e32 v54, 16, v177
	v_and_b32_e32 v55, 0xffff0000, v177
	v_lshlrev_b32_e32 v56, 16, v178
	v_and_b32_e32 v57, 0xffff0000, v178
	v_lshlrev_b32_e32 v58, 16, v179
	v_and_b32_e32 v59, 0xffff0000, v179
	v_pk_mul_f32 v[46:47], v[46:47], 0.5 op_sel_hi:[1,0]
	v_pk_mul_f32 v[44:45], v[44:45], 0.5 op_sel_hi:[1,0]
	v_pk_add_f32 v[54:55], v[54:55], v[58:59]
	v_pk_add_f32 v[52:53], v[52:53], v[56:57]
	v_pk_mul_f32 v[46:47], v[46:47], v[54:55]
	v_pk_mul_f32 v[44:45], v[44:45], v[52:53]
	v_pk_fma_f32 v[178:179], v[42:43], s[42:43], v[46:47] op_sel_hi:[1,0,1]
	v_pk_fma_f32 v[176:177], v[40:41], s[42:43], v[44:45] op_sel_hi:[1,0,1]
	v_add_f32_e32 v41, v178, v179
	v_add_f32_e32 v40, v176, v177
	v_add_f32_e32 v40, v40, v41
	v_add_f32_e32 v42, v60, v40
	ds_bpermute_b32 v43, v99, v42
	v_add_f32_e32 v92, v80, v81
	v_add_f32_e32 v93, v82, v83
	v_add_f32_e32 v40, v92, v93
	v_add_f32_e32 v52, v143, v40
	s_waitcnt lgkmcnt(0)
	v_add_f32_e32 v46, v42, v43
	ds_bpermute_b32 v47, v101, v46
	v_lshlrev_b32_e32 v40, 16, v172
	v_and_b32_e32 v41, 0xffff0000, v172
	v_lshlrev_b32_e32 v44, 16, v174
	v_and_b32_e32 v45, 0xffff0000, v174
	s_waitcnt lgkmcnt(0)
	v_add_f32_e32 v53, v46, v47
	ds_bpermute_b32 v54, v103, v53
	v_pk_mul_f32 v[36:37], v[36:37], 0.5 op_sel_hi:[1,0]
	v_pk_add_f32 v[40:41], v[40:41], v[44:45]
	v_lshlrev_b32_e32 v42, 16, v173
	v_pk_mul_f32 v[36:37], v[36:37], v[40:41]
	s_waitcnt lgkmcnt(0)
	v_add_f32_e32 v53, v53, v54
	ds_bpermute_b32 v54, v105, v53
	v_and_b32_e32 v43, 0xffff0000, v173
	v_lshlrev_b32_e32 v46, 16, v175
	v_and_b32_e32 v47, 0xffff0000, v175
	v_pk_mul_f32 v[38:39], v[38:39], 0.5 op_sel_hi:[1,0]
	s_waitcnt lgkmcnt(0)
	v_add_f32_e32 v40, v53, v54
	ds_bpermute_b32 v41, v225, v40
	v_pk_add_f32 v[42:43], v[42:43], v[46:47]
	v_pk_fma_f32 v[92:93], v[32:33], s[42:43], v[36:37] op_sel_hi:[1,0,1]
	v_pk_mul_f32 v[38:39], v[38:39], v[42:43]
	v_add_f32_e32 v32, v92, v93
	v_pk_fma_f32 v[94:95], v[34:35], s[42:43], v[38:39] op_sel_hi:[1,0,1]
	s_waitcnt lgkmcnt(0)
	v_add_f32_e32 v34, v40, v41
	ds_bpermute_b32 v35, v226, v34
	v_add_f32_e32 v33, v94, v95
	v_add_f32_e32 v32, v32, v33
	v_add_f32_e32 v42, v52, v32
	v_lshlrev_b64 v[32:33], 11, v[192:193]
	s_waitcnt lgkmcnt(0)
	v_add_f32_e32 v43, v34, v35
	v_fmamk_f32 v191, v43, 0xba800000, v191
	v_fmac_f32_e32 v190, 0xba800000, v43
	v_fmamk_f32 v189, v43, 0xba800000, v189
	v_fmac_f32_e32 v188, 0xba800000, v43
	v_pk_mul_f32 v[34:35], v[188:189], v[188:189]
	v_pk_mul_f32 v[36:37], v[190:191], v[190:191]
	v_fmamk_f32 v185, v43, 0xba800000, v185
	v_pk_mov_b32 v[38:39], v[36:37], v[34:35] op_sel:[1,0]
	v_mov_b32_e32 v37, v35
	v_pk_add_f32 v[34:35], v[38:39], v[36:37]
	v_fmac_f32_e32 v184, 0xba800000, v43
	v_pk_add_f32 v[34:35], v[34:35], v[34:35] op_sel_hi:[0,1]
	v_fmamk_f32 v187, v43, 0xba800000, v187
	v_fmac_f32_e32 v186, 0xba800000, v43
	ds_bpermute_b32 v34, v99, v42
	v_pk_mul_f32 v[36:37], v[186:187], v[186:187]
	v_pk_mul_f32 v[38:39], v[184:185], v[184:185]
	v_fmac_f32_e32 v48, 0xba800000, v43
	v_pk_mov_b32 v[40:41], v[38:39], v[36:37] op_sel:[1,0]
	v_mov_b32_e32 v39, v37
	v_pk_add_f32 v[36:37], v[40:41], v[38:39]
	v_fmamk_f32 v49, v43, 0xba800000, v49
	v_pk_add_f32 v[36:37], v[36:37], v[36:37] op_sel_hi:[0,1]
	s_waitcnt lgkmcnt(0)
	v_add_f32_e32 v36, v42, v34
	ds_bpermute_b32 v38, v101, v36
	v_fmac_f32_e32 v50, 0xba800000, v43
	v_mul_f32_e32 v34, v48, v48
	v_fmamk_f32 v51, v43, 0xba800000, v51
	v_fmamk_f32 v179, v43, 0xba800000, v179
	s_waitcnt lgkmcnt(0)
	v_add_f32_e32 v36, v36, v38
	ds_bpermute_b32 v42, v103, v36
	v_pk_fma_f32 v[38:39], v[48:49], v[48:49], v[34:35] op_sel_hi:[1,1,0]
	v_mul_f32_e32 v34, v50, v50
	v_pk_fma_f32 v[40:41], v[50:51], v[50:51], v[34:35] op_sel_hi:[1,1,0]
	v_fmac_f32_e32 v178, 0xba800000, v43
	s_waitcnt lgkmcnt(0)
	v_add_f32_e32 v34, v36, v42
	ds_bpermute_b32 v36, v105, v34
	v_fmamk_f32 v177, v43, 0xba800000, v177
	v_fmac_f32_e32 v176, 0xba800000, v43
	v_mul_f32_e32 v38, v176, v176
	v_mul_f32_e32 v40, v177, v177
	s_waitcnt lgkmcnt(0)
	v_add_f32_e32 v42, v34, v36
	v_mul_f32_e32 v34, v178, v178
	v_mul_f32_e32 v36, v179, v179
	v_pk_add_f32 v[38:39], v[38:39], v[40:41]
	v_pk_add_f32 v[34:35], v[34:35], v[36:37]
	ds_bpermute_b32 v43, v225, v42
	v_pk_add_f32 v[34:35], v[38:39], v[34:35]
	ds_read_b128 v[36:39], v210
	ds_read_b128 v[56:59], v210 offset:4096
	v_lshl_add_u64 v[32:33], s[56:57], 0, v[32:33]
	s_mov_b64 s[4:5], 0x1000000
	s_waitcnt lgkmcnt(0)
	v_add_f32_e32 v40, v42, v43
	ds_bpermute_b32 v41, v226, v40
	v_ashrrev_i32_e32 v136, 10, v136
	v_lshl_add_u64 v[60:61], v[32:33], 0, s[4:5]
	v_mov_b32_e32 v145, v153
	v_add_u32_e32 v136, 1, v136
	s_waitcnt lgkmcnt(0)
	v_add_f32_e32 v52, v40, v41
	v_fmamk_f32 v89, v52, 0xba800000, v89
	v_fmac_f32_e32 v88, 0xba800000, v52
	v_fmamk_f32 v91, v52, 0xba800000, v91
	v_fmac_f32_e32 v90, 0xba800000, v52
	v_pk_mul_f32 v[40:41], v[90:91], v[90:91]
	v_pk_mul_f32 v[42:43], v[88:89], v[88:89]
	v_fmamk_f32 v85, v52, 0xba800000, v85
	v_pk_mov_b32 v[44:45], v[42:43], v[40:41] op_sel:[1,0]
	v_mov_b32_e32 v43, v41
	v_pk_add_f32 v[40:41], v[44:45], v[42:43]
	v_fmac_f32_e32 v84, 0xba800000, v52
	v_fmamk_f32 v87, v52, 0xba800000, v87
	v_fmac_f32_e32 v86, 0xba800000, v52
	v_pk_add_f32 v[40:41], v[40:41], v[40:41] op_sel_hi:[0,1]
	v_pk_mul_f32 v[42:43], v[86:87], v[86:87]
	v_pk_mul_f32 v[44:45], v[84:85], v[84:85]
	v_fmac_f32_e32 v80, 0xba800000, v52
	v_pk_mov_b32 v[46:47], v[44:45], v[42:43] op_sel:[1,0]
	v_mov_b32_e32 v45, v43
	v_fmamk_f32 v81, v52, 0xba800000, v81
	v_fmac_f32_e32 v82, 0xba800000, v52
	v_mul_f32_e32 v40, v80, v80
	v_pk_add_f32 v[42:43], v[46:47], v[44:45]
	v_fmamk_f32 v83, v52, 0xba800000, v83
	v_pk_fma_f32 v[44:45], v[80:81], v[80:81], v[40:41] op_sel_hi:[1,1,0]
	v_mul_f32_e32 v40, v82, v82
	v_pk_add_f32 v[42:43], v[42:43], v[42:43] op_sel_hi:[0,1]
	v_pk_fma_f32 v[46:47], v[82:83], v[82:83], v[40:41] op_sel_hi:[1,1,0]
	v_fmamk_f32 v95, v52, 0xba800000, v95
	v_fmac_f32_e32 v94, 0xba800000, v52
	v_fmamk_f32 v93, v52, 0xba800000, v93
	v_fmac_f32_e32 v92, 0xba800000, v52
	v_mul_f32_e32 v44, v92, v92
	v_mul_f32_e32 v46, v93, v93
	v_mul_f32_e32 v40, v94, v94
	v_mul_f32_e32 v42, v95, v95
	v_pk_add_f32 v[44:45], v[44:45], v[46:47]
	v_pk_add_f32 v[40:41], v[40:41], v[42:43]
	v_mov_b32_e32 v43, v34
	v_pk_add_f32 v[40:41], v[44:45], v[40:41]
	v_mov_b32_e32 v147, v153
	v_mov_b32_e32 v42, v40
	v_mov_b32_e32 v34, v41
	v_pk_add_f32 v[34:35], v[42:43], v[34:35]
	ds_bpermute_b32 v41, v99, v35
	ds_bpermute_b32 v40, v99, v34
	v_lshl_add_u64 v[192:193], v[60:61], 0, v[144:145]
	v_cndmask_b32_e64 v136, v136, 0, s[10:11]
	v_lshl_add_u64 v[172:173], v[32:33], 0, v[146:147]
	v_lshl_add_u64 v[180:181], v[60:61], 0, v[146:147]
	s_waitcnt lgkmcnt(0)
	v_pk_add_f32 v[34:35], v[34:35], v[40:41]
	ds_bpermute_b32 v41, v101, v35
	ds_bpermute_b32 v40, v101, v34
	v_ashrrev_i32_e32 v137, 31, v136
	v_lshl_add_u64 v[136:137], v[136:137], 0, s[28:29]
	v_mad_u64_u32 v[62:63], s[4:5], v136, s7, v[110:111]
	s_waitcnt lgkmcnt(0)
	v_pk_add_f32 v[46:47], v[34:35], v[40:41]
	ds_bpermute_b32 v53, v103, v47
	ds_bpermute_b32 v52, v103, v46
	v_lshl_add_u64 v[44:45], v[170:171], 0, v[152:153]
	v_mad_i32_i24 v63, v137, s7, v63
	flat_load_dwordx4 v[40:43], v[44:45]
	flat_load_dwordx4 v[32:35], v[44:45] offset:1024
	flat_load_dwordx4 v[68:71], v[62:63]
	flat_load_dwordx4 v[64:67], v[62:63] offset:1024
	v_mov_b32_e32 v149, v153
	s_waitcnt lgkmcnt(0)
	v_pk_add_f32 v[46:47], v[46:47], v[52:53]
	ds_bpermute_b32 v53, v105, v47
	ds_bpermute_b32 v52, v105, v46
	v_mov_b32_e32 v143, v153
	s_mov_b32 s2, 0x3727c5ac
	v_lshl_add_u64 v[148:149], v[60:61], 0, v[148:149]
	v_lshl_add_u64 v[60:61], v[60:61], 0, v[142:143]
	s_waitcnt lgkmcnt(0)
	v_pk_add_f32 v[144:145], v[46:47], v[52:53]
	ds_bpermute_b32 v147, v225, v145
	ds_bpermute_b32 v146, v225, v144
	flat_load_dwordx4 v[52:55], v[44:45] offset:2048
	s_nop 0
	flat_load_dwordx4 v[44:47], v[44:45] offset:3072
	s_nop 0
	flat_load_dwordx4 v[76:79], v[62:63] offset:2048
	flat_load_dwordx4 v[72:75], v[62:63] offset:3072
	v_mov_b64_e32 v[142:143], s[2:3]
	s_mov_b32 s2, 0x3a800000
	v_pk_mul_f32 v[230:231], v[24:25], 0.5 op_sel_hi:[1,0]
	s_waitcnt lgkmcnt(0)
	v_pk_add_f32 v[62:63], v[144:145], v[146:147]
	ds_bpermute_b32 v183, v226, v63
	ds_bpermute_b32 v182, v226, v62
	flat_load_dwordx2 v[174:175], v[172:173]
	flat_load_dwordx2 v[170:171], v[172:173] offset:512
	flat_load_dwordx2 v[146:147], v[172:173] offset:1024
	flat_load_dwordx2 v[144:145], v[172:173] offset:1536
	v_pk_mul_f32 v[228:229], v[26:27], 0.5 op_sel_hi:[1,0]
	v_pk_mul_f32 v[196:197], v[28:29], 0.5 op_sel_hi:[1,0]
	v_lshlrev_b32_e32 v198, 16, v162
	s_waitcnt lgkmcnt(0)
	v_pk_add_f32 v[62:63], v[62:63], v[182:183]
	flat_load_dwordx2 v[182:183], v[180:181]
	s_nop 0
	flat_load_dwordx2 v[180:181], v[192:193]
	flat_load_dwordx2 v[172:173], v[148:149]
	s_nop 0
	flat_load_dwordx2 v[148:149], v[60:61]
	v_pk_fma_f32 v[194:195], v[62:63], s[2:3], v[142:143] op_sel_hi:[1,0,0]
	v_lshlrev_b64 v[60:61], 12, v[138:139]
	v_mul_f32_e32 v62, 0x4b800000, v195
	v_cmp_gt_f32_e32 vcc, s68, v195
	v_lshl_add_u64 v[138:139], v[112:113], 0, v[60:61]
	v_mul_f32_e32 v24, 0x4b800000, v194
	v_cndmask_b32_e32 v62, v195, v62, vcc
	v_rsq_f32_e32 v62, v62
	v_and_b32_e32 v199, 0xffff0000, v162
	v_lshlrev_b32_e32 v162, 16, v163
	v_and_b32_e32 v163, 0xffff0000, v163
	v_mul_f32_e32 v60, 0x45800000, v62
	v_cndmask_b32_e32 v192, v62, v60, vcc
	v_pk_mul_f32 v[60:61], v[190:191], v[192:193] op_sel_hi:[1,0]
	v_pk_mul_f32 v[62:63], v[188:189], v[192:193] op_sel_hi:[1,0]
	s_waitcnt vmcnt(0) lgkmcnt(0)
	v_pk_fma_f32 v[60:61], v[36:37], v[60:61], v[56:57]
	v_pk_fma_f32 v[62:63], v[38:39], v[62:63], v[58:59]
	flat_store_dwordx4 v[138:139], v[60:63]
	ds_read_b128 v[36:39], v210 offset:1024
	ds_read_b128 v[56:59], v210 offset:5120
	v_pk_mul_f32 v[186:187], v[186:187], v[192:193] op_sel_hi:[1,0]
	v_pk_mul_f32 v[184:185], v[184:185], v[192:193] op_sel_hi:[1,0]
	v_pk_mul_f32 v[50:51], v[50:51], v[192:193] op_sel_hi:[1,0]
	v_pk_mul_f32 v[48:49], v[48:49], v[192:193] op_sel_hi:[1,0]
	v_pk_mul_f32 v[178:179], v[178:179], v[192:193] op_sel_hi:[1,0]
	v_pk_mul_f32 v[176:177], v[176:177], v[192:193] op_sel_hi:[1,0]
	v_cmp_gt_f32_e32 vcc, s68, v194
	v_pk_mul_f32 v[192:193], v[30:31], 0.5 op_sel_hi:[1,0]
	v_lshlrev_b32_e32 v188, 16, v166
	v_cndmask_b32_e32 v24, v194, v24, vcc
	v_rsq_f32_e32 v26, v24
	v_lshlrev_b64 v[24:25], 12, v[140:141]
	v_and_b32_e32 v189, 0xffff0000, v166
	v_lshlrev_b32_e32 v166, 16, v167
	v_and_b32_e32 v167, 0xffff0000, v167
	v_lshlrev_b32_e32 v190, 16, v168
	v_and_b32_e32 v191, 0xffff0000, v168
	v_lshlrev_b32_e32 v168, 16, v169
	v_and_b32_e32 v169, 0xffff0000, v169
	v_lshlrev_b32_e32 v200, 16, v164
	v_and_b32_e32 v201, 0xffff0000, v164
	v_lshlrev_b32_e32 v164, 16, v165
	v_and_b32_e32 v165, 0xffff0000, v165
	v_lshlrev_b32_e32 v202, 16, v158
	v_and_b32_e32 v203, 0xffff0000, v158
	v_lshlrev_b32_e32 v158, 16, v159
	v_and_b32_e32 v159, 0xffff0000, v159
	v_lshlrev_b32_e32 v204, 16, v160
	v_and_b32_e32 v205, 0xffff0000, v160
	v_lshlrev_b32_e32 v160, 16, v161
	v_and_b32_e32 v161, 0xffff0000, v161
	v_pk_add_f32 v[166:167], v[166:167], v[168:169]
	v_pk_add_f32 v[168:169], v[188:189], v[190:191]
	v_pk_mul_f32 v[22:23], v[22:23], 0.5 op_sel_hi:[1,0]
	v_pk_mul_f32 v[20:21], v[20:21], 0.5 op_sel_hi:[1,0]
	v_lshlrev_b32_e32 v232, 16, v150
	v_and_b32_e32 v233, 0xffff0000, v150
	v_lshlrev_b32_e32 v150, 16, v151
	v_and_b32_e32 v151, 0xffff0000, v151
	v_lshlrev_b32_e32 v234, 16, v156
	v_and_b32_e32 v235, 0xffff0000, v156
	v_lshlrev_b32_e32 v156, 16, v157
	v_and_b32_e32 v157, 0xffff0000, v157
	v_pk_add_f32 v[162:163], v[162:163], v[164:165]
	v_pk_add_f32 v[164:165], v[198:199], v[200:201]
	v_pk_add_f32 v[158:159], v[158:159], v[160:161]
	v_pk_add_f32 v[160:161], v[202:203], v[204:205]
	v_pk_mul_f32 v[168:169], v[196:197], v[168:169]
	v_pk_mul_f32 v[166:167], v[192:193], v[166:167]
	v_pk_mul_f32 v[18:19], v[18:19], 0.5 op_sel_hi:[1,0]
	v_pk_mul_f32 v[16:17], v[16:17], 0.5 op_sel_hi:[1,0]
	v_pk_add_f32 v[150:151], v[150:151], v[156:157]
	v_pk_add_f32 v[156:157], v[232:233], v[234:235]
	v_pk_mul_f32 v[164:165], v[20:21], v[164:165]
	v_pk_mul_f32 v[162:163], v[22:23], v[162:163]
	v_pk_mul_f32 v[160:161], v[230:231], v[160:161]
	v_pk_fma_f32 v[22:23], v[2:3], s[42:43], v[166:167] op_sel_hi:[1,0,1]
	v_pk_fma_f32 v[20:21], v[0:1], s[42:43], v[168:169] op_sel_hi:[1,0,1]
	v_pk_mul_f32 v[158:159], v[228:229], v[158:159]
	v_pk_mul_f32 v[156:157], v[16:17], v[156:157]
	v_pk_mul_f32 v[150:151], v[18:19], v[150:151]
	v_pk_fma_f32 v[18:19], v[6:7], s[42:43], v[162:163] op_sel_hi:[1,0,1]
	v_pk_fma_f32 v[16:17], v[4:5], s[42:43], v[164:165] op_sel_hi:[1,0,1]
	v_pk_fma_f32 v[4:5], v[8:9], s[42:43], v[160:161] op_sel_hi:[1,0,1]
	v_add_f32_e32 v8, v20, v21
	v_add_f32_e32 v9, v22, v23
	v_pk_fma_f32 v[6:7], v[10:11], s[42:43], v[158:159] op_sel_hi:[1,0,1]
	v_add_f32_e32 v10, v16, v17
	v_add_f32_e32 v11, v18, v19
	v_add_f32_e32 v8, v8, v9
	v_pk_fma_f32 v[2:3], v[14:15], s[42:43], v[150:151] op_sel_hi:[1,0,1]
	v_pk_fma_f32 v[0:1], v[12:13], s[42:43], v[156:157] op_sel_hi:[1,0,1]
	v_add_f32_e32 v12, v4, v5
	v_add_f32_e32 v13, v6, v7
	v_add_f32_e32 v9, v10, v11
	v_add_f32_e32 v8, 0, v8
	v_add_f32_e32 v14, v0, v1
	v_add_f32_e32 v15, v2, v3
	v_add_f32_e32 v10, v12, v13
	s_waitcnt vmcnt(1) lgkmcnt(0)
	v_pk_fma_f32 v[56:57], v[36:37], v[184:185], v[56:57]
	v_pk_fma_f32 v[58:59], v[38:39], v[186:187], v[58:59]
	flat_store_dwordx4 v[138:139], v[56:59] offset:1024
	ds_read_b128 v[36:39], v210 offset:2048
	ds_read_b128 v[184:187], v210 offset:6144
	v_add_f32_e32 v8, v8, v9
	v_add_f32_e32 v11, v14, v15
	v_add_f32_e32 v8, v8, v10
	v_add_f32_e32 v8, v8, v11
	ds_bpermute_b32 v9, v99, v8
	v_lshlrev_b32_e32 v14, 16, v171
	v_and_b32_e32 v15, 0xffff0000, v171
	s_waitcnt lgkmcnt(0)
	v_lshlrev_b32_e32 v162, 16, v182
	v_and_b32_e32 v163, 0xffff0000, v182
	v_add_f32_e32 v8, v8, v9
	ds_bpermute_b32 v9, v101, v8
	v_lshlrev_b32_e32 v164, 16, v183
	v_and_b32_e32 v165, 0xffff0000, v183
	v_lshlrev_b32_e32 v168, 16, v181
	v_and_b32_e32 v169, 0xffff0000, v181
	s_waitcnt lgkmcnt(0)
	v_add_f32_e32 v8, v8, v9
	ds_bpermute_b32 v9, v103, v8
	v_and_b32_e32 v13, 0xffff0000, v170
	v_lshlrev_b32_e32 v166, 16, v180
	v_and_b32_e32 v167, 0xffff0000, v180
	v_pk_add_f32 v[14:15], v[14:15], v[168:169]
	s_waitcnt lgkmcnt(0)
	v_add_f32_e32 v8, v8, v9
	ds_bpermute_b32 v9, v105, v8
	v_pk_mul_f32 v[70:71], v[70:71], 0.5 op_sel_hi:[1,0]
	v_pk_mul_f32 v[68:69], v[68:69], 0.5 op_sel_hi:[1,0]
	v_pk_mul_f32 v[66:67], v[66:67], 0.5 op_sel_hi:[1,0]
	v_pk_mul_f32 v[64:65], v[64:65], 0.5 op_sel_hi:[1,0]
	s_waitcnt lgkmcnt(0)
	v_add_f32_e32 v8, v8, v9
	ds_bpermute_b32 v9, v225, v8
	v_pk_mul_f32 v[66:67], v[66:67], v[14:15]
	v_lshlrev_b32_e32 v158, 16, v146
	v_and_b32_e32 v159, 0xffff0000, v146
	v_lshlrev_b32_e32 v146, 16, v147
	s_waitcnt lgkmcnt(0)
	v_add_f32_e32 v8, v8, v9
	ds_bpermute_b32 v9, v226, v8
	v_and_b32_e32 v147, 0xffff0000, v147
	v_lshlrev_b32_e32 v160, 16, v144
	v_and_b32_e32 v161, 0xffff0000, v144
	v_lshlrev_b32_e32 v144, 16, v145
	s_waitcnt lgkmcnt(0)
	v_add_f32_e32 v12, v8, v9
	v_fmamk_f32 v21, v12, 0xba800000, v21
	v_fmac_f32_e32 v20, 0xba800000, v12
	v_fmamk_f32 v23, v12, 0xba800000, v23
	v_fmac_f32_e32 v22, 0xba800000, v12
	v_fmamk_f32 v17, v12, 0xba800000, v17
	v_fmac_f32_e32 v16, 0xba800000, v12
	v_fmamk_f32 v19, v12, 0xba800000, v19
	v_fmac_f32_e32 v18, 0xba800000, v12
	v_fmamk_f32 v5, v12, 0xba800000, v5
	v_fmac_f32_e32 v4, 0xba800000, v12
	v_fmamk_f32 v7, v12, 0xba800000, v7
	v_fmac_f32_e32 v6, 0xba800000, v12
	v_fmamk_f32 v3, v12, 0xba800000, v3
	v_fmac_f32_e32 v2, 0xba800000, v12
	v_fmamk_f32 v1, v12, 0xba800000, v1
	v_fmac_f32_e32 v0, 0xba800000, v12
	v_lshlrev_b32_e32 v12, 16, v170
	v_pk_add_f32 v[12:13], v[12:13], v[166:167]
	v_and_b32_e32 v145, 0xffff0000, v145
	v_pk_mul_f32 v[64:65], v[64:65], v[12:13]
	v_lshlrev_b32_e32 v170, 16, v172
	v_and_b32_e32 v171, 0xffff0000, v172
	v_lshlrev_b32_e32 v172, 16, v173
	v_and_b32_e32 v173, 0xffff0000, v173
	v_pk_add_f32 v[158:159], v[158:159], v[170:171]
	v_pk_add_f32 v[146:147], v[146:147], v[172:173]
	v_pk_mul_f32 v[78:79], v[78:79], 0.5 op_sel_hi:[1,0]
	v_pk_mul_f32 v[76:77], v[76:77], 0.5 op_sel_hi:[1,0]
	v_pk_mul_f32 v[74:75], v[74:75], 0.5 op_sel_hi:[1,0]
	v_pk_mul_f32 v[72:73], v[72:73], 0.5 op_sel_hi:[1,0]
	v_pk_mul_f32 v[150:151], v[22:23], v[22:23]
	v_pk_mul_f32 v[156:157], v[20:21], v[20:21]
	v_readlane_b32 s4, v254, 33
	v_readlane_b32 s5, v254, 34
	s_waitcnt vmcnt(2) lgkmcnt(0)
	v_pk_fma_f32 v[48:49], v[36:37], v[48:49], v[184:185]
	v_pk_fma_f32 v[50:51], v[38:39], v[50:51], v[186:187]
	flat_store_dwordx4 v[138:139], v[48:51] offset:2048
	ds_read_b128 v[36:39], v210 offset:3072
	ds_read_b128 v[184:187], v210 offset:7168
	s_waitcnt vmcnt(3) lgkmcnt(0)
	v_pk_fma_f32 v[36:37], v[36:37], v[176:177], v[184:185]
	v_pk_fma_f32 v[38:39], v[38:39], v[178:179], v[186:187]
	flat_store_dwordx4 v[138:139], v[36:39] offset:3072
	ds_read_b128 v[176:179], v210
	ds_read_b128 v[184:187], v210 offset:4096
	v_lshl_add_u64 v[138:139], v[112:113], 0, v[24:25]
	v_mul_f32_e32 v24, 0x45800000, v26
	v_cndmask_b32_e32 v140, v26, v24, vcc
	v_pk_mul_f32 v[26:27], v[90:91], v[140:141] op_sel_hi:[1,0]
	v_pk_mul_f32 v[24:25], v[88:89], v[140:141] op_sel_hi:[1,0]
	v_pk_mul_f32 v[8:9], v[86:87], v[140:141] op_sel_hi:[1,0]
	v_pk_mul_f32 v[10:11], v[84:85], v[140:141] op_sel_hi:[1,0]
	s_waitcnt vmcnt(4) lgkmcnt(0)
	v_pk_fma_f32 v[24:25], v[176:177], v[24:25], v[184:185]
	v_pk_fma_f32 v[26:27], v[178:179], v[26:27], v[186:187]
	flat_store_dwordx4 v[138:139], v[24:27]
	ds_read_b128 v[28:31], v210 offset:1024
	ds_read_b128 v[88:91], v210 offset:5120
	s_waitcnt vmcnt(5) lgkmcnt(0)
	v_pk_fma_f32 v[28:29], v[28:29], v[10:11], v[88:89]
	v_pk_fma_f32 v[30:31], v[30:31], v[8:9], v[90:91]
	flat_store_dwordx4 v[138:139], v[28:31] offset:1024
	ds_read_b128 v[84:87], v210 offset:2048
	ds_read_b128 v[88:91], v210 offset:6144
	v_lshlrev_b32_e32 v8, 16, v174
	v_and_b32_e32 v9, 0xffff0000, v174
	v_lshlrev_b32_e32 v10, 16, v175
	v_and_b32_e32 v11, 0xffff0000, v175
	v_pk_add_f32 v[8:9], v[8:9], v[162:163]
	v_pk_add_f32 v[10:11], v[10:11], v[164:165]
	v_pk_mul_f32 v[8:9], v[68:69], v[8:9]
	v_pk_mul_f32 v[10:11], v[70:71], v[10:11]
	v_pk_fma_f32 v[12:13], v[40:41], s[42:43], v[8:9] op_sel_hi:[1,0,1]
	v_pk_fma_f32 v[14:15], v[42:43], s[42:43], v[10:11] op_sel_hi:[1,0,1]
	v_pk_fma_f32 v[8:9], v[34:35], s[42:43], v[66:67] op_sel_hi:[1,0,1]
	v_pk_mul_f32 v[10:11], v[82:83], v[140:141] op_sel_hi:[1,0]
	v_pk_mul_f32 v[34:35], v[80:81], v[140:141] op_sel_hi:[1,0]
	v_lshlrev_b32_e32 v174, 16, v148
	v_and_b32_e32 v175, 0xffff0000, v148
	v_lshlrev_b32_e32 v148, 16, v149
	v_and_b32_e32 v149, 0xffff0000, v149
	v_pk_add_f32 v[160:161], v[160:161], v[174:175]
	v_pk_add_f32 v[144:145], v[144:145], v[148:149]
	v_pk_mul_f32 v[68:69], v[78:79], v[146:147]
	v_pk_mul_f32 v[146:147], v[76:77], v[158:159]
	v_pk_mul_f32 v[144:145], v[74:75], v[144:145]
	v_pk_mul_f32 v[148:149], v[72:73], v[160:161]
	v_pk_fma_f32 v[66:67], v[46:47], s[42:43], v[144:145] op_sel_hi:[1,0,1]
	v_mov_b32_e32 v47, v9
	v_pk_fma_f32 v[70:71], v[54:55], s[42:43], v[68:69] op_sel_hi:[1,0,1]
	v_pk_fma_f32 v[68:69], v[52:53], s[42:43], v[146:147] op_sel_hi:[1,0,1]
	v_add_f32_e32 v54, v70, v71
	v_add_f32_e32 v52, v68, v69
	v_mov_b32_e32 v53, v66
	v_mov_b32_e32 v55, v67
	s_waitcnt vmcnt(6) lgkmcnt(0)
	v_pk_fma_f32 v[40:41], v[84:85], v[34:35], v[88:89]
	v_pk_fma_f32 v[42:43], v[86:87], v[10:11], v[90:91]
	flat_store_dwordx4 v[138:139], v[40:43] offset:2048
	ds_read_b128 v[72:75], v210 offset:3072
	ds_read_b128 v[76:79], v210 offset:7168
	v_pk_fma_f32 v[10:11], v[32:33], s[42:43], v[64:65] op_sel_hi:[1,0,1]
	v_pk_fma_f32 v[64:65], v[44:45], s[42:43], v[148:149] op_sel_hi:[1,0,1]
	v_pk_mov_b32 v[32:33], v[12:13], v[14:15] op_sel:[1,0]
	v_mov_b32_e32 v34, v12
	v_mov_b32_e32 v35, v15
	v_pk_mov_b32 v[44:45], v[10:11], v[8:9] op_sel:[1,0]
	v_mov_b32_e32 v46, v10
	v_pk_add_f32 v[32:33], v[32:33], v[34:35]
	v_pk_add_f32 v[34:35], v[44:45], v[46:47]
	v_add_f32_e32 v46, v32, v33
	v_pk_add_f32 v[32:33], v[34:35], v[34:35] op_sel:[0,1] op_sel_hi:[1,0]
	v_mov_b32_e32 v81, v64
	v_add_f32_e32 v80, 0, v46
	v_mov_b32_e32 v33, v65
	v_pk_add_f32 v[44:45], v[52:53], v[54:55]
	v_pk_add_f32 v[32:33], v[80:81], v[32:33]
	v_pk_mul_f32 v[34:35], v[16:17], v[16:17]
	v_pk_add_f32 v[32:33], v[32:33], v[44:45]
	v_mul_f32_e32 v44, v4, v4
	v_add_f32_e32 v45, v32, v33
	ds_bpermute_b32 v47, v99, v45
	v_pk_mul_f32 v[32:33], v[18:19], v[18:19]
	v_mul_f32_e32 v46, v6, v6
	v_pk_mov_b32 v[52:53], v[156:157], v[150:151] op_sel:[1,0]
	v_mov_b32_e32 v157, v151
	s_waitcnt lgkmcnt(0)
	v_add_f32_e32 v45, v45, v47
	ds_bpermute_b32 v47, v101, v45
	v_pk_mov_b32 v[54:55], v[34:35], v[32:33] op_sel:[1,0]
	v_mov_b32_e32 v35, v33
	v_pk_fma_f32 v[32:33], v[4:5], v[4:5], v[44:45] op_sel_hi:[1,1,0]
	v_pk_add_f32 v[34:35], v[54:55], v[34:35]
	s_waitcnt lgkmcnt(0)
	v_add_f32_e32 v80, v45, v47
	ds_bpermute_b32 v81, v103, v80
	v_pk_fma_f32 v[44:45], v[6:7], v[6:7], v[46:47] op_sel_hi:[1,1,0]
	v_pk_add_f32 v[46:47], v[52:53], v[156:157]
	v_mul_f32_e32 v32, v0, v0
	v_mul_f32_e32 v44, v1, v1
	s_waitcnt lgkmcnt(0)
	v_add_f32_e32 v52, v80, v81
	ds_bpermute_b32 v53, v105, v52
	v_pk_add_f32 v[32:33], v[32:33], v[44:45]
	v_pk_add_f32 v[46:47], v[46:47], v[46:47] op_sel_hi:[0,1]
	v_pk_add_f32 v[34:35], v[34:35], v[34:35] op_sel_hi:[0,1]
	v_mul_f32_e32 v46, v2, v2
	s_waitcnt lgkmcnt(0)
	v_add_f32_e32 v52, v52, v53
	ds_bpermute_b32 v53, v225, v52
	v_mul_f32_e32 v34, v3, v3
	v_pk_add_f32 v[34:35], v[46:47], v[34:35]
	s_waitcnt lgkmcnt(0)
	v_add_f32_e32 v44, v52, v53
	ds_bpermute_b32 v45, v226, v44
	v_pk_add_f32 v[80:81], v[32:33], v[34:35]
	v_pk_mul_f32 v[32:33], v[94:95], v[140:141] op_sel_hi:[1,0]
	v_pk_mul_f32 v[34:35], v[92:93], v[140:141] op_sel_hi:[1,0]
	v_mov_b32_e32 v83, v80
	s_waitcnt lgkmcnt(0)
	v_add_f32_e32 v44, v44, v45
	v_fmamk_f32 v13, v44, 0xba800000, v13
	v_fmac_f32_e32 v12, 0xba800000, v44
	v_fmamk_f32 v15, v44, 0xba800000, v15
	v_fmac_f32_e32 v14, 0xba800000, v44
	v_fmamk_f32 v11, v44, 0xba800000, v11
	v_fmac_f32_e32 v10, 0xba800000, v44
	v_fmamk_f32 v9, v44, 0xba800000, v9
	v_fmac_f32_e32 v8, 0xba800000, v44
	v_fmamk_f32 v69, v44, 0xba800000, v69
	v_fmac_f32_e32 v68, 0xba800000, v44
	v_fmamk_f32 v71, v44, 0xba800000, v71
	v_fmac_f32_e32 v70, 0xba800000, v44
	v_fmamk_f32 v67, v44, 0xba800000, v67
	v_fmac_f32_e32 v66, 0xba800000, v44
	v_fmamk_f32 v65, v44, 0xba800000, v65
	v_fmac_f32_e32 v64, 0xba800000, v44
	v_pk_mul_f32 v[84:85], v[14:15], v[14:15]
	v_mul_f32_e32 v80, v70, v70
	s_waitcnt vmcnt(7) lgkmcnt(0)
	v_pk_fma_f32 v[52:53], v[72:73], v[34:35], v[76:77]
	v_pk_fma_f32 v[54:55], v[74:75], v[32:33], v[78:79]
	flat_store_dwordx4 v[138:139], v[52:55] offset:3072
	ds_read_b128 v[32:35], v210
	ds_read_b128 v[44:47], v210 offset:4096
	v_pk_mul_f32 v[72:73], v[12:13], v[12:13]
	v_pk_mul_f32 v[74:75], v[8:9], v[8:9]
	v_pk_mul_f32 v[76:77], v[10:11], v[10:11]
	v_pk_mov_b32 v[86:87], v[72:73], v[84:85] op_sel:[1,0]
	v_mov_b32_e32 v73, v85
	v_pk_mov_b32 v[84:85], v[76:77], v[74:75] op_sel:[1,0]
	v_mov_b32_e32 v77, v75
	v_mul_f32_e32 v78, v68, v68
	v_pk_add_f32 v[72:73], v[86:87], v[72:73]
	v_pk_add_f32 v[76:77], v[84:85], v[76:77]
	v_pk_fma_f32 v[74:75], v[68:69], v[68:69], v[78:79] op_sel_hi:[1,1,0]
	v_pk_fma_f32 v[78:79], v[70:71], v[70:71], v[80:81] op_sel_hi:[1,1,0]
	v_pk_add_f32 v[72:73], v[72:73], v[72:73] op_sel_hi:[0,1]
	v_pk_add_f32 v[76:77], v[76:77], v[76:77] op_sel_hi:[0,1]
	v_mul_f32_e32 v74, v64, v64
	v_mul_f32_e32 v78, v65, v65
	v_mul_f32_e32 v72, v66, v66
	v_mul_f32_e32 v76, v67, v67
	v_pk_add_f32 v[74:75], v[74:75], v[78:79]
	v_pk_add_f32 v[72:73], v[72:73], v[76:77]
	s_nop 0
	v_pk_add_f32 v[72:73], v[74:75], v[72:73]
	s_nop 0
	v_mov_b32_e32 v82, v72
	v_mov_b32_e32 v80, v73
	v_pk_add_f32 v[72:73], v[82:83], v[80:81]
	ds_bpermute_b32 v75, v99, v73
	ds_bpermute_b32 v74, v99, v72
	s_waitcnt lgkmcnt(0)
	v_pk_add_f32 v[72:73], v[72:73], v[74:75]
	ds_bpermute_b32 v75, v101, v73
	ds_bpermute_b32 v74, v101, v72
	s_waitcnt lgkmcnt(0)
	v_pk_add_f32 v[72:73], v[72:73], v[74:75]
	ds_bpermute_b32 v75, v103, v73
	ds_bpermute_b32 v74, v103, v72
	s_waitcnt lgkmcnt(0)
	v_pk_add_f32 v[72:73], v[72:73], v[74:75]
	ds_bpermute_b32 v75, v105, v73
	ds_bpermute_b32 v74, v105, v72
	s_waitcnt lgkmcnt(0)
	v_pk_add_f32 v[72:73], v[72:73], v[74:75]
	ds_bpermute_b32 v75, v225, v73
	ds_bpermute_b32 v74, v225, v72
	s_waitcnt lgkmcnt(0)
	v_pk_add_f32 v[72:73], v[72:73], v[74:75]
	ds_bpermute_b32 v75, v226, v73
	ds_bpermute_b32 v74, v226, v72
	s_waitcnt lgkmcnt(0)
	v_pk_add_f32 v[72:73], v[72:73], v[74:75]
	s_nop 0
	v_pk_fma_f32 v[72:73], v[72:73], s[2:3], v[142:143] op_sel_hi:[1,0,0]
	s_nop 0
	v_mul_f32_e32 v74, 0x4b800000, v73
	v_cmp_gt_f32_e32 vcc, s68, v73
	s_nop 1
	v_cndmask_b32_e32 v73, v73, v74, vcc
	v_rsq_f32_e32 v73, v73
	v_lshlrev_b64 v[74:75], 12, v[132:133]
	v_lshl_add_u64 v[74:75], v[112:113], 0, v[74:75]
	v_mul_f32_e32 v76, 0x45800000, v73
	v_cndmask_b32_e32 v76, v73, v76, vcc
	v_pk_mul_f32 v[22:23], v[22:23], v[76:77] op_sel_hi:[1,0]
	v_pk_mul_f32 v[20:21], v[20:21], v[76:77] op_sel_hi:[1,0]
	s_waitcnt vmcnt(8) lgkmcnt(0)
	v_pk_fma_f32 v[46:47], v[34:35], v[22:23], v[46:47]
	v_pk_fma_f32 v[44:45], v[32:33], v[20:21], v[44:45]
	flat_store_dwordx4 v[74:75], v[44:47]
	ds_read_b128 v[20:23], v210 offset:1024
	ds_read_b128 v[32:35], v210 offset:5120
	v_pk_mul_f32 v[18:19], v[18:19], v[76:77] op_sel_hi:[1,0]
	v_pk_mul_f32 v[16:17], v[16:17], v[76:77] op_sel_hi:[1,0]
	v_pk_mul_f32 v[6:7], v[6:7], v[76:77] op_sel_hi:[1,0]
	v_pk_mul_f32 v[4:5], v[4:5], v[76:77] op_sel_hi:[1,0]
	v_pk_mul_f32 v[2:3], v[2:3], v[76:77] op_sel_hi:[1,0]
	v_pk_mul_f32 v[0:1], v[0:1], v[76:77] op_sel_hi:[1,0]
	v_mul_f32_e32 v73, 0x4b800000, v72
	v_cmp_gt_f32_e32 vcc, s68, v72
	s_waitcnt vmcnt(9) lgkmcnt(0)
	v_pk_fma_f32 v[32:33], v[20:21], v[16:17], v[32:33]
	v_pk_fma_f32 v[34:35], v[22:23], v[18:19], v[34:35]
	flat_store_dwordx4 v[74:75], v[32:35] offset:1024
	ds_read_b128 v[16:19], v210 offset:2048
	ds_read_b128 v[20:23], v210 offset:6144
	v_cndmask_b32_e32 v72, v72, v73, vcc
	s_waitcnt vmcnt(10) lgkmcnt(0)
	v_pk_fma_f32 v[20:21], v[16:17], v[4:5], v[20:21]
	v_pk_fma_f32 v[22:23], v[18:19], v[6:7], v[22:23]
	flat_store_dwordx4 v[74:75], v[20:23] offset:2048
	ds_read_b128 v[4:7], v210 offset:3072
	ds_read_b128 v[16:19], v210 offset:7168
	s_waitcnt vmcnt(11) lgkmcnt(0)
	v_pk_fma_f32 v[16:17], v[4:5], v[0:1], v[16:17]
	v_pk_fma_f32 v[18:19], v[6:7], v[2:3], v[18:19]
	flat_store_dwordx4 v[74:75], v[16:19] offset:3072
	ds_read_b128 v[0:3], v210
	ds_read_b128 v[4:7], v210 offset:4096
	v_rsq_f32_e32 v74, v72
	v_lshl_add_u64 v[72:73], v[112:113], 0, v[134:135]
	v_mul_f32_e32 v75, 0x45800000, v74
	v_cndmask_b32_e32 v74, v74, v75, vcc
	v_pk_mul_f32 v[14:15], v[14:15], v[74:75] op_sel_hi:[1,0]
	v_pk_mul_f32 v[12:13], v[12:13], v[74:75] op_sel_hi:[1,0]
	v_pk_mul_f32 v[76:77], v[8:9], v[74:75] op_sel_hi:[1,0]
	v_pk_mul_f32 v[8:9], v[10:11], v[74:75] op_sel_hi:[1,0]
	v_pk_mul_f32 v[70:71], v[70:71], v[74:75] op_sel_hi:[1,0]
	v_pk_mul_f32 v[68:69], v[68:69], v[74:75] op_sel_hi:[1,0]
	v_pk_mul_f32 v[66:67], v[66:67], v[74:75] op_sel_hi:[1,0]
	v_pk_mul_f32 v[64:65], v[64:65], v[74:75] op_sel_hi:[1,0]
	s_andn2_b64 vcc, exec, s[4:5]
	s_waitcnt vmcnt(12) lgkmcnt(0)
	v_pk_fma_f32 v[12:13], v[0:1], v[12:13], v[4:5]
	v_pk_fma_f32 v[14:15], v[2:3], v[14:15], v[6:7]
	flat_store_dwordx4 v[72:73], v[12:15]
	ds_read_b128 v[0:3], v210 offset:1024
	ds_read_b128 v[4:7], v210 offset:5120
	s_waitcnt vmcnt(13) lgkmcnt(0)
	v_pk_fma_f32 v[8:9], v[0:1], v[8:9], v[4:5]
	v_pk_fma_f32 v[10:11], v[2:3], v[76:77], v[6:7]
	flat_store_dwordx4 v[72:73], v[8:11] offset:1024
	ds_read_b128 v[0:3], v210 offset:2048
	ds_read_b128 v[4:7], v210 offset:6144
	s_waitcnt vmcnt(14) lgkmcnt(0)
	v_pk_fma_f32 v[4:5], v[0:1], v[68:69], v[4:5]
	v_pk_fma_f32 v[6:7], v[2:3], v[70:71], v[6:7]
	flat_store_dwordx4 v[72:73], v[4:7] offset:2048
	ds_read_b128 v[0:3], v210 offset:3072
	ds_read_b128 v[68:71], v210 offset:7168
	s_waitcnt vmcnt(15) lgkmcnt(0)
	v_pk_fma_f32 v[0:1], v[0:1], v[64:65], v[68:69]
	v_pk_fma_f32 v[2:3], v[2:3], v[66:67], v[70:71]
	flat_store_dwordx4 v[72:73], v[0:3] offset:3072
	s_cbranch_vccnz .LBB0_179
	v_mad_u64_u32 v[70:71], s[4:5], v126, s7, 0
	v_mad_i32_i24 v71, v127, s7, v71
	v_mad_u64_u32 v[68:69], s[4:5], v128, s7, 0
	v_mad_u64_u32 v[66:67], s[4:5], v130, s7, 0
	v_mad_u64_u32 v[64:65], s[4:5], v136, s7, 0
	v_lshl_add_u64 v[70:71], s[60:61], 0, v[70:71]
	s_mov_b64 s[4:5], 0x3000
	s_mov_b64 s[8:9], 0x4000
	v_lshl_add_u64 v[72:73], v[70:71], 0, s[4:5]
	v_lshl_add_u64 v[70:71], v[70:71], 0, s[8:9]
	v_lshl_add_u64 v[74:75], v[72:73], 0, v[152:153]
	v_lshl_add_u64 v[78:79], v[70:71], 0, v[152:153]
	flat_load_dwordx4 v[74:77], v[74:75]
	v_mad_i32_i24 v69, v129, s7, v69
	flat_load_dwordx4 v[78:81], v[78:79]
	v_mad_i32_i24 v67, v131, s7, v67
	v_mad_i32_i24 v65, v137, s7, v65
	s_waitcnt vmcnt(0) lgkmcnt(0)
	v_pk_add_f32 v[80:81], v[80:81], 1.0 op_sel_hi:[1,0]
	v_pk_add_f32 v[78:79], v[78:79], 1.0 op_sel_hi:[1,0]
	v_pk_fma_f32 v[62:63], v[62:63], v[80:81], v[76:77]
	v_pk_fma_f32 v[60:61], v[60:61], v[78:79], v[74:75]
	s_nop 0
	v_cvt_pk_bf16_f32 v60, v60, v61
	v_cvt_pk_bf16_f32 v61, v62, v63
	flat_store_dwordx2 v[118:119], v[60:61]
	v_lshlrev_b32_e32 v60, 2, v100
	v_mov_b32_e32 v61, v153
	v_lshl_add_u64 v[62:63], v[72:73], 0, v[60:61]
	flat_load_dwordx4 v[74:77], v[62:63]
	v_lshl_add_u64 v[62:63], v[70:71], 0, v[60:61]
	flat_load_dwordx4 v[78:81], v[62:63]
	s_waitcnt vmcnt(0) lgkmcnt(0)
	v_pk_add_f32 v[62:63], v[80:81], 1.0 op_sel_hi:[1,0]
	v_pk_add_f32 v[78:79], v[78:79], 1.0 op_sel_hi:[1,0]
	v_pk_fma_f32 v[58:59], v[58:59], v[62:63], v[76:77]
	v_pk_fma_f32 v[56:57], v[56:57], v[78:79], v[74:75]
	s_nop 0
	v_cvt_pk_bf16_f32 v56, v56, v57
	v_cvt_pk_bf16_f32 v57, v58, v59
	flat_store_dwordx2 v[118:119], v[56:57] offset:512
	v_lshlrev_b32_e32 v56, 2, v102
	v_mov_b32_e32 v57, v153
	v_lshl_add_u64 v[58:59], v[72:73], 0, v[56:57]
	flat_load_dwordx4 v[74:77], v[58:59]
	v_lshl_add_u64 v[58:59], v[70:71], 0, v[56:57]
	flat_load_dwordx4 v[78:81], v[58:59]
	s_waitcnt vmcnt(0) lgkmcnt(0)
	v_pk_add_f32 v[58:59], v[80:81], 1.0 op_sel_hi:[1,0]
	v_pk_add_f32 v[62:63], v[78:79], 1.0 op_sel_hi:[1,0]
	v_pk_fma_f32 v[50:51], v[50:51], v[58:59], v[76:77]
	v_pk_fma_f32 v[48:49], v[48:49], v[62:63], v[74:75]
	s_nop 0
	v_cvt_pk_bf16_f32 v48, v48, v49
	v_cvt_pk_bf16_f32 v49, v50, v51
	flat_store_dwordx2 v[118:119], v[48:49] offset:1024
	v_lshlrev_b32_e32 v48, 2, v104
	v_mov_b32_e32 v49, v153
	v_lshl_add_u64 v[50:51], v[72:73], 0, v[48:49]
	flat_load_dwordx4 v[72:75], v[50:51]
	v_lshl_add_u64 v[50:51], v[70:71], 0, v[48:49]
	flat_load_dwordx4 v[76:79], v[50:51]
	s_waitcnt vmcnt(0) lgkmcnt(0)
	v_pk_add_f32 v[50:51], v[78:79], 1.0 op_sel_hi:[1,0]
	v_pk_add_f32 v[58:59], v[76:77], 1.0 op_sel_hi:[1,0]
	v_pk_fma_f32 v[38:39], v[38:39], v[50:51], v[74:75]
	v_pk_fma_f32 v[36:37], v[36:37], v[58:59], v[72:73]
	v_lshlrev_b64 v[50:51], 11, v[124:125]
	v_cvt_pk_bf16_f32 v36, v36, v37
	v_cvt_pk_bf16_f32 v37, v38, v39
	flat_store_dwordx2 v[118:119], v[36:37] offset:1536
	v_lshl_add_u64 v[36:37], s[60:61], 0, v[68:69]
	v_lshl_add_u64 v[38:39], v[36:37], 0, s[4:5]
	v_lshl_add_u64 v[36:37], v[36:37], 0, s[8:9]
	v_lshl_add_u64 v[58:59], v[38:39], 0, v[152:153]
	flat_load_dwordx4 v[68:71], v[58:59]
	v_lshl_add_u64 v[58:59], v[36:37], 0, v[152:153]
	flat_load_dwordx4 v[72:75], v[58:59]
	v_lshl_add_u64 v[50:51], v[114:115], 0, v[50:51]
	s_waitcnt vmcnt(0) lgkmcnt(0)
	v_pk_add_f32 v[58:59], v[74:75], 1.0 op_sel_hi:[1,0]
	v_pk_add_f32 v[62:63], v[72:73], 1.0 op_sel_hi:[1,0]
	v_pk_fma_f32 v[26:27], v[26:27], v[58:59], v[70:71]
	v_pk_fma_f32 v[24:25], v[24:25], v[62:63], v[68:69]
	v_lshl_add_u64 v[58:59], v[36:37], 0, v[60:61]
	v_cvt_pk_bf16_f32 v24, v24, v25
	v_cvt_pk_bf16_f32 v25, v26, v27
	flat_store_dwordx2 v[50:51], v[24:25]
	v_lshl_add_u64 v[24:25], v[38:39], 0, v[60:61]
	flat_load_dwordx4 v[24:27], v[24:25]
	s_nop 0
	flat_load_dwordx4 v[68:71], v[58:59]
	s_waitcnt vmcnt(0) lgkmcnt(0)
	v_pk_add_f32 v[58:59], v[70:71], 1.0 op_sel_hi:[1,0]
	v_pk_add_f32 v[62:63], v[68:69], 1.0 op_sel_hi:[1,0]
	v_pk_fma_f32 v[26:27], v[30:31], v[58:59], v[26:27]
	v_pk_fma_f32 v[24:25], v[28:29], v[62:63], v[24:25]
	v_lshl_add_u64 v[28:29], v[36:37], 0, v[56:57]
	v_cvt_pk_bf16_f32 v24, v24, v25
	v_cvt_pk_bf16_f32 v25, v26, v27
	flat_store_dwordx2 v[50:51], v[24:25] offset:512
	v_lshl_add_u64 v[24:25], v[38:39], 0, v[56:57]
	flat_load_dwordx4 v[24:27], v[24:25]
	s_nop 0
	flat_load_dwordx4 v[28:31], v[28:29]
	s_waitcnt vmcnt(0) lgkmcnt(0)
	v_pk_add_f32 v[30:31], v[30:31], 1.0 op_sel_hi:[1,0]
	v_pk_add_f32 v[28:29], v[28:29], 1.0 op_sel_hi:[1,0]
	v_pk_fma_f32 v[26:27], v[42:43], v[30:31], v[26:27]
	v_pk_fma_f32 v[24:25], v[40:41], v[28:29], v[24:25]
	v_lshl_add_u64 v[28:29], v[36:37], 0, v[48:49]
	v_cvt_pk_bf16_f32 v24, v24, v25
	v_cvt_pk_bf16_f32 v25, v26, v27
	flat_store_dwordx2 v[50:51], v[24:25] offset:1024
	v_lshl_add_u64 v[24:25], v[38:39], 0, v[48:49]
	flat_load_dwordx4 v[24:27], v[24:25]
	s_nop 0
	flat_load_dwordx4 v[28:31], v[28:29]
	s_waitcnt vmcnt(0) lgkmcnt(0)
	v_pk_add_f32 v[30:31], v[30:31], 1.0 op_sel_hi:[1,0]
	v_pk_add_f32 v[28:29], v[28:29], 1.0 op_sel_hi:[1,0]
	v_pk_fma_f32 v[26:27], v[54:55], v[30:31], v[26:27]
	v_pk_fma_f32 v[24:25], v[52:53], v[28:29], v[24:25]
	v_lshlrev_b64 v[30:31], 11, v[122:123]
	v_cvt_pk_bf16_f32 v24, v24, v25
	v_cvt_pk_bf16_f32 v25, v26, v27
	flat_store_dwordx2 v[50:51], v[24:25] offset:1536
	v_lshl_add_u64 v[24:25], s[60:61], 0, v[66:67]
	v_lshl_add_u64 v[40:41], v[24:25], 0, s[4:5]
	v_lshl_add_u64 v[24:25], v[24:25], 0, s[8:9]
	v_lshl_add_u64 v[26:27], v[40:41], 0, v[152:153]
	v_lshl_add_u64 v[36:37], v[24:25], 0, v[152:153]
	flat_load_dwordx4 v[26:29], v[26:27]
	v_lshl_add_u64 v[42:43], v[114:115], 0, v[30:31]
	flat_load_dwordx4 v[36:39], v[36:37]
	v_lshl_add_u64 v[30:31], v[24:25], 0, v[60:61]
	s_waitcnt vmcnt(0) lgkmcnt(0)
	v_pk_add_f32 v[38:39], v[38:39], 1.0 op_sel_hi:[1,0]
	v_pk_add_f32 v[36:37], v[36:37], 1.0 op_sel_hi:[1,0]
	v_pk_fma_f32 v[28:29], v[46:47], v[38:39], v[28:29]
	v_pk_fma_f32 v[26:27], v[44:45], v[36:37], v[26:27]
	s_nop 0
	v_cvt_pk_bf16_f32 v26, v26, v27
	v_cvt_pk_bf16_f32 v27, v28, v29
	flat_store_dwordx2 v[42:43], v[26:27]
	v_lshl_add_u64 v[26:27], v[40:41], 0, v[60:61]
	flat_load_dwordx4 v[26:29], v[26:27]
	s_nop 0
	flat_load_dwordx4 v[36:39], v[30:31]
	s_waitcnt vmcnt(0) lgkmcnt(0)
	v_pk_add_f32 v[30:31], v[38:39], 1.0 op_sel_hi:[1,0]
	v_pk_add_f32 v[36:37], v[36:37], 1.0 op_sel_hi:[1,0]
	v_pk_fma_f32 v[28:29], v[34:35], v[30:31], v[28:29]
	v_pk_fma_f32 v[26:27], v[32:33], v[36:37], v[26:27]
	v_lshl_add_u64 v[30:31], v[24:25], 0, v[56:57]
	v_cvt_pk_bf16_f32 v26, v26, v27
	v_cvt_pk_bf16_f32 v27, v28, v29
	flat_store_dwordx2 v[42:43], v[26:27] offset:512
	v_lshl_add_u64 v[26:27], v[40:41], 0, v[56:57]
	flat_load_dwordx4 v[26:29], v[26:27]
	v_lshl_add_u64 v[24:25], v[24:25], 0, v[48:49]
	flat_load_dwordx4 v[30:33], v[30:31]
	s_waitcnt vmcnt(0) lgkmcnt(0)
	v_pk_add_f32 v[32:33], v[32:33], 1.0 op_sel_hi:[1,0]
	v_pk_add_f32 v[30:31], v[30:31], 1.0 op_sel_hi:[1,0]
	v_pk_fma_f32 v[22:23], v[22:23], v[32:33], v[28:29]
	v_pk_fma_f32 v[20:21], v[20:21], v[30:31], v[26:27]
	v_lshlrev_b64 v[28:29], 11, v[120:121]
	v_cvt_pk_bf16_f32 v20, v20, v21
	v_cvt_pk_bf16_f32 v21, v22, v23
	flat_store_dwordx2 v[42:43], v[20:21] offset:1024
	v_lshl_add_u64 v[20:21], v[40:41], 0, v[48:49]
	flat_load_dwordx4 v[20:23], v[20:21]
	s_nop 0
	flat_load_dwordx4 v[24:27], v[24:25]
	s_waitcnt vmcnt(0) lgkmcnt(0)
	v_pk_add_f32 v[26:27], v[26:27], 1.0 op_sel_hi:[1,0]
	v_pk_add_f32 v[24:25], v[24:25], 1.0 op_sel_hi:[1,0]
	v_pk_fma_f32 v[18:19], v[18:19], v[26:27], v[22:23]
	v_pk_fma_f32 v[16:17], v[16:17], v[24:25], v[20:21]
	s_nop 0
	v_cvt_pk_bf16_f32 v16, v16, v17
	v_cvt_pk_bf16_f32 v17, v18, v19
	flat_store_dwordx2 v[42:43], v[16:17] offset:1536
	v_lshl_add_u64 v[16:17], s[60:61], 0, v[64:65]
	v_lshl_add_u64 v[26:27], v[16:17], 0, s[4:5]
	v_lshl_add_u64 v[16:17], v[16:17], 0, s[8:9]
	v_lshl_add_u64 v[18:19], v[26:27], 0, v[152:153]
	v_lshl_add_u64 v[22:23], v[16:17], 0, v[152:153]
	flat_load_dwordx4 v[18:21], v[18:19]
	s_nop 0
	flat_load_dwordx4 v[22:25], v[22:23]
	s_waitcnt vmcnt(0) lgkmcnt(0)
	v_pk_add_f32 v[24:25], v[24:25], 1.0 op_sel_hi:[1,0]
	v_pk_add_f32 v[22:23], v[22:23], 1.0 op_sel_hi:[1,0]
	v_pk_fma_f32 v[14:15], v[14:15], v[24:25], v[20:21]
	v_pk_fma_f32 v[12:13], v[12:13], v[22:23], v[18:19]
	v_lshl_add_u64 v[22:23], v[114:115], 0, v[28:29]
	v_cvt_pk_bf16_f32 v12, v12, v13
	v_cvt_pk_bf16_f32 v13, v14, v15
	flat_store_dwordx2 v[22:23], v[12:13]
	v_lshl_add_u64 v[12:13], v[26:27], 0, v[60:61]
	v_lshl_add_u64 v[18:19], v[16:17], 0, v[60:61]
	flat_load_dwordx4 v[12:15], v[12:13]
	s_nop 0
	flat_load_dwordx4 v[18:21], v[18:19]
	s_waitcnt vmcnt(0) lgkmcnt(0)
	v_pk_add_f32 v[20:21], v[20:21], 1.0 op_sel_hi:[1,0]
	v_pk_add_f32 v[18:19], v[18:19], 1.0 op_sel_hi:[1,0]
	v_pk_fma_f32 v[10:11], v[10:11], v[20:21], v[14:15]
	v_pk_fma_f32 v[8:9], v[8:9], v[18:19], v[12:13]
	v_lshl_add_u64 v[12:13], v[16:17], 0, v[56:57]
	v_cvt_pk_bf16_f32 v8, v8, v9
	v_cvt_pk_bf16_f32 v9, v10, v11
	flat_store_dwordx2 v[22:23], v[8:9] offset:512
	v_lshl_add_u64 v[8:9], v[26:27], 0, v[56:57]
	flat_load_dwordx4 v[8:11], v[8:9]
	s_nop 0
	flat_load_dwordx4 v[12:15], v[12:13]
	s_waitcnt vmcnt(0) lgkmcnt(0)
	v_pk_add_f32 v[14:15], v[14:15], 1.0 op_sel_hi:[1,0]
	v_pk_add_f32 v[12:13], v[12:13], 1.0 op_sel_hi:[1,0]
	v_pk_fma_f32 v[6:7], v[6:7], v[14:15], v[10:11]
	v_pk_fma_f32 v[4:5], v[4:5], v[12:13], v[8:9]
	v_lshl_add_u64 v[8:9], v[16:17], 0, v[48:49]
	v_cvt_pk_bf16_f32 v4, v4, v5
	v_cvt_pk_bf16_f32 v5, v6, v7
	flat_store_dwordx2 v[22:23], v[4:5] offset:1024
	v_lshl_add_u64 v[4:5], v[26:27], 0, v[48:49]
	flat_load_dwordx4 v[4:7], v[4:5]
	s_nop 0
	flat_load_dwordx4 v[8:11], v[8:9]
	s_waitcnt vmcnt(0) lgkmcnt(0)
	v_pk_add_f32 v[10:11], v[10:11], 1.0 op_sel_hi:[1,0]
	v_pk_add_f32 v[8:9], v[8:9], 1.0 op_sel_hi:[1,0]
	v_pk_fma_f32 v[2:3], v[2:3], v[10:11], v[6:7]
	v_pk_fma_f32 v[0:1], v[0:1], v[8:9], v[4:5]
	s_nop 0
	v_cvt_pk_bf16_f32 v0, v0, v1
	v_cvt_pk_bf16_f32 v1, v2, v3
	flat_store_dwordx2 v[22:23], v[0:1] offset:1536
	s_branch .LBB0_179

.LBB0_225:
	global_load_dwordx4 v[154:157], v[74:75], off
	global_load_dwordx4 v[158:161], v[76:77], off
	global_load_dwordx4 v[162:165], v[74:75], off offset:1024
	global_load_dwordx4 v[166:169], v[76:77], off offset:1024
	global_load_dwordx4 v[170:173], v[74:75], off offset:2048
	global_load_dwordx4 v[174:177], v[76:77], off offset:2048
	global_load_dwordx4 v[178:181], v[74:75], off offset:3072
	global_load_dwordx4 v[182:185], v[76:77], off offset:3072
	v_add_u32_e32 v0, 0xfffff000, v64
	v_ashrrev_i32_e32 v0, 10, v0
	v_add_u32_e32 v0, 1, v0
	v_cmp_lt_i32_e32 vcc, s33, v64
	global_load_dwordx4 v[186:189], v[86:87], off offset:1024
	global_load_dwordx4 v[186:189], v[86:87], off offset:2048
	global_load_dwordx4 v[186:189], v[86:87], off offset:3072
	flat_load_dwordx4 v[8:11], v[86:87]
	s_mov_b64 s[8:9], 0x1000000
	v_cndmask_b32_e32 v94, 0, v0, vcc
	v_add_u32_e32 v0, s38, v64
	v_cmp_lt_i32_e32 vcc, s6, v0
	v_ashrrev_i32_e32 v95, 31, v94
	v_lshl_add_u64 v[4:5], v[94:95], 0, s[28:29]
	v_cndmask_b32_e32 v0, v0, v64, vcc
	v_add_u32_e32 v1, 0xfffff000, v0
	v_ashrrev_i32_e32 v1, 10, v1
	v_add_u32_e32 v1, 1, v1
	v_cmp_lt_i32_e32 vcc, s33, v0
	v_mad_u64_u32 v[2:3], s[4:5], v4, s7, v[78:79]
	s_nop 0
	v_cndmask_b32_e32 v92, 0, v1, vcc
	v_add_u32_e32 v1, s35, v64
	v_cmp_lt_i32_e32 vcc, s6, v1
	s_mov_b32 s4, 0x1000000
	v_mad_i32_i24 v3, v5, s7, v3
	v_cndmask_b32_e32 v18, v1, v64, vcc
	v_add_u32_e32 v1, 0xfffff000, v18
	v_ashrrev_i32_e32 v1, 10, v1
	v_add_u32_e32 v1, 1, v1
	v_cmp_lt_i32_e32 vcc, s33, v18
	global_load_dwordx4 v[186:189], v[2:3], off offset:1024
	global_load_dwordx4 v[186:189], v[2:3], off offset:2048
	global_load_dwordx4 v[186:189], v[2:3], off offset:3072
	flat_load_dwordx4 v[12:15], v[2:3]
	v_ashrrev_i32_e32 v93, 31, v92
	v_cndmask_b32_e32 v90, 0, v1, vcc
	v_add_u32_e32 v1, s26, v64
	v_cmp_lt_i32_e32 vcc, s6, v1
	v_lshlrev_b32_e32 v152, 1, v66
	v_lshlrev_b32_e32 v42, 1, v68
	v_cndmask_b32_e32 v16, v1, v64, vcc
	v_add_u32_e32 v1, 0xfffff000, v16
	v_ashrrev_i32_e32 v1, 10, v1
	v_add_u32_e32 v1, 1, v1
	v_cmp_lt_i32_e32 vcc, s33, v16
	v_mov_b32_e32 v43, v153
	v_lshlrev_b32_e32 v104, 1, v70
	v_cndmask_b32_e32 v88, 0, v1, vcc
	v_add_co_u32_e32 v4, vcc, s4, v84
	s_brev_b32 s4, 64
	s_nop 0
	v_addc_co_u32_e32 v5, vcc, 0, v85, vcc
	global_load_dwordx2 v[186:187], v[4:5], off offset:512
	global_load_dwordx2 v[186:187], v[4:5], off offset:1024
	global_load_dwordx2 v[186:187], v[4:5], off offset:1536
	flat_load_dwordx2 v[6:7], v[4:5]
	v_mov_b32_e32 v105, v153
	v_lshlrev_b32_e32 v106, 1, v72
	v_mov_b32_e32 v107, v153
	v_ashrrev_i32_e32 v19, 31, v18
	v_ashrrev_i32_e32 v91, 31, v90
	v_lshlrev_b64 v[100:101], 11, v[18:19]
	v_ashrrev_i32_e32 v17, 31, v16
	v_ashrrev_i32_e32 v89, 31, v88
	s_waitcnt vmcnt(0) lgkmcnt(0)
	v_pk_mul_f32 v[14:15], v[14:15], 0.5 op_sel_hi:[1,0]
	v_pk_mul_f32 v[12:13], v[12:13], 0.5 op_sel_hi:[1,0]
	v_lshlrev_b32_e32 v20, 16, v6
	v_and_b32_e32 v21, 0xffff0000, v6
	v_add_co_u32_e32 v6, vcc, s4, v84
	v_lshlrev_b32_e32 v22, 16, v7
	v_and_b32_e32 v23, 0xffff0000, v7
	v_addc_co_u32_e32 v7, vcc, 0, v85, vcc
	flat_load_dwordx2 v[24:25], v[6:7]
	s_waitcnt vmcnt(0) lgkmcnt(0)
	v_lshlrev_b32_e32 v26, 16, v24
	v_and_b32_e32 v27, 0xffff0000, v24
	v_lshlrev_b32_e32 v24, 16, v25
	v_and_b32_e32 v25, 0xffff0000, v25
	v_pk_add_f32 v[20:21], v[20:21], v[26:27]
	v_pk_add_f32 v[22:23], v[22:23], v[24:25]
	v_pk_mul_f32 v[12:13], v[12:13], v[20:21]
	v_pk_mul_f32 v[14:15], v[14:15], v[22:23]
	v_pk_fma_f32 v[8:9], v[8:9], s[42:43], v[12:13] op_sel_hi:[1,0,1]
	v_pk_fma_f32 v[10:11], v[10:11], s[42:43], v[14:15] op_sel_hi:[1,0,1]
	v_mov_b32_e32 v14, v8
	v_pk_mov_b32 v[12:13], v[8:9], v[10:11] op_sel:[1,0]
	v_mov_b32_e32 v15, v11
	v_pk_add_f32 v[12:13], v[12:13], v[14:15]
	s_nop 0
	v_add_f32_e32 v1, v12, v13
	flat_load_dwordx4 v[12:15], v[86:87] offset:1024
	flat_load_dwordx4 v[20:23], v[2:3] offset:1024
	flat_load_dwordx2 v[24:25], v[4:5] offset:512
	flat_load_dwordx2 v[30:31], v[6:7] offset:512
	v_add_f32_e32 v28, 0, v1
	v_ashrrev_i32_e32 v1, 31, v0
	v_lshlrev_b64 v[96:97], 11, v[0:1]
	s_waitcnt vmcnt(0) lgkmcnt(0)
	v_pk_mul_f32 v[22:23], v[22:23], 0.5 op_sel_hi:[1,0]
	v_lshlrev_b32_e32 v26, 16, v24
	v_and_b32_e32 v27, 0xffff0000, v24
	v_lshlrev_b32_e32 v24, 16, v25
	v_and_b32_e32 v25, 0xffff0000, v25
	v_lshlrev_b32_e32 v32, 16, v30
	v_and_b32_e32 v33, 0xffff0000, v30
	v_lshlrev_b32_e32 v30, 16, v31
	v_and_b32_e32 v31, 0xffff0000, v31
	v_pk_mul_f32 v[20:21], v[20:21], 0.5 op_sel_hi:[1,0]
	v_pk_add_f32 v[26:27], v[26:27], v[32:33]
	v_pk_add_f32 v[24:25], v[24:25], v[30:31]
	v_pk_mul_f32 v[20:21], v[20:21], v[26:27]
	v_pk_mul_f32 v[22:23], v[22:23], v[24:25]
	v_pk_fma_f32 v[12:13], v[12:13], s[42:43], v[20:21] op_sel_hi:[1,0,1]
	v_pk_fma_f32 v[14:15], v[14:15], s[42:43], v[22:23] op_sel_hi:[1,0,1]
	v_mov_b32_e32 v22, v12
	v_pk_mov_b32 v[20:21], v[12:13], v[14:15] op_sel:[1,0]
	v_mov_b32_e32 v23, v15
	v_pk_add_f32 v[20:21], v[20:21], v[22:23]
	s_nop 0
	v_pk_add_f32 v[30:31], v[20:21], v[20:21] op_sel:[0,1] op_sel_hi:[1,0]
	flat_load_dwordx4 v[20:23], v[86:87] offset:2048
	flat_load_dwordx4 v[24:27], v[2:3] offset:2048
	flat_load_dwordx2 v[32:33], v[4:5] offset:1024
	flat_load_dwordx2 v[36:37], v[6:7] offset:1024
	s_waitcnt vmcnt(0) lgkmcnt(0)
	v_pk_mul_f32 v[26:27], v[26:27], 0.5 op_sel_hi:[1,0]
	v_lshlrev_b32_e32 v34, 16, v32
	v_and_b32_e32 v35, 0xffff0000, v32
	v_lshlrev_b32_e32 v32, 16, v33
	v_and_b32_e32 v33, 0xffff0000, v33
	v_lshlrev_b32_e32 v38, 16, v36
	v_and_b32_e32 v39, 0xffff0000, v36
	v_lshlrev_b32_e32 v36, 16, v37
	v_and_b32_e32 v37, 0xffff0000, v37
	v_pk_mul_f32 v[24:25], v[24:25], 0.5 op_sel_hi:[1,0]
	v_pk_add_f32 v[32:33], v[32:33], v[36:37]
	v_pk_add_f32 v[34:35], v[34:35], v[38:39]
	v_pk_mul_f32 v[26:27], v[26:27], v[32:33]
	v_pk_mul_f32 v[24:25], v[24:25], v[34:35]
	v_pk_fma_f32 v[22:23], v[22:23], s[42:43], v[26:27] op_sel_hi:[1,0,1]
	v_pk_fma_f32 v[20:21], v[20:21], s[42:43], v[24:25] op_sel_hi:[1,0,1]
	flat_load_dwordx4 v[24:27], v[86:87] offset:3072
	flat_load_dwordx4 v[32:35], v[2:3] offset:3072
	s_nop 0
	flat_load_dwordx2 v[2:3], v[4:5] offset:1536
	v_add_f32_e32 v36, v20, v21
	flat_load_dwordx2 v[6:7], v[6:7] offset:1536
	v_add_f32_e32 v38, v22, v23
	s_waitcnt vmcnt(0) lgkmcnt(0)
	v_pk_mul_f32 v[34:35], v[34:35], 0.5 op_sel_hi:[1,0]
	v_lshlrev_b32_e32 v4, 16, v2
	v_and_b32_e32 v5, 0xffff0000, v2
	v_lshlrev_b32_e32 v2, 16, v3
	v_and_b32_e32 v3, 0xffff0000, v3
	v_lshlrev_b32_e32 v40, 16, v6
	v_and_b32_e32 v41, 0xffff0000, v6
	v_lshlrev_b32_e32 v6, 16, v7
	v_and_b32_e32 v7, 0xffff0000, v7
	v_pk_mul_f32 v[32:33], v[32:33], 0.5 op_sel_hi:[1,0]
	v_pk_add_f32 v[2:3], v[2:3], v[6:7]
	v_pk_add_f32 v[4:5], v[4:5], v[40:41]
	v_pk_mul_f32 v[2:3], v[34:35], v[2:3]
	v_pk_mul_f32 v[4:5], v[32:33], v[4:5]
	v_pk_fma_f32 v[26:27], v[26:27], s[42:43], v[2:3] op_sel_hi:[1,0,1]
	v_pk_fma_f32 v[24:25], v[24:25], s[42:43], v[4:5] op_sel_hi:[1,0,1]
	v_mov_b32_e32 v37, v26
	v_mov_b32_e32 v29, v24
	v_mov_b32_e32 v31, v25
	v_mov_b32_e32 v39, v27
	v_lshl_add_u64 v[34:35], s[56:57], 0, v[96:97]
	v_pk_add_f32 v[2:3], v[28:29], v[30:31]
	v_pk_add_f32 v[4:5], v[36:37], v[38:39]
	v_lshl_add_u64 v[6:7], v[92:93], 0, s[28:29]
	v_lshl_add_u64 v[46:47], v[34:35], 0, s[8:9]
	v_pk_add_f32 v[2:3], v[2:3], v[4:5]
	v_mad_u64_u32 v[4:5], s[4:5], v6, s7, v[78:79]
	v_lshl_add_u64 v[48:49], v[34:35], 0, v[152:153]
	v_lshl_add_u64 v[36:37], v[46:47], 0, v[152:153]
	v_mad_i32_i24 v5, v7, s7, v5
	global_load_dwordx2 v[186:187], v[48:49], off offset:512
	global_load_dwordx2 v[186:187], v[48:49], off offset:1024
	global_load_dwordx2 v[186:187], v[48:49], off offset:1536
	flat_load_dwordx2 v[6:7], v[48:49]
	v_add_f32_e32 v120, v2, v3
	global_load_dwordx2 v[186:187], v[36:37], off offset:512
	global_load_dwordx2 v[186:187], v[36:37], off offset:1024
	global_load_dwordx2 v[186:187], v[36:37], off offset:1536
	flat_load_dwordx2 v[36:37], v[36:37]
	v_lshlrev_b64 v[2:3], 12, v[0:1]
	global_load_dwordx4 v[186:189], v[4:5], off offset:1024
	global_load_dwordx4 v[186:189], v[4:5], off offset:2048
	global_load_dwordx4 v[186:189], v[4:5], off offset:3072
	flat_load_dwordx4 v[28:31], v[4:5]
	v_lshl_add_u64 v[32:33], v[80:81], 0, v[2:3]
	global_load_dwordx4 v[186:189], v[32:33], off offset:1024
	global_load_dwordx4 v[186:189], v[32:33], off offset:2048
	global_load_dwordx4 v[186:189], v[32:33], off offset:3072
	flat_load_dwordx4 v[0:3], v[32:33]
	v_lshl_add_u64 v[44:45], v[46:47], 0, v[42:43]
	v_lshl_add_u64 v[52:53], v[46:47], 0, v[104:105]
	v_lshl_add_u64 v[46:47], v[46:47], 0, v[106:107]
	s_waitcnt vmcnt(0) lgkmcnt(0)
	v_lshlrev_b32_e32 v34, 16, v6
	v_and_b32_e32 v35, 0xffff0000, v6
	v_lshlrev_b32_e32 v6, 16, v7
	v_and_b32_e32 v7, 0xffff0000, v7
	v_lshlrev_b32_e32 v38, 16, v36
	v_and_b32_e32 v39, 0xffff0000, v36
	v_lshlrev_b32_e32 v36, 16, v37
	v_and_b32_e32 v37, 0xffff0000, v37
	v_pk_mul_f32 v[30:31], v[30:31], 0.5 op_sel_hi:[1,0]
	v_pk_mul_f32 v[28:29], v[28:29], 0.5 op_sel_hi:[1,0]
	v_pk_add_f32 v[34:35], v[34:35], v[38:39]
	v_pk_add_f32 v[6:7], v[6:7], v[36:37]
	v_pk_mul_f32 v[28:29], v[28:29], v[34:35]
	v_pk_mul_f32 v[6:7], v[30:31], v[6:7]
	v_pk_fma_f32 v[34:35], v[0:1], s[42:43], v[28:29] op_sel_hi:[1,0,1]
	v_pk_fma_f32 v[36:37], v[2:3], s[42:43], v[6:7] op_sel_hi:[1,0,1]
	v_mov_b32_e32 v2, v34
	v_pk_mov_b32 v[0:1], v[34:35], v[36:37] op_sel:[1,0]
	v_mov_b32_e32 v3, v37
	v_pk_add_f32 v[0:1], v[0:1], v[2:3]
	s_nop 0
	v_add_f32_e32 v0, v0, v1
	v_add_f32_e32 v40, 0, v0
	flat_load_dwordx4 v[0:3], v[32:33] offset:1024
	flat_load_dwordx4 v[28:31], v[4:5] offset:1024
	flat_load_dwordx2 v[6:7], v[48:49] offset:512
	s_waitcnt vmcnt(0) lgkmcnt(0)
	v_pk_mul_f32 v[30:31], v[30:31], 0.5 op_sel_hi:[1,0]
	flat_load_dwordx2 v[44:45], v[44:45]
	v_lshlrev_b32_e32 v38, 16, v6
	v_and_b32_e32 v39, 0xffff0000, v6
	v_lshlrev_b32_e32 v6, 16, v7
	v_and_b32_e32 v7, 0xffff0000, v7
	v_pk_mul_f32 v[28:29], v[28:29], 0.5 op_sel_hi:[1,0]
	s_waitcnt vmcnt(0) lgkmcnt(0)
	v_lshlrev_b32_e32 v50, 16, v44
	v_and_b32_e32 v51, 0xffff0000, v44
	v_lshlrev_b32_e32 v44, 16, v45
	v_and_b32_e32 v45, 0xffff0000, v45
	v_pk_add_f32 v[38:39], v[38:39], v[50:51]
	v_pk_add_f32 v[6:7], v[6:7], v[44:45]
	v_pk_mul_f32 v[28:29], v[28:29], v[38:39]
	v_pk_mul_f32 v[6:7], v[30:31], v[6:7]
	v_pk_fma_f32 v[38:39], v[0:1], s[42:43], v[28:29] op_sel_hi:[1,0,1]
	v_pk_fma_f32 v[60:61], v[2:3], s[42:43], v[6:7] op_sel_hi:[1,0,1]
	v_mov_b32_e32 v2, v38
	v_pk_mov_b32 v[0:1], v[38:39], v[60:61] op_sel:[1,0]
	v_mov_b32_e32 v3, v61
	v_pk_add_f32 v[0:1], v[0:1], v[2:3]
	s_nop 0
	v_pk_add_f32 v[44:45], v[0:1], v[0:1] op_sel:[0,1] op_sel_hi:[1,0]
	flat_load_dwordx4 v[0:3], v[32:33] offset:2048
	flat_load_dwordx4 v[28:31], v[4:5] offset:2048
	flat_load_dwordx2 v[6:7], v[48:49] offset:1024
	s_waitcnt vmcnt(0) lgkmcnt(0)
	v_pk_mul_f32 v[30:31], v[30:31], 0.5 op_sel_hi:[1,0]
	flat_load_dwordx2 v[52:53], v[52:53]
	v_lshlrev_b32_e32 v50, 16, v6
	v_and_b32_e32 v51, 0xffff0000, v6
	v_lshlrev_b32_e32 v6, 16, v7
	v_and_b32_e32 v7, 0xffff0000, v7
	v_pk_mul_f32 v[28:29], v[28:29], 0.5 op_sel_hi:[1,0]
	s_waitcnt vmcnt(0) lgkmcnt(0)
	v_lshlrev_b32_e32 v54, 16, v52
	v_and_b32_e32 v55, 0xffff0000, v52
	v_lshlrev_b32_e32 v52, 16, v53
	v_and_b32_e32 v53, 0xffff0000, v53
	v_pk_add_f32 v[6:7], v[6:7], v[52:53]
	v_pk_add_f32 v[50:51], v[50:51], v[54:55]
	v_pk_mul_f32 v[6:7], v[30:31], v[6:7]
	v_pk_mul_f32 v[28:29], v[28:29], v[50:51]
	v_pk_fma_f32 v[30:31], v[2:3], s[42:43], v[6:7] op_sel_hi:[1,0,1]
	v_pk_fma_f32 v[28:29], v[0:1], s[42:43], v[28:29] op_sel_hi:[1,0,1]
	flat_load_dwordx4 v[0:3], v[32:33] offset:3072
	s_nop 0
	flat_load_dwordx4 v[4:7], v[4:5] offset:3072
	s_nop 0
	flat_load_dwordx2 v[54:55], v[48:49] offset:1536
	v_add_f32_e32 v50, v28, v29
	flat_load_dwordx2 v[46:47], v[46:47]
	v_add_f32_e32 v52, v30, v31
	s_waitcnt vmcnt(0) lgkmcnt(0)
	v_pk_mul_f32 v[6:7], v[6:7], 0.5 op_sel_hi:[1,0]
	v_lshlrev_b32_e32 v48, 16, v54
	v_and_b32_e32 v49, 0xffff0000, v54
	v_lshlrev_b32_e32 v54, 16, v55
	v_and_b32_e32 v55, 0xffff0000, v55
	v_lshlrev_b32_e32 v56, 16, v46
	v_and_b32_e32 v57, 0xffff0000, v46
	v_lshlrev_b32_e32 v46, 16, v47
	v_and_b32_e32 v47, 0xffff0000, v47
	v_pk_mul_f32 v[4:5], v[4:5], 0.5 op_sel_hi:[1,0]
	v_pk_add_f32 v[46:47], v[54:55], v[46:47]
	v_pk_add_f32 v[48:49], v[48:49], v[56:57]
	v_pk_mul_f32 v[6:7], v[6:7], v[46:47]
	v_pk_mul_f32 v[4:5], v[4:5], v[48:49]
	v_pk_fma_f32 v[118:119], v[2:3], s[42:43], v[6:7] op_sel_hi:[1,0,1]
	v_pk_fma_f32 v[62:63], v[0:1], s[42:43], v[4:5] op_sel_hi:[1,0,1]
	v_mov_b32_e32 v51, v118
	v_mov_b32_e32 v41, v62
	v_mov_b32_e32 v45, v63
	v_mov_b32_e32 v53, v119
	v_pk_add_f32 v[0:1], v[40:41], v[44:45]
	v_pk_add_f32 v[2:3], v[50:51], v[52:53]
	v_lshl_add_u64 v[4:5], v[90:91], 0, s[28:29]
	v_pk_add_f32 v[0:1], v[0:1], v[2:3]
	v_mad_u64_u32 v[48:49], s[4:5], v4, s7, v[78:79]
	v_add_f32_e32 v121, v0, v1
	v_lshlrev_b64 v[0:1], 12, v[18:19]
	v_lshl_add_u64 v[18:19], s[56:57], 0, v[100:101]
	v_lshl_add_u64 v[46:47], v[18:19], 0, s[8:9]
	v_mad_i32_i24 v49, v5, s7, v49
	v_lshl_add_u64 v[18:19], v[18:19], 0, v[152:153]
	v_lshl_add_u64 v[52:53], v[46:47], 0, v[152:153]
	global_load_dwordx4 v[186:189], v[48:49], off offset:1024
	global_load_dwordx4 v[186:189], v[48:49], off offset:2048
	global_load_dwordx4 v[186:189], v[48:49], off offset:3072
	flat_load_dwordx4 v[4:7], v[48:49]
	global_load_dwordx2 v[186:187], v[18:19], off offset:512
	global_load_dwordx2 v[186:187], v[18:19], off offset:1024
	global_load_dwordx2 v[186:187], v[18:19], off offset:1536
	flat_load_dwordx2 v[44:45], v[18:19]
	v_lshl_add_u64 v[40:41], v[80:81], 0, v[0:1]
	global_load_dwordx2 v[186:187], v[52:53], off offset:512
	global_load_dwordx2 v[186:187], v[52:53], off offset:1024
	global_load_dwordx2 v[186:187], v[52:53], off offset:1536
	flat_load_dwordx2 v[52:53], v[52:53]
	v_lshl_add_u64 v[56:57], v[46:47], 0, v[42:43]
	global_load_dwordx4 v[186:189], v[40:41], off offset:1024
	global_load_dwordx4 v[186:189], v[40:41], off offset:2048
	global_load_dwordx4 v[186:189], v[40:41], off offset:3072
	flat_load_dwordx4 v[0:3], v[40:41]
	v_lshl_add_u64 v[108:109], v[46:47], 0, v[104:105]
	v_lshl_add_u64 v[46:47], v[46:47], 0, v[106:107]
	s_waitcnt vmcnt(0) lgkmcnt(0)
	v_pk_mul_f32 v[6:7], v[6:7], 0.5 op_sel_hi:[1,0]
	v_lshlrev_b32_e32 v50, 16, v44
	v_and_b32_e32 v51, 0xffff0000, v44
	v_lshlrev_b32_e32 v44, 16, v45
	v_and_b32_e32 v45, 0xffff0000, v45
	v_lshlrev_b32_e32 v54, 16, v52
	v_and_b32_e32 v55, 0xffff0000, v52
	v_lshlrev_b32_e32 v52, 16, v53
	v_and_b32_e32 v53, 0xffff0000, v53
	v_pk_mul_f32 v[4:5], v[4:5], 0.5 op_sel_hi:[1,0]
	v_pk_add_f32 v[50:51], v[50:51], v[54:55]
	v_pk_add_f32 v[44:45], v[44:45], v[52:53]
	v_pk_mul_f32 v[4:5], v[4:5], v[50:51]
	v_pk_mul_f32 v[6:7], v[6:7], v[44:45]
	v_pk_fma_f32 v[44:45], v[0:1], s[42:43], v[4:5] op_sel_hi:[1,0,1]
	v_pk_fma_f32 v[50:51], v[2:3], s[42:43], v[6:7] op_sel_hi:[1,0,1]
	v_mov_b32_e32 v2, v44
	v_pk_mov_b32 v[0:1], v[44:45], v[50:51] op_sel:[1,0]
	v_mov_b32_e32 v3, v51
	v_pk_add_f32 v[0:1], v[0:1], v[2:3]
	s_nop 0
	v_add_f32_e32 v0, v0, v1
	v_add_f32_e32 v98, 0, v0
	flat_load_dwordx4 v[0:3], v[40:41] offset:1024
	flat_load_dwordx4 v[4:7], v[48:49] offset:1024
	flat_load_dwordx2 v[52:53], v[18:19] offset:512
	s_waitcnt vmcnt(0) lgkmcnt(0)
	v_pk_mul_f32 v[6:7], v[6:7], 0.5 op_sel_hi:[1,0]
	flat_load_dwordx2 v[56:57], v[56:57]
	v_lshlrev_b32_e32 v54, 16, v52
	v_and_b32_e32 v55, 0xffff0000, v52
	v_lshlrev_b32_e32 v52, 16, v53
	v_and_b32_e32 v53, 0xffff0000, v53
	v_pk_mul_f32 v[4:5], v[4:5], 0.5 op_sel_hi:[1,0]
	s_waitcnt vmcnt(0) lgkmcnt(0)
	v_lshlrev_b32_e32 v58, 16, v56
	v_and_b32_e32 v59, 0xffff0000, v56
	v_lshlrev_b32_e32 v56, 16, v57
	v_and_b32_e32 v57, 0xffff0000, v57
	v_pk_add_f32 v[54:55], v[54:55], v[58:59]
	v_pk_add_f32 v[52:53], v[52:53], v[56:57]
	v_pk_mul_f32 v[4:5], v[4:5], v[54:55]
	v_pk_mul_f32 v[6:7], v[6:7], v[52:53]
	v_pk_fma_f32 v[56:57], v[0:1], s[42:43], v[4:5] op_sel_hi:[1,0,1]
	v_pk_fma_f32 v[58:59], v[2:3], s[42:43], v[6:7] op_sel_hi:[1,0,1]
	v_mov_b32_e32 v2, v56
	v_pk_mov_b32 v[0:1], v[56:57], v[58:59] op_sel:[1,0]
	v_mov_b32_e32 v3, v59
	v_pk_add_f32 v[0:1], v[0:1], v[2:3]
	s_nop 0
	v_pk_add_f32 v[102:103], v[0:1], v[0:1] op_sel:[0,1] op_sel_hi:[1,0]
	flat_load_dwordx4 v[0:3], v[40:41] offset:2048
	flat_load_dwordx4 v[4:7], v[48:49] offset:2048
	flat_load_dwordx2 v[52:53], v[18:19] offset:1024
	s_waitcnt vmcnt(0) lgkmcnt(0)
	v_pk_mul_f32 v[6:7], v[6:7], 0.5 op_sel_hi:[1,0]
	flat_load_dwordx2 v[108:109], v[108:109]
	v_lshlrev_b32_e32 v54, 16, v52
	v_and_b32_e32 v55, 0xffff0000, v52
	v_lshlrev_b32_e32 v52, 16, v53
	v_and_b32_e32 v53, 0xffff0000, v53
	v_pk_mul_f32 v[4:5], v[4:5], 0.5 op_sel_hi:[1,0]
	s_waitcnt vmcnt(0) lgkmcnt(0)
	v_lshlrev_b32_e32 v110, 16, v108
	v_and_b32_e32 v111, 0xffff0000, v108
	v_lshlrev_b32_e32 v108, 16, v109
	v_and_b32_e32 v109, 0xffff0000, v109
	v_pk_add_f32 v[52:53], v[52:53], v[108:109]
	v_pk_add_f32 v[54:55], v[54:55], v[110:111]
	v_pk_mul_f32 v[6:7], v[6:7], v[52:53]
	v_pk_mul_f32 v[4:5], v[4:5], v[54:55]
	v_pk_fma_f32 v[54:55], v[2:3], s[42:43], v[6:7] op_sel_hi:[1,0,1]
	v_pk_fma_f32 v[52:53], v[0:1], s[42:43], v[4:5] op_sel_hi:[1,0,1]
	flat_load_dwordx4 v[0:3], v[40:41] offset:3072
	flat_load_dwordx4 v[4:7], v[48:49] offset:3072
	s_nop 0
	flat_load_dwordx2 v[18:19], v[18:19] offset:1536
	v_add_f32_e32 v108, v52, v53
	flat_load_dwordx2 v[46:47], v[46:47]
	v_add_f32_e32 v110, v54, v55
	s_waitcnt vmcnt(0) lgkmcnt(0)
	v_pk_mul_f32 v[6:7], v[6:7], 0.5 op_sel_hi:[1,0]
	v_lshlrev_b32_e32 v48, 16, v18
	v_and_b32_e32 v49, 0xffff0000, v18
	v_lshlrev_b32_e32 v18, 16, v19
	v_and_b32_e32 v19, 0xffff0000, v19
	v_lshlrev_b32_e32 v112, 16, v46
	v_and_b32_e32 v113, 0xffff0000, v46
	v_lshlrev_b32_e32 v46, 16, v47
	v_and_b32_e32 v47, 0xffff0000, v47
	v_pk_mul_f32 v[4:5], v[4:5], 0.5 op_sel_hi:[1,0]
	v_pk_add_f32 v[18:19], v[18:19], v[46:47]
	v_pk_add_f32 v[46:47], v[48:49], v[112:113]
	v_pk_mul_f32 v[6:7], v[6:7], v[18:19]
	v_pk_mul_f32 v[4:5], v[4:5], v[46:47]
	v_pk_fma_f32 v[48:49], v[2:3], s[42:43], v[6:7] op_sel_hi:[1,0,1]
	v_pk_fma_f32 v[46:47], v[0:1], s[42:43], v[4:5] op_sel_hi:[1,0,1]
	v_mov_b32_e32 v109, v48
	v_mov_b32_e32 v99, v46
	v_mov_b32_e32 v103, v47
	v_mov_b32_e32 v111, v49
	v_pk_add_f32 v[0:1], v[98:99], v[102:103]
	v_pk_add_f32 v[2:3], v[108:109], v[110:111]
	v_lshlrev_b64 v[98:99], 11, v[16:17]
	v_pk_add_f32 v[0:1], v[0:1], v[2:3]
	v_lshl_add_u64 v[4:5], v[88:89], 0, s[28:29]
	v_add_f32_e32 v125, v0, v1
	v_lshlrev_b64 v[0:1], 12, v[16:17]
	v_lshl_add_u64 v[16:17], s[56:57], 0, v[98:99]
	v_lshl_add_u64 v[18:19], v[16:17], 0, s[8:9]
	v_mad_u64_u32 v[126:127], s[4:5], v4, s7, v[78:79]
	v_mad_i32_i24 v127, v5, s7, v127
	v_lshl_add_u64 v[16:17], v[16:17], 0, v[152:153]
	v_lshl_add_u64 v[112:113], v[18:19], 0, v[152:153]
	global_load_dwordx4 v[186:189], v[126:127], off offset:1024
	global_load_dwordx4 v[186:189], v[126:127], off offset:2048
	global_load_dwordx4 v[186:189], v[126:127], off offset:3072
	flat_load_dwordx4 v[4:7], v[126:127]
	global_load_dwordx2 v[186:187], v[16:17], off offset:512
	global_load_dwordx2 v[186:187], v[16:17], off offset:1024
	global_load_dwordx2 v[186:187], v[16:17], off offset:1536
	flat_load_dwordx2 v[108:109], v[16:17]
	v_lshl_add_u64 v[102:103], v[80:81], 0, v[0:1]
	global_load_dwordx2 v[186:187], v[112:113], off offset:512
	global_load_dwordx2 v[186:187], v[112:113], off offset:1024
	global_load_dwordx2 v[186:187], v[112:113], off offset:1536
	flat_load_dwordx2 v[112:113], v[112:113]
	v_lshl_add_u64 v[42:43], v[18:19], 0, v[42:43]
	global_load_dwordx4 v[186:189], v[102:103], off offset:1024
	global_load_dwordx4 v[186:189], v[102:103], off offset:2048
	global_load_dwordx4 v[186:189], v[102:103], off offset:3072
	flat_load_dwordx4 v[0:3], v[102:103]
	v_lshl_add_u64 v[104:105], v[18:19], 0, v[104:105]
	v_lshl_add_u64 v[18:19], v[18:19], 0, v[106:107]
	s_mov_b32 s4, 0x3727c5ac
	s_waitcnt vmcnt(0) lgkmcnt(0)
	v_pk_mul_f32 v[6:7], v[6:7], 0.5 op_sel_hi:[1,0]
	v_lshlrev_b32_e32 v110, 16, v108
	v_and_b32_e32 v111, 0xffff0000, v108
	v_lshlrev_b32_e32 v108, 16, v109
	v_and_b32_e32 v109, 0xffff0000, v109
	v_lshlrev_b32_e32 v114, 16, v112
	v_and_b32_e32 v115, 0xffff0000, v112
	v_lshlrev_b32_e32 v112, 16, v113
	v_and_b32_e32 v113, 0xffff0000, v113
	v_pk_mul_f32 v[4:5], v[4:5], 0.5 op_sel_hi:[1,0]
	v_pk_add_f32 v[110:111], v[110:111], v[114:115]
	v_pk_add_f32 v[108:109], v[108:109], v[112:113]
	v_pk_mul_f32 v[4:5], v[4:5], v[110:111]
	v_pk_mul_f32 v[6:7], v[6:7], v[108:109]
	v_pk_fma_f32 v[114:115], v[0:1], s[42:43], v[4:5] op_sel_hi:[1,0,1]
	v_pk_fma_f32 v[116:117], v[2:3], s[42:43], v[6:7] op_sel_hi:[1,0,1]
	v_mov_b32_e32 v2, v114
	v_pk_mov_b32 v[0:1], v[114:115], v[116:117] op_sel:[1,0]
	v_mov_b32_e32 v3, v117
	v_pk_add_f32 v[0:1], v[0:1], v[2:3]
	s_nop 0
	v_add_f32_e32 v0, v0, v1
	v_add_f32_e32 v128, 0, v0
	flat_load_dwordx4 v[0:3], v[102:103] offset:1024
	flat_load_dwordx4 v[4:7], v[126:127] offset:1024
	flat_load_dwordx2 v[108:109], v[16:17] offset:512
	s_waitcnt vmcnt(0) lgkmcnt(0)
	v_pk_mul_f32 v[6:7], v[6:7], 0.5 op_sel_hi:[1,0]
	flat_load_dwordx2 v[42:43], v[42:43]
	v_lshlrev_b32_e32 v110, 16, v108
	v_and_b32_e32 v111, 0xffff0000, v108
	v_lshlrev_b32_e32 v108, 16, v109
	v_and_b32_e32 v109, 0xffff0000, v109
	v_pk_mul_f32 v[4:5], v[4:5], 0.5 op_sel_hi:[1,0]
	s_waitcnt vmcnt(0) lgkmcnt(0)
	v_lshlrev_b32_e32 v112, 16, v42
	v_and_b32_e32 v113, 0xffff0000, v42
	v_lshlrev_b32_e32 v42, 16, v43
	v_and_b32_e32 v43, 0xffff0000, v43
	v_pk_add_f32 v[110:111], v[110:111], v[112:113]
	v_pk_add_f32 v[42:43], v[108:109], v[42:43]
	v_pk_mul_f32 v[4:5], v[4:5], v[110:111]
	v_pk_mul_f32 v[6:7], v[6:7], v[42:43]
	v_pk_fma_f32 v[42:43], v[0:1], s[42:43], v[4:5] op_sel_hi:[1,0,1]
	v_pk_fma_f32 v[112:113], v[2:3], s[42:43], v[6:7] op_sel_hi:[1,0,1]
	v_mov_b32_e32 v2, v42
	v_pk_mov_b32 v[0:1], v[42:43], v[112:113] op_sel:[1,0]
	v_mov_b32_e32 v3, v113
	v_pk_add_f32 v[0:1], v[0:1], v[2:3]
	s_nop 0
	v_pk_add_f32 v[130:131], v[0:1], v[0:1] op_sel:[0,1] op_sel_hi:[1,0]
	flat_load_dwordx4 v[0:3], v[102:103] offset:2048
	flat_load_dwordx4 v[4:7], v[126:127] offset:2048
	flat_load_dwordx2 v[108:109], v[16:17] offset:1024
	s_waitcnt vmcnt(0) lgkmcnt(0)
	v_pk_mul_f32 v[6:7], v[6:7], 0.5 op_sel_hi:[1,0]
	flat_load_dwordx2 v[104:105], v[104:105]
	v_lshlrev_b32_e32 v110, 16, v108
	v_and_b32_e32 v111, 0xffff0000, v108
	v_lshlrev_b32_e32 v108, 16, v109
	v_and_b32_e32 v109, 0xffff0000, v109
	v_pk_mul_f32 v[4:5], v[4:5], 0.5 op_sel_hi:[1,0]
	s_waitcnt vmcnt(0) lgkmcnt(0)
	v_lshlrev_b32_e32 v132, 16, v104
	v_and_b32_e32 v133, 0xffff0000, v104
	v_lshlrev_b32_e32 v104, 16, v105
	v_and_b32_e32 v105, 0xffff0000, v105
	v_pk_add_f32 v[104:105], v[108:109], v[104:105]
	v_pk_add_f32 v[108:109], v[110:111], v[132:133]
	v_pk_mul_f32 v[6:7], v[6:7], v[104:105]
	v_pk_mul_f32 v[4:5], v[4:5], v[108:109]
	v_pk_fma_f32 v[110:111], v[2:3], s[42:43], v[6:7] op_sel_hi:[1,0,1]
	v_pk_fma_f32 v[108:109], v[0:1], s[42:43], v[4:5] op_sel_hi:[1,0,1]
	flat_load_dwordx4 v[0:3], v[102:103] offset:3072
	flat_load_dwordx4 v[4:7], v[126:127] offset:3072
	s_nop 0
	flat_load_dwordx2 v[16:17], v[16:17] offset:1536
	v_add_f32_e32 v132, v108, v109
	flat_load_dwordx2 v[18:19], v[18:19]
	v_add_f32_e32 v134, v110, v111
	s_waitcnt vmcnt(0) lgkmcnt(0)
	v_pk_mul_f32 v[6:7], v[6:7], 0.5 op_sel_hi:[1,0]
	v_lshlrev_b32_e32 v104, 16, v16
	v_and_b32_e32 v105, 0xffff0000, v16
	v_lshlrev_b32_e32 v16, 16, v17
	v_and_b32_e32 v17, 0xffff0000, v17
	v_lshlrev_b32_e32 v106, 16, v18
	v_and_b32_e32 v107, 0xffff0000, v18
	v_lshlrev_b32_e32 v18, 16, v19
	v_and_b32_e32 v19, 0xffff0000, v19
	v_pk_mul_f32 v[4:5], v[4:5], 0.5 op_sel_hi:[1,0]
	v_pk_add_f32 v[16:17], v[16:17], v[18:19]
	v_pk_add_f32 v[18:19], v[104:105], v[106:107]
	v_pk_mul_f32 v[6:7], v[6:7], v[16:17]
	v_pk_mul_f32 v[4:5], v[4:5], v[18:19]
	v_pk_fma_f32 v[106:107], v[2:3], s[42:43], v[6:7] op_sel_hi:[1,0,1]
	v_pk_fma_f32 v[104:105], v[0:1], s[42:43], v[4:5] op_sel_hi:[1,0,1]
	v_mov_b32_e32 v133, v106
	v_mov_b32_e32 v129, v104
	v_mov_b32_e32 v131, v105
	v_mov_b32_e32 v135, v107
	v_pk_add_f32 v[0:1], v[128:129], v[130:131]
	v_pk_add_f32 v[2:3], v[132:133], v[134:135]
	ds_bpermute_b32 v18, v67, v121
	v_pk_add_f32 v[0:1], v[0:1], v[2:3]
	s_waitcnt lgkmcnt(0)
	v_add_f32_e32 v18, v121, v18
	v_add_f32_e32 v65, v0, v1
	ds_bpermute_b32 v0, v67, v120
	ds_bpermute_b32 v19, v69, v18
	s_waitcnt lgkmcnt(1)
	v_add_f32_e32 v0, v120, v0
	ds_bpermute_b32 v1, v69, v0
	s_waitcnt lgkmcnt(1)
	v_add_f32_e32 v18, v18, v19
	ds_bpermute_b32 v19, v71, v18
	s_waitcnt lgkmcnt(1)
	v_add_f32_e32 v0, v0, v1
	ds_bpermute_b32 v1, v71, v0
	s_waitcnt lgkmcnt(1)
	v_add_f32_e32 v18, v18, v19
	ds_bpermute_b32 v19, v73, v18
	s_waitcnt lgkmcnt(1)
	v_add_f32_e32 v0, v0, v1
	ds_bpermute_b32 v1, v73, v0
	s_waitcnt lgkmcnt(1)
	v_add_f32_e32 v18, v18, v19
	ds_bpermute_b32 v19, v123, v18
	s_waitcnt lgkmcnt(1)
	v_add_f32_e32 v0, v0, v1
	ds_bpermute_b32 v1, v123, v0
	s_waitcnt lgkmcnt(1)
	v_add_f32_e32 v18, v18, v19
	ds_bpermute_b32 v19, v124, v18
	s_waitcnt lgkmcnt(1)
	v_add_f32_e32 v0, v0, v1
	ds_bpermute_b32 v1, v124, v0
	s_waitcnt lgkmcnt(1)
	v_add_f32_e32 v122, v18, v19
	v_fmamk_f32 v35, v122, 0xba800000, v35
	v_fmac_f32_e32 v34, 0xba800000, v122
	v_fmamk_f32 v37, v122, 0xba800000, v37
	s_waitcnt lgkmcnt(0)
	v_add_f32_e32 v16, v0, v1
	v_fmamk_f32 v9, v16, 0xba800000, v9
	v_fmac_f32_e32 v8, 0xba800000, v16
	v_fmamk_f32 v11, v16, 0xba800000, v11
	v_fmac_f32_e32 v10, 0xba800000, v16
	v_pk_mul_f32 v[0:1], v[10:11], v[10:11]
	v_pk_mul_f32 v[2:3], v[8:9], v[8:9]
	v_fmamk_f32 v13, v16, 0xba800000, v13
	v_pk_mov_b32 v[4:5], v[2:3], v[0:1] op_sel:[1,0]
	v_mov_b32_e32 v3, v1
	v_pk_add_f32 v[0:1], v[4:5], v[2:3]
	v_fmac_f32_e32 v12, 0xba800000, v16
	v_fmamk_f32 v15, v16, 0xba800000, v15
	v_fmac_f32_e32 v14, 0xba800000, v16
	v_pk_add_f32 v[0:1], v[0:1], v[0:1] op_sel_hi:[0,1]
	v_pk_mul_f32 v[2:3], v[14:15], v[14:15]
	v_pk_mul_f32 v[4:5], v[12:13], v[12:13]
	v_fmac_f32_e32 v20, 0xba800000, v16
	v_pk_mov_b32 v[6:7], v[4:5], v[2:3] op_sel:[1,0]
	v_mov_b32_e32 v5, v3
	v_fmamk_f32 v21, v16, 0xba800000, v21
	v_fmac_f32_e32 v22, 0xba800000, v16
	v_mul_f32_e32 v0, v20, v20
	v_pk_add_f32 v[2:3], v[6:7], v[4:5]
	v_fmamk_f32 v23, v16, 0xba800000, v23
	v_pk_fma_f32 v[4:5], v[20:21], v[20:21], v[0:1] op_sel_hi:[1,1,0]
	v_mul_f32_e32 v0, v22, v22
	v_pk_add_f32 v[2:3], v[2:3], v[2:3] op_sel_hi:[0,1]
	v_pk_fma_f32 v[6:7], v[22:23], v[22:23], v[0:1] op_sel_hi:[1,1,0]
	v_fmamk_f32 v27, v16, 0xba800000, v27
	v_fmac_f32_e32 v26, 0xba800000, v16
	v_fmamk_f32 v25, v16, 0xba800000, v25
	v_fmac_f32_e32 v24, 0xba800000, v16
	v_mul_f32_e32 v4, v24, v24
	v_mul_f32_e32 v6, v25, v25
	v_mul_f32_e32 v0, v26, v26
	v_mul_f32_e32 v2, v27, v27
	v_pk_add_f32 v[4:5], v[4:5], v[6:7]
	v_pk_add_f32 v[0:1], v[0:1], v[2:3]
	v_fmac_f32_e32 v36, 0xba800000, v122
	v_pk_add_f32 v[16:17], v[4:5], v[0:1]
	v_mov_b64_e32 v[0:1], v[154:155]
	v_mov_b64_e32 v[2:3], v[156:157]
	v_mov_b64_e32 v[4:5], v[158:159]
	v_mov_b64_e32 v[6:7], v[160:161]
	v_pk_mul_f32 v[18:19], v[36:37], v[36:37]
	v_pk_mul_f32 v[120:121], v[34:35], v[34:35]
	v_fmamk_f32 v39, v122, 0xba800000, v39
	v_pk_mov_b32 v[126:127], v[120:121], v[18:19] op_sel:[1,0]
	v_mov_b32_e32 v121, v19
	v_pk_add_f32 v[18:19], v[126:127], v[120:121]
	v_fmac_f32_e32 v38, 0xba800000, v122
	v_fmamk_f32 v61, v122, 0xba800000, v61
	v_fmac_f32_e32 v60, 0xba800000, v122
	v_pk_add_f32 v[18:19], v[18:19], v[18:19] op_sel_hi:[0,1]
	v_pk_mul_f32 v[120:121], v[60:61], v[60:61]
	v_pk_mul_f32 v[126:127], v[38:39], v[38:39]
	v_fmac_f32_e32 v28, 0xba800000, v122
	v_pk_mov_b32 v[128:129], v[126:127], v[120:121] op_sel:[1,0]
	v_mov_b32_e32 v127, v121
	v_fmamk_f32 v29, v122, 0xba800000, v29
	v_fmac_f32_e32 v30, 0xba800000, v122
	v_mul_f32_e32 v18, v28, v28
	v_pk_add_f32 v[120:121], v[128:129], v[126:127]
	v_fmamk_f32 v31, v122, 0xba800000, v31
	v_pk_fma_f32 v[126:127], v[28:29], v[28:29], v[18:19] op_sel_hi:[1,1,0]
	v_mul_f32_e32 v18, v30, v30
	v_pk_add_f32 v[120:121], v[120:121], v[120:121] op_sel_hi:[0,1]
	v_pk_fma_f32 v[128:129], v[30:31], v[30:31], v[18:19] op_sel_hi:[1,1,0]
	v_fmamk_f32 v119, v122, 0xba800000, v119
	v_fmac_f32_e32 v118, 0xba800000, v122
	v_fmamk_f32 v63, v122, 0xba800000, v63
	v_fmac_f32_e32 v62, 0xba800000, v122
	v_mul_f32_e32 v126, v62, v62
	v_mul_f32_e32 v128, v63, v63
	v_mul_f32_e32 v18, v118, v118
	v_mul_f32_e32 v120, v119, v119
	v_pk_add_f32 v[126:127], v[126:127], v[128:129]
	v_pk_add_f32 v[18:19], v[18:19], v[120:121]
	v_mov_b32_e32 v121, v16
	v_pk_add_f32 v[18:19], v[126:127], v[18:19]
	s_nop 0
	v_mov_b32_e32 v120, v18
	v_mov_b32_e32 v16, v19
	v_pk_add_f32 v[16:17], v[120:121], v[16:17]
	ds_bpermute_b32 v19, v67, v17
	ds_bpermute_b32 v18, v67, v16
	v_mov_b64_e32 v[120:121], s[4:5]
	s_mov_b32 s4, 0x3a800000
	s_waitcnt lgkmcnt(0)
	v_pk_add_f32 v[16:17], v[16:17], v[18:19]
	ds_bpermute_b32 v19, v69, v17
	ds_bpermute_b32 v18, v69, v16
	s_waitcnt lgkmcnt(0)
	v_pk_add_f32 v[16:17], v[16:17], v[18:19]
	ds_bpermute_b32 v19, v71, v17
	ds_bpermute_b32 v18, v71, v16
	s_waitcnt lgkmcnt(0)
	v_pk_add_f32 v[16:17], v[16:17], v[18:19]
	ds_bpermute_b32 v19, v73, v17
	ds_bpermute_b32 v18, v73, v16
	s_waitcnt lgkmcnt(0)
	v_pk_add_f32 v[16:17], v[16:17], v[18:19]
	ds_bpermute_b32 v19, v123, v17
	ds_bpermute_b32 v18, v123, v16
	s_waitcnt lgkmcnt(0)
	v_pk_add_f32 v[16:17], v[16:17], v[18:19]
	ds_bpermute_b32 v19, v124, v17
	ds_bpermute_b32 v18, v124, v16
	s_waitcnt lgkmcnt(0)
	v_pk_add_f32 v[16:17], v[16:17], v[18:19]
	s_nop 0
	v_pk_fma_f32 v[126:127], v[16:17], s[4:5], v[120:121] op_sel_hi:[1,0,0]
	s_nop 0
	v_mul_f32_e32 v16, 0x4b800000, v127
	v_cmp_gt_f32_e64 s[8:9], s68, v127
	v_cmp_gt_f32_e32 vcc, s68, v126
	s_nop 0
	v_cndmask_b32_e64 v16, v127, v16, s[8:9]
	v_rsq_f32_e32 v16, v16
	s_nop 0
	v_mul_f32_e32 v17, 0x45800000, v16
	v_cndmask_b32_e64 v122, v16, v17, s[8:9]
	v_pk_mul_f32 v[8:9], v[8:9], v[122:123] op_sel_hi:[1,0]
	v_pk_mul_f32 v[10:11], v[10:11], v[122:123] op_sel_hi:[1,0]
	v_pk_fma_f32 v[16:17], v[0:1], v[8:9], v[4:5]
	v_pk_fma_f32 v[18:19], v[2:3], v[10:11], v[6:7]
	flat_store_dwordx4 v[86:87], v[16:19]
	v_mov_b64_e32 v[0:1], v[162:163]
	v_mov_b64_e32 v[2:3], v[164:165]
	v_mov_b64_e32 v[4:5], v[166:167]
	v_mov_b64_e32 v[6:7], v[168:169]
	v_pk_mul_f32 v[8:9], v[14:15], v[122:123] op_sel_hi:[1,0]
	v_pk_mul_f32 v[10:11], v[12:13], v[122:123] op_sel_hi:[1,0]
	v_pk_fma_f32 v[14:15], v[2:3], v[8:9], v[6:7]
	v_pk_fma_f32 v[12:13], v[0:1], v[10:11], v[4:5]
	flat_store_dwordx4 v[86:87], v[12:15] offset:1024
	v_mov_b64_e32 v[0:1], v[170:171]
	v_mov_b64_e32 v[2:3], v[172:173]
	v_mov_b64_e32 v[4:5], v[174:175]
	v_mov_b64_e32 v[6:7], v[176:177]
	v_pk_mul_f32 v[8:9], v[22:23], v[122:123] op_sel_hi:[1,0]
	v_pk_mul_f32 v[10:11], v[20:21], v[122:123] op_sel_hi:[1,0]
	v_pk_mul_f32 v[22:23], v[24:25], v[122:123] op_sel_hi:[1,0]
	v_pk_mul_f32 v[20:21], v[26:27], v[122:123] op_sel_hi:[1,0]
	v_pk_fma_f32 v[4:5], v[0:1], v[10:11], v[4:5]
	v_pk_fma_f32 v[6:7], v[2:3], v[8:9], v[6:7]
	flat_store_dwordx4 v[86:87], v[4:7] offset:2048
	v_mov_b64_e32 v[0:1], v[178:179]
	v_mov_b64_e32 v[2:3], v[180:181]
	v_mov_b64_e32 v[8:9], v[182:183]
	v_mov_b64_e32 v[10:11], v[184:185]
	v_pk_fma_f32 v[0:1], v[0:1], v[22:23], v[8:9]
	v_mul_f32_e32 v8, 0x4b800000, v126
	v_cndmask_b32_e32 v8, v126, v8, vcc
	v_rsq_f32_e32 v8, v8
	v_pk_fma_f32 v[2:3], v[2:3], v[20:21], v[10:11]
	flat_store_dwordx4 v[86:87], v[0:3] offset:3072
	v_mul_f32_e32 v9, 0x45800000, v8
	v_cndmask_b32_e32 v122, v8, v9, vcc
	v_mov_b64_e32 v[8:9], v[154:155]
	v_mov_b64_e32 v[10:11], v[156:157]
	v_mov_b64_e32 v[20:21], v[158:159]
	v_mov_b64_e32 v[22:23], v[160:161]
	v_pk_mul_f32 v[24:25], v[36:37], v[122:123] op_sel_hi:[1,0]
	v_pk_mul_f32 v[26:27], v[34:35], v[122:123] op_sel_hi:[1,0]
	v_pk_mul_f32 v[34:35], v[60:61], v[122:123] op_sel_hi:[1,0]
	v_pk_mul_f32 v[36:37], v[38:39], v[122:123] op_sel_hi:[1,0]
	v_pk_mul_f32 v[38:39], v[118:119], v[122:123] op_sel_hi:[1,0]
	v_pk_mul_f32 v[60:61], v[62:63], v[122:123] op_sel_hi:[1,0]
	ds_bpermute_b32 v62, v67, v65
	s_waitcnt lgkmcnt(0)
	v_add_f32_e32 v62, v65, v62
	ds_bpermute_b32 v63, v69, v62
	s_waitcnt lgkmcnt(0)
	v_add_f32_e32 v62, v62, v63
	ds_bpermute_b32 v63, v71, v62
	s_waitcnt lgkmcnt(0)
	v_add_f32_e32 v62, v62, v63
	ds_bpermute_b32 v63, v73, v62
	s_waitcnt lgkmcnt(0)
	v_add_f32_e32 v62, v62, v63
	ds_bpermute_b32 v63, v123, v62
	s_waitcnt lgkmcnt(0)
	v_add_f32_e32 v62, v62, v63
	ds_bpermute_b32 v63, v124, v62
	s_waitcnt lgkmcnt(0)
	v_add_f32_e32 v65, v62, v63
	v_fmamk_f32 v115, v65, 0xba800000, v115
	v_fmac_f32_e32 v114, 0xba800000, v65
	v_fmamk_f32 v117, v65, 0xba800000, v117
	v_fmac_f32_e32 v116, 0xba800000, v65
	v_pk_mul_f32 v[62:63], v[116:117], v[116:117]
	v_pk_mul_f32 v[118:119], v[114:115], v[114:115]
	v_fmamk_f32 v43, v65, 0xba800000, v43
	v_pk_mov_b32 v[126:127], v[118:119], v[62:63] op_sel:[1,0]
	v_mov_b32_e32 v119, v63
	v_pk_add_f32 v[62:63], v[126:127], v[118:119]
	v_fmac_f32_e32 v42, 0xba800000, v65
	v_fmamk_f32 v113, v65, 0xba800000, v113
	v_fmac_f32_e32 v112, 0xba800000, v65
	v_pk_add_f32 v[62:63], v[62:63], v[62:63] op_sel_hi:[0,1]
	v_pk_mul_f32 v[118:119], v[112:113], v[112:113]
	v_pk_mul_f32 v[126:127], v[42:43], v[42:43]
	v_fmac_f32_e32 v108, 0xba800000, v65
	v_pk_mov_b32 v[128:129], v[126:127], v[118:119] op_sel:[1,0]
	v_mov_b32_e32 v127, v119
	v_fmamk_f32 v109, v65, 0xba800000, v109
	v_fmac_f32_e32 v110, 0xba800000, v65
	v_mul_f32_e32 v62, v108, v108
	v_pk_add_f32 v[118:119], v[128:129], v[126:127]
	v_fmamk_f32 v111, v65, 0xba800000, v111
	v_pk_fma_f32 v[126:127], v[108:109], v[108:109], v[62:63] op_sel_hi:[1,1,0]
	v_mul_f32_e32 v62, v110, v110
	v_pk_add_f32 v[118:119], v[118:119], v[118:119] op_sel_hi:[0,1]
	v_pk_fma_f32 v[128:129], v[110:111], v[110:111], v[62:63] op_sel_hi:[1,1,0]
	v_fmamk_f32 v107, v65, 0xba800000, v107
	v_fmac_f32_e32 v106, 0xba800000, v65
	v_fmamk_f32 v105, v65, 0xba800000, v105
	v_fmac_f32_e32 v104, 0xba800000, v65
	v_mul_f32_e32 v126, v104, v104
	v_mul_f32_e32 v128, v105, v105
	v_mul_f32_e32 v62, v106, v106
	v_mul_f32_e32 v118, v107, v107
	v_pk_add_f32 v[126:127], v[126:127], v[128:129]
	v_pk_fma_f32 v[8:9], v[8:9], v[26:27], v[20:21]
	v_pk_fma_f32 v[10:11], v[10:11], v[24:25], v[22:23]
	flat_store_dwordx4 v[32:33], v[8:11]
	v_mov_b64_e32 v[20:21], v[162:163]
	v_mov_b64_e32 v[22:23], v[164:165]
	v_mov_b64_e32 v[24:25], v[166:167]
	v_mov_b64_e32 v[26:27], v[168:169]
	v_pk_add_f32 v[62:63], v[62:63], v[118:119]
	v_pk_fma_f32 v[20:21], v[20:21], v[36:37], v[24:25]
	v_pk_fma_f32 v[22:23], v[22:23], v[34:35], v[26:27]
	flat_store_dwordx4 v[32:33], v[20:23] offset:1024
	v_pk_mul_f32 v[34:35], v[30:31], v[122:123] op_sel_hi:[1,0]
	v_pk_mul_f32 v[36:37], v[28:29], v[122:123] op_sel_hi:[1,0]
	v_mov_b64_e32 v[24:25], v[170:171]
	v_mov_b64_e32 v[26:27], v[172:173]
	v_mov_b64_e32 v[28:29], v[174:175]
	v_mov_b64_e32 v[30:31], v[176:177]
	v_pk_add_f32 v[62:63], v[126:127], v[62:63]
	v_pk_fma_f32 v[28:29], v[24:25], v[36:37], v[28:29]
	v_pk_fma_f32 v[30:31], v[26:27], v[34:35], v[30:31]
	flat_store_dwordx4 v[32:33], v[28:31] offset:2048
	v_mov_b64_e32 v[24:25], v[178:179]
	v_mov_b64_e32 v[26:27], v[180:181]
	v_mov_b64_e32 v[34:35], v[182:183]
	v_mov_b64_e32 v[36:37], v[184:185]
	v_mov_b32_e32 v118, v62
	v_pk_fma_f32 v[24:25], v[24:25], v[60:61], v[34:35]
	v_pk_fma_f32 v[26:27], v[26:27], v[38:39], v[36:37]
	flat_store_dwordx4 v[32:33], v[24:27] offset:3072
	ds_bpermute_b32 v32, v67, v125
	s_waitcnt lgkmcnt(0)
	v_add_f32_e32 v32, v125, v32
	ds_bpermute_b32 v33, v69, v32
	s_waitcnt lgkmcnt(0)
	v_add_f32_e32 v32, v32, v33
	ds_bpermute_b32 v33, v71, v32
	s_waitcnt lgkmcnt(0)
	v_add_f32_e32 v32, v32, v33
	ds_bpermute_b32 v33, v73, v32
	s_waitcnt lgkmcnt(0)
	v_add_f32_e32 v32, v32, v33
	ds_bpermute_b32 v33, v123, v32
	s_waitcnt lgkmcnt(0)
	v_add_f32_e32 v32, v32, v33
	ds_bpermute_b32 v33, v124, v32
	s_waitcnt lgkmcnt(0)
	v_add_f32_e32 v60, v32, v33
	v_fmamk_f32 v45, v60, 0xba800000, v45
	v_fmac_f32_e32 v44, 0xba800000, v60
	v_fmamk_f32 v51, v60, 0xba800000, v51
	v_fmac_f32_e32 v50, 0xba800000, v60
	v_pk_mul_f32 v[32:33], v[50:51], v[50:51]
	v_pk_mul_f32 v[34:35], v[44:45], v[44:45]
	v_fmamk_f32 v57, v60, 0xba800000, v57
	v_pk_mov_b32 v[36:37], v[34:35], v[32:33] op_sel:[1,0]
	v_mov_b32_e32 v35, v33
	v_pk_add_f32 v[32:33], v[36:37], v[34:35]
	v_fmac_f32_e32 v56, 0xba800000, v60
	v_fmamk_f32 v59, v60, 0xba800000, v59
	v_fmac_f32_e32 v58, 0xba800000, v60
	v_pk_add_f32 v[32:33], v[32:33], v[32:33] op_sel_hi:[0,1]
	v_pk_mul_f32 v[34:35], v[58:59], v[58:59]
	v_pk_mul_f32 v[36:37], v[56:57], v[56:57]
	v_fmac_f32_e32 v52, 0xba800000, v60
	v_pk_mov_b32 v[38:39], v[36:37], v[34:35] op_sel:[1,0]
	v_mov_b32_e32 v37, v35
	v_fmamk_f32 v53, v60, 0xba800000, v53
	v_fmac_f32_e32 v54, 0xba800000, v60
	v_mul_f32_e32 v32, v52, v52
	v_pk_add_f32 v[34:35], v[38:39], v[36:37]
	v_fmamk_f32 v55, v60, 0xba800000, v55
	v_pk_fma_f32 v[36:37], v[52:53], v[52:53], v[32:33] op_sel_hi:[1,1,0]
	v_mul_f32_e32 v32, v54, v54
	v_pk_add_f32 v[34:35], v[34:35], v[34:35] op_sel_hi:[0,1]
	v_pk_fma_f32 v[38:39], v[54:55], v[54:55], v[32:33] op_sel_hi:[1,1,0]
	v_fmamk_f32 v49, v60, 0xba800000, v49
	v_fmac_f32_e32 v48, 0xba800000, v60
	v_fmamk_f32 v47, v60, 0xba800000, v47
	v_fmac_f32_e32 v46, 0xba800000, v60
	v_mul_f32_e32 v36, v46, v46
	v_mul_f32_e32 v38, v47, v47
	v_mul_f32_e32 v32, v48, v48
	v_mul_f32_e32 v34, v49, v49
	v_pk_add_f32 v[36:37], v[36:37], v[38:39]
	v_pk_add_f32 v[32:33], v[32:33], v[34:35]
	s_nop 0
	v_pk_add_f32 v[60:61], v[36:37], v[32:33]
	v_mov_b64_e32 v[32:33], v[154:155]
	v_mov_b64_e32 v[34:35], v[156:157]
	v_mov_b64_e32 v[36:37], v[158:159]
	v_mov_b64_e32 v[38:39], v[160:161]
	v_mov_b32_e32 v119, v60
	v_mov_b32_e32 v60, v63
	v_pk_add_f32 v[60:61], v[118:119], v[60:61]
	ds_bpermute_b32 v63, v67, v61
	ds_bpermute_b32 v62, v67, v60
	s_waitcnt lgkmcnt(0)
	v_pk_add_f32 v[60:61], v[60:61], v[62:63]
	ds_bpermute_b32 v63, v69, v61
	ds_bpermute_b32 v62, v69, v60
	s_waitcnt lgkmcnt(0)
	v_pk_add_f32 v[60:61], v[60:61], v[62:63]
	ds_bpermute_b32 v63, v71, v61
	ds_bpermute_b32 v62, v71, v60
	s_waitcnt lgkmcnt(0)
	v_pk_add_f32 v[60:61], v[60:61], v[62:63]
	ds_bpermute_b32 v63, v73, v61
	ds_bpermute_b32 v62, v73, v60
	s_waitcnt lgkmcnt(0)
	v_pk_add_f32 v[60:61], v[60:61], v[62:63]
	ds_bpermute_b32 v63, v123, v61
	ds_bpermute_b32 v62, v123, v60
	s_waitcnt lgkmcnt(0)
	v_pk_add_f32 v[60:61], v[60:61], v[62:63]
	ds_bpermute_b32 v63, v124, v61
	ds_bpermute_b32 v62, v124, v60
	s_waitcnt lgkmcnt(0)
	v_pk_add_f32 v[60:61], v[60:61], v[62:63]
	s_nop 0
	v_pk_fma_f32 v[118:119], v[60:61], s[4:5], v[120:121] op_sel_hi:[1,0,0]
	s_nop 0
	v_mul_f32_e32 v60, 0x4b800000, v119
	v_cmp_gt_f32_e64 s[8:9], s68, v119
	v_cmp_gt_f32_e32 vcc, s68, v118
	s_nop 0
	v_cndmask_b32_e64 v60, v119, v60, s[8:9]
	v_rsq_f32_e32 v60, v60
	s_nop 0
	v_mul_f32_e32 v61, 0x45800000, v60
	v_cndmask_b32_e64 v120, v60, v61, s[8:9]
	v_pk_mul_f32 v[50:51], v[50:51], v[120:121] op_sel_hi:[1,0]
	v_pk_mul_f32 v[44:45], v[44:45], v[120:121] op_sel_hi:[1,0]
	v_pk_mul_f32 v[46:47], v[46:47], v[120:121] op_sel_hi:[1,0]
	v_pk_fma_f32 v[60:61], v[32:33], v[44:45], v[36:37]
	v_pk_fma_f32 v[62:63], v[34:35], v[50:51], v[38:39]
	flat_store_dwordx4 v[40:41], v[60:63]
	v_mov_b64_e32 v[32:33], v[162:163]
	v_mov_b64_e32 v[34:35], v[164:165]
	v_mov_b64_e32 v[36:37], v[166:167]
	v_mov_b64_e32 v[38:39], v[168:169]
	v_pk_mul_f32 v[44:45], v[58:59], v[120:121] op_sel_hi:[1,0]
	v_pk_mul_f32 v[50:51], v[56:57], v[120:121] op_sel_hi:[1,0]
	v_pk_fma_f32 v[58:59], v[34:35], v[44:45], v[38:39]
	v_pk_fma_f32 v[56:57], v[32:33], v[50:51], v[36:37]
	flat_store_dwordx4 v[40:41], v[56:59] offset:1024
	v_mov_b64_e32 v[32:33], v[170:171]
	v_mov_b64_e32 v[34:35], v[172:173]
	v_mov_b64_e32 v[36:37], v[174:175]
	v_mov_b64_e32 v[38:39], v[176:177]
	v_pk_mul_f32 v[44:45], v[54:55], v[120:121] op_sel_hi:[1,0]
	v_pk_mul_f32 v[50:51], v[52:53], v[120:121] op_sel_hi:[1,0]
	v_pk_fma_f32 v[54:55], v[34:35], v[44:45], v[38:39]
	v_pk_fma_f32 v[52:53], v[32:33], v[50:51], v[36:37]
	flat_store_dwordx4 v[40:41], v[52:55] offset:2048
	v_mov_b64_e32 v[32:33], v[178:179]
	v_mov_b64_e32 v[34:35], v[180:181]
	v_mov_b64_e32 v[36:37], v[182:183]
	v_mov_b64_e32 v[38:39], v[184:185]
	v_pk_mul_f32 v[44:45], v[48:49], v[120:121] op_sel_hi:[1,0]
	v_pk_fma_f32 v[48:49], v[32:33], v[46:47], v[36:37]
	v_mul_f32_e32 v32, 0x4b800000, v118
	v_cndmask_b32_e32 v32, v118, v32, vcc
	v_rsq_f32_e32 v32, v32
	v_pk_fma_f32 v[50:51], v[34:35], v[44:45], v[38:39]
	flat_store_dwordx4 v[40:41], v[48:51] offset:3072
	v_mul_f32_e32 v33, 0x45800000, v32
	v_cndmask_b32_e32 v118, v32, v33, vcc
	v_mov_b64_e32 v[32:33], v[154:155]
	v_mov_b64_e32 v[34:35], v[156:157]
	v_mov_b64_e32 v[36:37], v[158:159]
	v_mov_b64_e32 v[38:39], v[160:161]
	v_pk_mul_f32 v[40:41], v[116:117], v[118:119] op_sel_hi:[1,0]
	v_pk_mul_f32 v[44:45], v[114:115], v[118:119] op_sel_hi:[1,0]
	v_pk_mul_f32 v[112:113], v[112:113], v[118:119] op_sel_hi:[1,0]
	v_pk_mul_f32 v[110:111], v[110:111], v[118:119] op_sel_hi:[1,0]
	v_pk_mul_f32 v[108:109], v[108:109], v[118:119] op_sel_hi:[1,0]
	s_andn2_b64 vcc, exec, s[14:15]
	v_pk_fma_f32 v[44:45], v[32:33], v[44:45], v[36:37]
	v_pk_fma_f32 v[46:47], v[34:35], v[40:41], v[38:39]
	flat_store_dwordx4 v[102:103], v[44:47]
	v_mov_b64_e32 v[32:33], v[162:163]
	v_mov_b64_e32 v[34:35], v[164:165]
	v_mov_b64_e32 v[36:37], v[166:167]
	v_mov_b64_e32 v[38:39], v[168:169]
	v_pk_mul_f32 v[40:41], v[42:43], v[118:119] op_sel_hi:[1,0]
	v_pk_fma_f32 v[42:43], v[34:35], v[112:113], v[38:39]
	v_pk_fma_f32 v[40:41], v[32:33], v[40:41], v[36:37]
	flat_store_dwordx4 v[102:103], v[40:43] offset:1024
	v_mov_b64_e32 v[32:33], v[170:171]
	v_mov_b64_e32 v[34:35], v[172:173]
	v_mov_b64_e32 v[36:37], v[174:175]
	v_mov_b64_e32 v[38:39], v[176:177]
	v_pk_fma_f32 v[36:37], v[32:33], v[108:109], v[36:37]
	v_pk_fma_f32 v[38:39], v[34:35], v[110:111], v[38:39]
	flat_store_dwordx4 v[102:103], v[36:39] offset:2048
	v_pk_mul_f32 v[108:109], v[106:107], v[118:119] op_sel_hi:[1,0]
	v_pk_mul_f32 v[110:111], v[104:105], v[118:119] op_sel_hi:[1,0]
	v_mov_b64_e32 v[32:33], v[178:179]
	v_mov_b64_e32 v[34:35], v[180:181]
	v_mov_b64_e32 v[104:105], v[182:183]
	v_mov_b64_e32 v[106:107], v[184:185]
	v_pk_fma_f32 v[32:33], v[32:33], v[110:111], v[104:105]
	v_pk_fma_f32 v[34:35], v[34:35], v[108:109], v[106:107]
	flat_store_dwordx4 v[102:103], v[32:35] offset:3072
	s_cbranch_vccnz .LBB0_224
	v_lshl_add_u64 v[102:103], v[94:95], 0, s[2:3]
	v_mov_b64_e32 v[94:95], s[60:61]
	v_mad_u64_u32 v[104:105], s[4:5], v102, s7, v[94:95]
	v_mad_i32_i24 v105, v103, s7, v105
	v_lshl_add_u64 v[110:111], v[104:105], 0, s[30:31]
	v_lshlrev_b32_e32 v152, 2, v66
	v_lshl_add_u64 v[112:113], v[104:105], 0, v[152:153]
	v_lshl_add_u64 v[106:107], v[110:111], 0, v[152:153]
	flat_load_dwordx4 v[102:105], v[112:113]
	s_nop 0
	flat_load_dwordx4 v[106:109], v[106:107]
	s_waitcnt vmcnt(0) lgkmcnt(0)
	v_pk_add_f32 v[108:109], v[108:109], 1.0 op_sel_hi:[1,0]
	v_pk_add_f32 v[106:107], v[106:107], 1.0 op_sel_hi:[1,0]
	v_pk_fma_f32 v[18:19], v[18:19], v[108:109], v[104:105]
	v_pk_fma_f32 v[16:17], v[16:17], v[106:107], v[102:103]
	s_nop 0
	v_cvt_pk_bf16_f32 v16, v16, v17
	v_cvt_pk_bf16_f32 v17, v18, v19
	flat_store_dwordx2 v[84:85], v[16:17]
	v_lshlrev_b32_e32 v16, 2, v68
	v_mov_b32_e32 v17, v153
	v_lshl_add_u64 v[18:19], v[110:111], 0, v[16:17]
	flat_load_dwordx4 v[102:105], v[112:113] offset:1024
	flat_load_dwordx4 v[106:109], v[18:19]
	s_waitcnt vmcnt(0) lgkmcnt(0)
	v_pk_add_f32 v[18:19], v[108:109], 1.0 op_sel_hi:[1,0]
	v_pk_add_f32 v[106:107], v[106:107], 1.0 op_sel_hi:[1,0]
	v_pk_fma_f32 v[14:15], v[14:15], v[18:19], v[104:105]
	v_pk_fma_f32 v[12:13], v[12:13], v[106:107], v[102:103]
	s_nop 0
	v_cvt_pk_bf16_f32 v12, v12, v13
	v_cvt_pk_bf16_f32 v13, v14, v15
	flat_store_dwordx2 v[84:85], v[12:13] offset:512
	v_lshlrev_b32_e32 v12, 2, v70
	v_mov_b32_e32 v13, v153
	v_lshl_add_u64 v[14:15], v[110:111], 0, v[12:13]
	flat_load_dwordx4 v[102:105], v[112:113] offset:2048
	flat_load_dwordx4 v[106:109], v[14:15]
	s_waitcnt vmcnt(0) lgkmcnt(0)
	v_pk_add_f32 v[14:15], v[108:109], 1.0 op_sel_hi:[1,0]
	v_pk_add_f32 v[18:19], v[106:107], 1.0 op_sel_hi:[1,0]
	v_pk_fma_f32 v[6:7], v[6:7], v[14:15], v[104:105]
	v_pk_fma_f32 v[4:5], v[4:5], v[18:19], v[102:103]
	s_nop 0
	v_cvt_pk_bf16_f32 v4, v4, v5
	v_cvt_pk_bf16_f32 v5, v6, v7
	flat_store_dwordx2 v[84:85], v[4:5] offset:1024
	v_lshlrev_b32_e32 v4, 2, v72
	v_mov_b32_e32 v5, v153
	v_lshl_add_u64 v[6:7], v[110:111], 0, v[4:5]
	flat_load_dwordx4 v[102:105], v[112:113] offset:3072
	flat_load_dwordx4 v[106:109], v[6:7]
	s_waitcnt vmcnt(0) lgkmcnt(0)
	v_pk_add_f32 v[6:7], v[108:109], 1.0 op_sel_hi:[1,0]
	v_pk_add_f32 v[14:15], v[106:107], 1.0 op_sel_hi:[1,0]
	v_pk_fma_f32 v[2:3], v[2:3], v[6:7], v[104:105]
	v_pk_fma_f32 v[0:1], v[0:1], v[14:15], v[102:103]
	s_nop 0
	v_cvt_pk_bf16_f32 v0, v0, v1
	v_cvt_pk_bf16_f32 v1, v2, v3
	flat_store_dwordx2 v[84:85], v[0:1] offset:1536
	v_lshl_add_u64 v[0:1], v[92:93], 0, s[2:3]
	v_mad_u64_u32 v[2:3], s[4:5], v0, s7, v[94:95]
	v_mad_i32_i24 v3, v1, s7, v3
	v_lshl_add_u64 v[0:1], v[2:3], 0, s[30:31]
	v_lshl_add_u64 v[2:3], v[2:3], 0, v[152:153]
	v_lshl_add_u64 v[6:7], v[0:1], 0, v[152:153]
	flat_load_dwordx4 v[102:105], v[2:3]
	flat_load_dwordx4 v[106:109], v[6:7]
	s_waitcnt vmcnt(0) lgkmcnt(0)
	v_pk_add_f32 v[6:7], v[108:109], 1.0 op_sel_hi:[1,0]
	v_pk_add_f32 v[14:15], v[106:107], 1.0 op_sel_hi:[1,0]
	v_pk_fma_f32 v[6:7], v[10:11], v[6:7], v[104:105]
	v_pk_fma_f32 v[8:9], v[8:9], v[14:15], v[102:103]
	v_lshl_add_u64 v[10:11], v[82:83], 0, v[96:97]
	v_cvt_pk_bf16_f32 v8, v8, v9
	v_cvt_pk_bf16_f32 v9, v6, v7
	flat_store_dwordx2 v[10:11], v[8:9]
	v_lshl_add_u64 v[14:15], v[0:1], 0, v[16:17]
	flat_load_dwordx4 v[6:9], v[2:3] offset:1024
	flat_load_dwordx4 v[102:105], v[14:15]
	s_waitcnt vmcnt(0) lgkmcnt(0)
	v_pk_add_f32 v[14:15], v[104:105], 1.0 op_sel_hi:[1,0]
	v_pk_add_f32 v[18:19], v[102:103], 1.0 op_sel_hi:[1,0]
	v_pk_fma_f32 v[8:9], v[22:23], v[14:15], v[8:9]
	v_pk_fma_f32 v[6:7], v[20:21], v[18:19], v[6:7]
	v_lshl_add_u64 v[14:15], v[0:1], 0, v[12:13]
	v_cvt_pk_bf16_f32 v6, v6, v7
	v_cvt_pk_bf16_f32 v7, v8, v9
	flat_store_dwordx2 v[10:11], v[6:7] offset:512
	flat_load_dwordx4 v[6:9], v[2:3] offset:2048
	v_lshl_add_u64 v[0:1], v[0:1], 0, v[4:5]
	flat_load_dwordx4 v[18:21], v[14:15]
	s_waitcnt vmcnt(0) lgkmcnt(0)
	v_pk_add_f32 v[14:15], v[20:21], 1.0 op_sel_hi:[1,0]
	v_pk_add_f32 v[18:19], v[18:19], 1.0 op_sel_hi:[1,0]
	v_pk_fma_f32 v[8:9], v[30:31], v[14:15], v[8:9]
	v_pk_fma_f32 v[6:7], v[28:29], v[18:19], v[6:7]
	s_nop 0
	v_cvt_pk_bf16_f32 v6, v6, v7
	v_cvt_pk_bf16_f32 v7, v8, v9
	flat_store_dwordx2 v[10:11], v[6:7] offset:1024
	flat_load_dwordx4 v[6:9], v[2:3] offset:3072
	s_nop 0
	flat_load_dwordx4 v[0:3], v[0:1]
	s_waitcnt vmcnt(0) lgkmcnt(0)
	v_pk_add_f32 v[2:3], v[2:3], 1.0 op_sel_hi:[1,0]
	v_pk_add_f32 v[0:1], v[0:1], 1.0 op_sel_hi:[1,0]
	v_pk_fma_f32 v[2:3], v[26:27], v[2:3], v[8:9]
	v_pk_fma_f32 v[0:1], v[24:25], v[0:1], v[6:7]
	s_nop 0
	v_cvt_pk_bf16_f32 v0, v0, v1
	v_cvt_pk_bf16_f32 v1, v2, v3
	flat_store_dwordx2 v[10:11], v[0:1] offset:1536
	v_lshl_add_u64 v[0:1], v[90:91], 0, s[2:3]
	v_mad_u64_u32 v[2:3], s[4:5], v0, s7, v[94:95]
	v_mad_i32_i24 v3, v1, s7, v3
	v_lshl_add_u64 v[0:1], v[2:3], 0, s[30:31]
	v_lshl_add_u64 v[2:3], v[2:3], 0, v[152:153]
	v_lshl_add_u64 v[10:11], v[0:1], 0, v[152:153]
	flat_load_dwordx4 v[6:9], v[2:3]
	flat_load_dwordx4 v[18:21], v[10:11]
	s_waitcnt vmcnt(0) lgkmcnt(0)
	v_pk_add_f32 v[10:11], v[20:21], 1.0 op_sel_hi:[1,0]
	v_pk_add_f32 v[14:15], v[18:19], 1.0 op_sel_hi:[1,0]
	v_pk_fma_f32 v[8:9], v[62:63], v[10:11], v[8:9]
	v_pk_fma_f32 v[6:7], v[60:61], v[14:15], v[6:7]
	v_lshl_add_u64 v[10:11], v[82:83], 0, v[100:101]
	v_cvt_pk_bf16_f32 v6, v6, v7
	v_cvt_pk_bf16_f32 v7, v8, v9
	flat_store_dwordx2 v[10:11], v[6:7]
	v_lshl_add_u64 v[14:15], v[0:1], 0, v[16:17]
	flat_load_dwordx4 v[6:9], v[2:3] offset:1024
	flat_load_dwordx4 v[18:21], v[14:15]
	s_waitcnt vmcnt(0) lgkmcnt(0)
	v_pk_add_f32 v[14:15], v[20:21], 1.0 op_sel_hi:[1,0]
	v_pk_add_f32 v[18:19], v[18:19], 1.0 op_sel_hi:[1,0]
	v_pk_fma_f32 v[8:9], v[58:59], v[14:15], v[8:9]
	v_pk_fma_f32 v[6:7], v[56:57], v[18:19], v[6:7]
	v_lshl_add_u64 v[14:15], v[0:1], 0, v[12:13]
	v_cvt_pk_bf16_f32 v6, v6, v7
	v_cvt_pk_bf16_f32 v7, v8, v9
	flat_store_dwordx2 v[10:11], v[6:7] offset:512
	flat_load_dwordx4 v[6:9], v[2:3] offset:2048
	v_lshl_add_u64 v[0:1], v[0:1], 0, v[4:5]
	flat_load_dwordx4 v[18:21], v[14:15]
	s_waitcnt vmcnt(0) lgkmcnt(0)
	v_pk_add_f32 v[14:15], v[20:21], 1.0 op_sel_hi:[1,0]
	v_pk_add_f32 v[18:19], v[18:19], 1.0 op_sel_hi:[1,0]
	v_pk_fma_f32 v[8:9], v[54:55], v[14:15], v[8:9]
	v_pk_fma_f32 v[6:7], v[52:53], v[18:19], v[6:7]
	s_nop 0
	v_cvt_pk_bf16_f32 v6, v6, v7
	v_cvt_pk_bf16_f32 v7, v8, v9
	flat_store_dwordx2 v[10:11], v[6:7] offset:1024
	flat_load_dwordx4 v[6:9], v[2:3] offset:3072
	s_nop 0
	flat_load_dwordx4 v[0:3], v[0:1]
	s_waitcnt vmcnt(0) lgkmcnt(0)
	v_pk_add_f32 v[2:3], v[2:3], 1.0 op_sel_hi:[1,0]
	v_pk_add_f32 v[0:1], v[0:1], 1.0 op_sel_hi:[1,0]
	v_pk_fma_f32 v[2:3], v[50:51], v[2:3], v[8:9]
	v_pk_fma_f32 v[0:1], v[48:49], v[0:1], v[6:7]
	s_nop 0
	v_cvt_pk_bf16_f32 v0, v0, v1
	v_cvt_pk_bf16_f32 v1, v2, v3
	flat_store_dwordx2 v[10:11], v[0:1] offset:1536
	v_lshl_add_u64 v[0:1], v[88:89], 0, s[2:3]
	v_mad_u64_u32 v[2:3], s[4:5], v0, s7, v[94:95]
	v_mad_i32_i24 v3, v1, s7, v3
	v_lshl_add_u64 v[0:1], v[2:3], 0, s[30:31]
	v_lshl_add_u64 v[2:3], v[2:3], 0, v[152:153]
	v_lshl_add_u64 v[10:11], v[0:1], 0, v[152:153]
	flat_load_dwordx4 v[6:9], v[2:3]
	flat_load_dwordx4 v[18:21], v[10:11]
	s_waitcnt vmcnt(0) lgkmcnt(0)
	v_pk_add_f32 v[10:11], v[20:21], 1.0 op_sel_hi:[1,0]
	v_pk_add_f32 v[14:15], v[18:19], 1.0 op_sel_hi:[1,0]
	v_pk_fma_f32 v[8:9], v[46:47], v[10:11], v[8:9]
	v_pk_fma_f32 v[6:7], v[44:45], v[14:15], v[6:7]
	v_lshl_add_u64 v[18:19], v[82:83], 0, v[98:99]
	v_cvt_pk_bf16_f32 v6, v6, v7
	v_cvt_pk_bf16_f32 v7, v8, v9
	flat_store_dwordx2 v[18:19], v[6:7]
	v_lshl_add_u64 v[10:11], v[0:1], 0, v[16:17]
	flat_load_dwordx4 v[6:9], v[2:3] offset:1024
	flat_load_dwordx4 v[14:17], v[10:11]
	s_waitcnt vmcnt(0) lgkmcnt(0)
	v_pk_add_f32 v[10:11], v[16:17], 1.0 op_sel_hi:[1,0]
	v_pk_add_f32 v[14:15], v[14:15], 1.0 op_sel_hi:[1,0]
	v_pk_fma_f32 v[8:9], v[42:43], v[10:11], v[8:9]
	v_pk_fma_f32 v[6:7], v[40:41], v[14:15], v[6:7]
	v_lshl_add_u64 v[10:11], v[0:1], 0, v[12:13]
	v_cvt_pk_bf16_f32 v6, v6, v7
	v_cvt_pk_bf16_f32 v7, v8, v9
	flat_store_dwordx2 v[18:19], v[6:7] offset:512
	flat_load_dwordx4 v[6:9], v[2:3] offset:2048
	v_lshl_add_u64 v[0:1], v[0:1], 0, v[4:5]
	flat_load_dwordx4 v[10:13], v[10:11]
	s_waitcnt vmcnt(0) lgkmcnt(0)
	v_pk_add_f32 v[12:13], v[12:13], 1.0 op_sel_hi:[1,0]
	v_pk_add_f32 v[10:11], v[10:11], 1.0 op_sel_hi:[1,0]
	v_pk_fma_f32 v[8:9], v[38:39], v[12:13], v[8:9]
	v_pk_fma_f32 v[6:7], v[36:37], v[10:11], v[6:7]
	s_nop 0
	v_cvt_pk_bf16_f32 v6, v6, v7
	v_cvt_pk_bf16_f32 v7, v8, v9
	flat_store_dwordx2 v[18:19], v[6:7] offset:1024
	flat_load_dwordx4 v[6:9], v[2:3] offset:3072
	s_nop 0
	flat_load_dwordx4 v[0:3], v[0:1]
	s_waitcnt vmcnt(0) lgkmcnt(0)
	v_pk_add_f32 v[2:3], v[2:3], 1.0 op_sel_hi:[1,0]
	v_pk_add_f32 v[0:1], v[0:1], 1.0 op_sel_hi:[1,0]
	v_pk_fma_f32 v[2:3], v[34:35], v[2:3], v[8:9]
	v_pk_fma_f32 v[0:1], v[32:33], v[0:1], v[6:7]
	s_nop 0
	v_cvt_pk_bf16_f32 v0, v0, v1
	v_cvt_pk_bf16_f32 v1, v2, v3
	flat_store_dwordx2 v[18:19], v[0:1] offset:1536
	s_branch .LBB0_224
